# hyena conv_mid: filter-spectrum slot loads issued before the two forward FFT passes (kept in spare VGPRs) instead of right before use
# baseline (speedup 1.0000x reference)
.LBB0_499:
	s_add_i32 s100, s72, s48
	s_lshl_b32 s100, s100, 16
	s_add_u32 s100, s54, s100
	s_addc_u32 s101, s55, 0
	v_and_b32_e32 v245, 0x1ff, v210
	v_lshlrev_b32_e32 v245, 3, v245
	s_add_u32 s100, s100, 0x1000
	s_addc_u32 s101, s101, 0
	global_load_dwordx2 v[214:215], v245, s[100:101] offset:-4096 nt
	global_load_dwordx2 v[216:217], v245, s[100:101] nt
	s_add_u32 s100, s100, 0x2000
	s_addc_u32 s101, s101, 0
	global_load_dwordx2 v[218:219], v245, s[100:101] offset:-4096 nt
	global_load_dwordx2 v[220:221], v245, s[100:101] nt
	s_add_u32 s100, s100, 0x2000
	s_addc_u32 s101, s101, 0
	global_load_dwordx2 v[222:223], v245, s[100:101] offset:-4096 nt
	global_load_dwordx2 v[224:225], v245, s[100:101] nt
	s_add_u32 s100, s100, 0x2000
	s_addc_u32 s101, s101, 0
	global_load_dwordx2 v[226:227], v245, s[100:101] offset:-4096 nt
	global_load_dwordx2 v[228:229], v245, s[100:101] nt
	s_add_u32 s100, s100, 0x2000
	s_addc_u32 s101, s101, 0
	global_load_dwordx2 v[230:231], v245, s[100:101] offset:-4096 nt
	global_load_dwordx2 v[232:233], v245, s[100:101] nt
	s_add_u32 s100, s100, 0x2000
	s_addc_u32 s101, s101, 0
	global_load_dwordx2 v[234:235], v245, s[100:101] offset:-4096 nt
	global_load_dwordx2 v[236:237], v245, s[100:101] nt
	s_add_u32 s100, s100, 0x2000
	s_addc_u32 s101, s101, 0
	global_load_dwordx2 v[238:239], v245, s[100:101] offset:-4096 nt
	global_load_dwordx2 v[240:241], v245, s[100:101] nt
	s_add_u32 s100, s100, 0x2000
	s_addc_u32 s101, s101, 0
	global_load_dwordx2 v[242:243], v245, s[100:101] offset:-4096 nt
	global_load_dwordx2 v[246:247], v245, s[100:101] nt
	v_mov_b32_e32 v2, v210
	s_mov_b32 s43, s8
	v_and_b32_e32 v3, 0x1ff, v2
	v_lshlrev_b32_e32 v2, 5, v2
	v_and_or_b32 v2, v2, s94, v3
	v_ashrrev_i32_e32 v4, 5, v2
	v_lshlrev_b32_e32 v2, 3, v2
	v_lshlrev_b32_e32 v4, 3, v4
	v_add3_u32 v18, 0, v2, v4
	ds_read_b64 v[128:129], v18
	ds_read_b64 v[134:135], v18 offset:4224
	ds_read_b64 v[136:137], v18 offset:8448
	ds_read_b64 v[138:139], v18 offset:12672
	ds_read_b64 v[140:141], v18 offset:16896
	ds_read_b64 v[142:143], v18 offset:21120
	ds_read_b64 v[132:133], v18 offset:25344
	ds_read_b64 v[130:131], v18 offset:29568
	ds_read_b64 v[144:145], v18 offset:33792
	ds_read_b64 v[148:149], v18 offset:38016
	ds_read_b64 v[150:151], v18 offset:42240
	ds_read_b64 v[152:153], v18 offset:46464
	s_waitcnt lgkmcnt(10)
	v_pk_mul_f32 v[162:163], v[134:135], s[10:11]
	s_mov_b32 s74, s11
	v_pk_fma_f32 v[162:163], v[134:135], s[8:9], v[162:163] op_sel:[0,0,1] op_sel_hi:[1,0,0]
	s_waitcnt lgkmcnt(2)
	v_pk_mul_f32 v[178:179], v[148:149], s[42:43]
	v_pk_add_f32 v[194:195], v[134:135], v[148:149]
	v_pk_add_f32 v[134:135], v[134:135], v[148:149] neg_lo:[0,1] neg_hi:[0,1]
	v_pk_mul_f32 v[164:165], v[136:137], s[18:19]
	s_mov_b32 s41, s16
	v_pk_fma_f32 v[178:179], v[148:149], s[74:75], v[178:179] op_sel:[0,0,1] op_sel_hi:[1,0,0] neg_lo:[1,0,0] neg_hi:[1,0,0]
	v_pk_mul_f32 v[148:149], v[134:135], s[18:19]
	v_pk_fma_f32 v[164:165], v[136:137], s[16:17], v[164:165] op_sel:[0,0,1] op_sel_hi:[1,0,0]
	s_mov_b32 s80, s19
	s_waitcnt lgkmcnt(1)
	v_pk_mul_f32 v[180:181], v[150:151], s[40:41]
	v_pk_fma_f32 v[134:135], v[134:135], s[16:17], v[148:149] op_sel:[0,0,1] op_sel_hi:[1,0,0]
	v_pk_add_f32 v[148:149], v[136:137], v[150:151]
	v_pk_add_f32 v[136:137], v[136:137], v[150:151] neg_lo:[0,1] neg_hi:[0,1]
	v_pk_mul_f32 v[166:167], v[138:139], s[26:27]
	s_mov_b32 s78, s37
	s_mov_b32 s39, s24
	v_pk_fma_f32 v[180:181], v[150:151], s[80:81], v[180:181] op_sel:[0,0,1] op_sel_hi:[1,0,0] neg_lo:[1,0,0] neg_hi:[1,0,0]
	v_pk_mul_f32 v[150:151], v[136:137], s[36:37]
	ds_read_b64 v[154:155], v18 offset:50688
	ds_read_b64 v[156:157], v18 offset:54912
	ds_read_b64 v[158:159], v18 offset:59136
	ds_read_b64 v[160:161], v18 offset:63360
	v_pk_fma_f32 v[166:167], v[138:139], s[24:25], v[166:167] op_sel:[0,0,1] op_sel_hi:[1,0,0]
	s_mov_b32 s0, s27
	s_waitcnt lgkmcnt(4)
	v_pk_mul_f32 v[182:183], v[152:153], s[38:39]
	v_pk_fma_f32 v[136:137], v[136:137], s[78:79], v[150:151] op_sel:[0,0,1] op_sel_hi:[1,0,0]
	v_pk_add_f32 v[150:151], v[138:139], v[152:153]
	v_pk_add_f32 v[138:139], v[138:139], v[152:153] neg_lo:[0,1] neg_hi:[0,1]
	v_pk_mul_f32 v[168:169], v[140:141], s[36:37]
	v_pk_fma_f32 v[182:183], v[152:153], s[0:1], v[182:183] op_sel:[0,0,1] op_sel_hi:[1,0,0] neg_lo:[1,0,0] neg_hi:[1,0,0]
	v_pk_mul_f32 v[152:153], v[138:139], s[40:41]
	v_pk_fma_f32 v[168:169], v[140:141], s[78:79], v[168:169] op_sel:[0,0,1] op_sel_hi:[1,0,0]
	v_pk_mul_f32 v[170:171], v[142:143], s[38:39]
	s_waitcnt lgkmcnt(3)
	v_pk_mul_f32 v[184:185], v[154:155], s[36:37]
	v_pk_fma_f32 v[138:139], v[138:139], s[80:81], v[152:153] op_sel:[0,0,1] op_sel_hi:[1,0,0]
	v_pk_add_f32 v[152:153], v[140:141], v[154:155]
	v_pk_add_f32 v[140:141], v[140:141], v[154:155] neg_lo:[0,1] neg_hi:[0,1]
	v_pk_fma_f32 v[170:171], v[142:143], s[0:1], v[170:171] op_sel:[0,0,1] op_sel_hi:[1,0,0]
	v_pk_fma_f32 v[184:185], v[154:155], s[78:79], v[184:185] op_sel:[0,0,1] op_sel_hi:[1,0,0] neg_lo:[1,0,0] neg_hi:[1,0,0]
	s_waitcnt lgkmcnt(2)
	v_pk_mul_f32 v[186:187], v[156:157], s[26:27]
	v_xor_b32_e32 v155, 0x80000000, v140
	v_mov_b32_e32 v154, v141
	v_pk_add_f32 v[140:141], v[142:143], v[156:157]
	v_pk_add_f32 v[142:143], v[142:143], v[156:157] neg_lo:[0,1] neg_hi:[0,1]
	v_pk_mul_f32 v[172:173], v[132:133], s[40:41]
	v_pk_fma_f32 v[186:187], v[156:157], s[24:25], v[186:187] op_sel:[0,0,1] op_sel_hi:[1,0,0] neg_lo:[1,0,0] neg_hi:[1,0,0]
	v_pk_mul_f32 v[156:157], v[142:143], s[40:41]
	v_pk_fma_f32 v[172:173], v[132:133], s[80:81], v[172:173] op_sel:[0,0,1] op_sel_hi:[1,0,0]
	s_waitcnt lgkmcnt(1)
	v_pk_mul_f32 v[188:189], v[158:159], s[18:19]
	v_pk_fma_f32 v[142:143], v[142:143], s[80:81], v[156:157] op_sel:[0,0,1] op_sel_hi:[1,0,0] neg_lo:[1,0,0] neg_hi:[1,0,0]
	v_pk_add_f32 v[156:157], v[132:133], v[158:159]
	v_pk_add_f32 v[132:133], v[132:133], v[158:159] neg_lo:[0,1] neg_hi:[0,1]
	v_pk_mul_f32 v[174:175], v[130:131], s[42:43]
	v_pk_fma_f32 v[188:189], v[158:159], s[16:17], v[188:189] op_sel:[0,0,1] op_sel_hi:[1,0,0] neg_lo:[1,0,0] neg_hi:[1,0,0]
	v_pk_mul_f32 v[158:159], v[132:133], s[36:37]
	v_pk_fma_f32 v[174:175], v[130:131], s[74:75], v[174:175] op_sel:[0,0,1] op_sel_hi:[1,0,0]
	s_waitcnt lgkmcnt(0)
	v_pk_mul_f32 v[190:191], v[160:161], s[10:11]
	v_pk_fma_f32 v[132:133], v[132:133], s[78:79], v[158:159] op_sel:[0,0,1] op_sel_hi:[1,0,0] neg_lo:[1,0,0] neg_hi:[1,0,0]
	v_pk_add_f32 v[158:159], v[130:131], v[160:161]
	v_pk_add_f32 v[130:131], v[130:131], v[160:161] neg_lo:[0,1] neg_hi:[0,1]
	v_xor_b32_e32 v177, 0x80000000, v144
	v_mov_b32_e32 v176, v145
	v_pk_fma_f32 v[190:191], v[160:161], s[8:9], v[190:191] op_sel:[0,0,1] op_sel_hi:[1,0,0] neg_lo:[1,0,0] neg_hi:[1,0,0]
	v_pk_mul_f32 v[160:161], v[130:131], s[18:19]
	v_pk_add_f32 v[192:193], v[128:129], v[144:145]
	v_pk_add_f32 v[144:145], v[128:129], v[144:145] neg_lo:[0,1] neg_hi:[0,1]
	v_pk_fma_f32 v[130:131], v[130:131], s[16:17], v[160:161] op_sel:[0,0,1] op_sel_hi:[1,0,0] neg_lo:[1,0,0] neg_hi:[1,0,0]
	v_pk_add_f32 v[160:161], v[128:129], v[176:177]
	v_pk_add_f32 v[128:129], v[128:129], v[176:177] neg_lo:[0,1] neg_hi:[0,1]
	v_pk_add_f32 v[176:177], v[162:163], v[178:179]
	v_pk_add_f32 v[162:163], v[162:163], v[178:179] neg_lo:[0,1] neg_hi:[0,1]
	v_cvt_f32_u32_e32 v2, v3
	v_pk_mul_f32 v[178:179], v[162:163], s[18:19]
	s_add_i32 s76, s72, s48
	v_pk_fma_f32 v[162:163], v[162:163], s[16:17], v[178:179] op_sel:[0,0,1] op_sel_hi:[1,0,0]
	v_pk_add_f32 v[178:179], v[164:165], v[180:181]
	v_pk_add_f32 v[164:165], v[164:165], v[180:181] neg_lo:[0,1] neg_hi:[0,1]
	v_mul_f32_e32 v2, 0x38800000, v2
	v_pk_mul_f32 v[180:181], v[164:165], s[36:37]
	v_sin_f32_e32 v34, v2
	v_pk_fma_f32 v[164:165], v[164:165], s[78:79], v[180:181] op_sel:[0,0,1] op_sel_hi:[1,0,0]
	v_pk_add_f32 v[180:181], v[166:167], v[182:183]
	v_pk_add_f32 v[166:167], v[166:167], v[182:183] neg_lo:[0,1] neg_hi:[0,1]
	v_cos_f32_e32 v30, v2
	v_pk_mul_f32 v[182:183], v[166:167], s[40:41]
	v_xor_b32_e32 v31, 0x80000000, v34
	v_pk_fma_f32 v[166:167], v[166:167], s[80:81], v[182:183] op_sel:[0,0,1] op_sel_hi:[1,0,0]
	v_pk_add_f32 v[182:183], v[168:169], v[184:185]
	v_pk_add_f32 v[168:169], v[168:169], v[184:185] neg_lo:[0,1] neg_hi:[0,1]
	v_mov_b32_e32 v35, v31
	v_xor_b32_e32 v185, 0x80000000, v168
	v_mov_b32_e32 v184, v169
	v_pk_add_f32 v[168:169], v[170:171], v[186:187]
	v_pk_add_f32 v[170:171], v[170:171], v[186:187] neg_lo:[0,1] neg_hi:[0,1]
	v_pk_mul_f32 v[2:3], v[30:31], v[34:35] op_sel:[1,0] op_sel_hi:[0,1]
	v_pk_mul_f32 v[186:187], v[170:171], s[40:41]
	v_pk_fma_f32 v[44:45], v[30:31], v[30:31], v[2:3] op_sel_hi:[1,0,1]
	v_pk_fma_f32 v[170:171], v[170:171], s[80:81], v[186:187] op_sel:[0,0,1] op_sel_hi:[1,0,0] neg_lo:[1,0,0] neg_hi:[1,0,0]
	v_pk_add_f32 v[186:187], v[172:173], v[188:189]
	v_pk_add_f32 v[172:173], v[172:173], v[188:189] neg_lo:[0,1] neg_hi:[0,1]
	v_pk_mul_f32 v[2:3], v[34:35], v[44:45] op_sel:[0,1] op_sel_hi:[1,0]
	v_pk_mul_f32 v[188:189], v[172:173], s[36:37]
	v_xor_b32_e32 v54, 0x80000000, v45
	v_pk_fma_f32 v[172:173], v[172:173], s[78:79], v[188:189] op_sel:[0,0,1] op_sel_hi:[1,0,0] neg_lo:[1,0,0] neg_hi:[1,0,0]
	v_pk_add_f32 v[188:189], v[174:175], v[190:191]
	v_pk_add_f32 v[174:175], v[174:175], v[190:191] neg_lo:[0,1] neg_hi:[0,1]
	v_mov_b32_e32 v55, v45
	v_pk_mul_f32 v[190:191], v[174:175], s[18:19]
	v_pk_fma_f32 v[46:47], v[30:31], v[44:45], v[2:3] op_sel_hi:[0,1,1]
	v_pk_fma_f32 v[174:175], v[174:175], s[16:17], v[190:191] op_sel:[0,0,1] op_sel_hi:[1,0,0] neg_lo:[1,0,0] neg_hi:[1,0,0]
	v_pk_add_f32 v[190:191], v[192:193], v[152:153]
	v_pk_add_f32 v[152:153], v[192:193], v[152:153] neg_lo:[0,1] neg_hi:[0,1]
	v_pk_add_f32 v[192:193], v[194:195], v[140:141]
	v_pk_add_f32 v[140:141], v[194:195], v[140:141] neg_lo:[0,1] neg_hi:[0,1]
	v_pk_mul_f32 v[2:3], v[44:45], v[54:55] op_sel:[1,0] op_sel_hi:[0,1]
	v_pk_mul_f32 v[194:195], v[140:141], s[36:37]
	v_pk_fma_f32 v[52:53], v[44:45], v[44:45], v[2:3] op_sel_hi:[1,0,1]
	v_pk_fma_f32 v[140:141], v[140:141], s[78:79], v[194:195] op_sel:[0,0,1] op_sel_hi:[1,0,0]
	v_pk_add_f32 v[194:195], v[148:149], v[156:157]
	v_pk_add_f32 v[148:149], v[148:149], v[156:157] neg_lo:[0,1] neg_hi:[0,1]
	v_xor_b32_e32 v58, 0x80000000, v53
	v_xor_b32_e32 v157, 0x80000000, v148
	v_mov_b32_e32 v156, v149
	v_pk_add_f32 v[148:149], v[150:151], v[158:159]
	v_pk_add_f32 v[150:151], v[150:151], v[158:159] neg_lo:[0,1] neg_hi:[0,1]
	v_mov_b32_e32 v59, v53
	v_pk_mul_f32 v[158:159], v[150:151], s[36:37]
	v_pk_mul_f32 v[2:3], v[52:53], v[58:59] op_sel:[1,0] op_sel_hi:[0,1]
	v_pk_fma_f32 v[150:151], v[150:151], s[78:79], v[158:159] op_sel:[0,0,1] op_sel_hi:[1,0,0] neg_lo:[1,0,0] neg_hi:[1,0,0]
	v_pk_add_f32 v[158:159], v[144:145], v[154:155]
	v_pk_add_f32 v[144:145], v[144:145], v[154:155] neg_lo:[0,1] neg_hi:[0,1]
	v_pk_add_f32 v[154:155], v[134:135], v[142:143]
	v_pk_add_f32 v[134:135], v[134:135], v[142:143] neg_lo:[0,1] neg_hi:[0,1]
	v_pk_fma_f32 v[48:49], v[52:53], v[52:53], v[2:3] op_sel_hi:[1,0,1]
	v_pk_mul_f32 v[142:143], v[134:135], s[36:37]
	v_pk_mul_f32 v[2:3], v[58:59], v[48:49] op_sel:[0,1] op_sel_hi:[1,0]
	v_pk_fma_f32 v[134:135], v[134:135], s[78:79], v[142:143] op_sel:[0,0,1] op_sel_hi:[1,0,0]
	v_pk_add_f32 v[142:143], v[136:137], v[132:133]
	v_pk_add_f32 v[132:133], v[136:137], v[132:133] neg_lo:[0,1] neg_hi:[0,1]
	v_pk_fma_f32 v[36:37], v[52:53], v[48:49], v[2:3] op_sel_hi:[0,1,1]
	v_xor_b32_e32 v137, 0x80000000, v132
	v_mov_b32_e32 v136, v133
	v_pk_add_f32 v[132:133], v[138:139], v[130:131]
	v_pk_add_f32 v[130:131], v[138:139], v[130:131] neg_lo:[0,1] neg_hi:[0,1]
	v_pk_mul_f32 v[2:3], v[58:59], v[36:37] op_sel:[0,1] op_sel_hi:[1,0]
	v_pk_mul_f32 v[138:139], v[130:131], s[36:37]
	v_pk_fma_f32 v[26:27], v[52:53], v[36:37], v[2:3] op_sel_hi:[0,1,1]
	v_pk_fma_f32 v[130:131], v[130:131], s[78:79], v[138:139] op_sel:[0,0,1] op_sel_hi:[1,0,0] neg_lo:[1,0,0] neg_hi:[1,0,0]
	v_pk_add_f32 v[138:139], v[160:161], v[182:183]
	v_pk_add_f32 v[160:161], v[160:161], v[182:183] neg_lo:[0,1] neg_hi:[0,1]
	v_pk_add_f32 v[182:183], v[176:177], v[168:169]
	v_pk_add_f32 v[168:169], v[176:177], v[168:169] neg_lo:[0,1] neg_hi:[0,1]
	v_pk_mul_f32 v[2:3], v[58:59], v[26:27] op_sel:[0,1] op_sel_hi:[1,0]
	v_pk_mul_f32 v[176:177], v[168:169], s[36:37]
	v_pk_fma_f32 v[20:21], v[52:53], v[26:27], v[2:3] op_sel_hi:[0,1,1]
	v_pk_fma_f32 v[168:169], v[168:169], s[78:79], v[176:177] op_sel:[0,0,1] op_sel_hi:[1,0,0]
	v_pk_add_f32 v[176:177], v[178:179], v[186:187]
	v_pk_add_f32 v[178:179], v[178:179], v[186:187] neg_lo:[0,1] neg_hi:[0,1]
	v_pk_mul_f32 v[2:3], v[58:59], v[20:21] op_sel:[0,1] op_sel_hi:[1,0]
	v_xor_b32_e32 v187, 0x80000000, v178
	v_mov_b32_e32 v186, v179
	v_pk_add_f32 v[178:179], v[180:181], v[188:189]
	v_pk_add_f32 v[180:181], v[180:181], v[188:189] neg_lo:[0,1] neg_hi:[0,1]
	v_pk_fma_f32 v[10:11], v[52:53], v[20:21], v[2:3] op_sel_hi:[0,1,1]
	v_pk_mul_f32 v[188:189], v[180:181], s[36:37]
	v_pk_mul_f32 v[2:3], v[58:59], v[10:11] op_sel:[0,1] op_sel_hi:[1,0]
	v_pk_fma_f32 v[180:181], v[180:181], s[78:79], v[188:189] op_sel:[0,0,1] op_sel_hi:[1,0,0] neg_lo:[1,0,0] neg_hi:[1,0,0]
	v_pk_add_f32 v[188:189], v[128:129], v[184:185]
	v_pk_add_f32 v[128:129], v[128:129], v[184:185] neg_lo:[0,1] neg_hi:[0,1]
	v_pk_add_f32 v[184:185], v[162:163], v[170:171]
	v_pk_add_f32 v[162:163], v[162:163], v[170:171] neg_lo:[0,1] neg_hi:[0,1]
	v_pk_fma_f32 v[4:5], v[52:53], v[10:11], v[2:3] op_sel_hi:[0,1,1]
	v_pk_mul_f32 v[170:171], v[162:163], s[36:37]
	v_pk_mul_f32 v[8:9], v[54:55], v[4:5] op_sel:[0,1] op_sel_hi:[1,0]
	v_pk_fma_f32 v[162:163], v[162:163], s[78:79], v[170:171] op_sel:[0,0,1] op_sel_hi:[1,0,0]
	v_pk_add_f32 v[170:171], v[164:165], v[172:173]
	v_pk_add_f32 v[164:165], v[164:165], v[172:173] neg_lo:[0,1] neg_hi:[0,1]
	v_pk_mul_f32 v[14:15], v[34:35], v[4:5] op_sel:[0,1] op_sel_hi:[1,0]
	v_xor_b32_e32 v173, 0x80000000, v164
	v_mov_b32_e32 v172, v165
	v_pk_add_f32 v[164:165], v[166:167], v[174:175]
	v_pk_add_f32 v[166:167], v[166:167], v[174:175] neg_lo:[0,1] neg_hi:[0,1]
	v_pk_mul_f32 v[32:33], v[54:55], v[10:11] op_sel:[0,1] op_sel_hi:[1,0]
	v_pk_mul_f32 v[174:175], v[166:167], s[36:37]
	v_pk_mul_f32 v[40:41], v[34:35], v[10:11] op_sel:[0,1] op_sel_hi:[1,0]
	v_pk_fma_f32 v[166:167], v[166:167], s[78:79], v[174:175] op_sel:[0,0,1] op_sel_hi:[1,0,0] neg_lo:[1,0,0] neg_hi:[1,0,0]
	v_pk_add_f32 v[174:175], v[190:191], v[194:195]
	v_pk_add_f32 v[190:191], v[190:191], v[194:195] neg_lo:[0,1] neg_hi:[0,1]
	v_pk_add_f32 v[194:195], v[192:193], v[148:149]
	v_pk_add_f32 v[148:149], v[192:193], v[148:149] neg_lo:[0,1] neg_hi:[0,1]
	v_pk_mul_f32 v[62:63], v[54:55], v[20:21] op_sel:[0,1] op_sel_hi:[1,0]
	v_xor_b32_e32 v193, 0x80000000, v148
	v_mov_b32_e32 v192, v149
	v_pk_add_f32 v[148:149], v[152:153], v[156:157]
	v_pk_add_f32 v[152:153], v[152:153], v[156:157] neg_lo:[0,1] neg_hi:[0,1]
	v_pk_add_f32 v[156:157], v[140:141], v[150:151]
	v_pk_add_f32 v[140:141], v[140:141], v[150:151] neg_lo:[0,1] neg_hi:[0,1]
	v_pk_mul_f32 v[66:67], v[34:35], v[20:21] op_sel:[0,1] op_sel_hi:[1,0]
	v_xor_b32_e32 v151, 0x80000000, v140
	v_mov_b32_e32 v150, v141
	v_pk_add_f32 v[140:141], v[158:159], v[142:143]
	v_pk_add_f32 v[142:143], v[158:159], v[142:143] neg_lo:[0,1] neg_hi:[0,1]
	v_pk_add_f32 v[158:159], v[154:155], v[132:133]
	v_pk_add_f32 v[132:133], v[154:155], v[132:133] neg_lo:[0,1] neg_hi:[0,1]
	v_pk_mul_f32 v[78:79], v[54:55], v[26:27] op_sel:[0,1] op_sel_hi:[1,0]
	v_xor_b32_e32 v155, 0x80000000, v132
	v_mov_b32_e32 v154, v133
	v_pk_add_f32 v[132:133], v[144:145], v[136:137]
	v_pk_add_f32 v[136:137], v[144:145], v[136:137] neg_lo:[0,1] neg_hi:[0,1]
	v_pk_add_f32 v[144:145], v[134:135], v[130:131]
	v_pk_add_f32 v[130:131], v[134:135], v[130:131] neg_lo:[0,1] neg_hi:[0,1]
	v_pk_mul_f32 v[82:83], v[34:35], v[26:27] op_sel:[0,1] op_sel_hi:[1,0]
	v_xor_b32_e32 v135, 0x80000000, v130
	v_mov_b32_e32 v134, v131
	v_pk_add_f32 v[130:131], v[138:139], v[176:177]
	v_pk_add_f32 v[138:139], v[138:139], v[176:177] neg_lo:[0,1] neg_hi:[0,1]
	v_pk_add_f32 v[176:177], v[182:183], v[178:179]
	v_pk_add_f32 v[178:179], v[182:183], v[178:179] neg_lo:[0,1] neg_hi:[0,1]
	v_pk_mul_f32 v[92:93], v[54:55], v[36:37] op_sel:[0,1] op_sel_hi:[1,0]
	v_xor_b32_e32 v183, 0x80000000, v178
	v_mov_b32_e32 v182, v179
	v_pk_add_f32 v[178:179], v[160:161], v[186:187]
	v_pk_add_f32 v[160:161], v[160:161], v[186:187] neg_lo:[0,1] neg_hi:[0,1]
	v_pk_add_f32 v[186:187], v[168:169], v[180:181]
	v_pk_add_f32 v[168:169], v[168:169], v[180:181] neg_lo:[0,1] neg_hi:[0,1]
	v_pk_mul_f32 v[96:97], v[34:35], v[36:37] op_sel:[0,1] op_sel_hi:[1,0]
	v_xor_b32_e32 v181, 0x80000000, v168
	v_mov_b32_e32 v180, v169
	v_pk_add_f32 v[168:169], v[188:189], v[170:171]
	v_pk_add_f32 v[170:171], v[188:189], v[170:171] neg_lo:[0,1] neg_hi:[0,1]
	v_pk_add_f32 v[188:189], v[184:185], v[164:165]
	v_pk_add_f32 v[164:165], v[184:185], v[164:165] neg_lo:[0,1] neg_hi:[0,1]
	v_pk_mul_f32 v[106:107], v[54:55], v[48:49] op_sel:[0,1] op_sel_hi:[1,0]
	v_xor_b32_e32 v185, 0x80000000, v164
	v_mov_b32_e32 v184, v165
	v_pk_add_f32 v[164:165], v[128:129], v[172:173]
	v_pk_add_f32 v[128:129], v[128:129], v[172:173] neg_lo:[0,1] neg_hi:[0,1]
	v_pk_add_f32 v[172:173], v[162:163], v[166:167]
	v_pk_add_f32 v[162:163], v[162:163], v[166:167] neg_lo:[0,1] neg_hi:[0,1]
	v_pk_mul_f32 v[110:111], v[34:35], v[48:49] op_sel:[0,1] op_sel_hi:[1,0]
	v_xor_b32_e32 v167, 0x80000000, v162
	v_mov_b32_e32 v166, v163
	v_pk_add_f32 v[162:163], v[174:175], v[194:195]
	v_pk_add_f32 v[174:175], v[174:175], v[194:195] neg_lo:[0,1] neg_hi:[0,1]
	v_pk_add_f32 v[194:195], v[190:191], v[192:193]
	v_pk_add_f32 v[190:191], v[190:191], v[192:193] neg_lo:[0,1] neg_hi:[0,1]
	v_pk_add_f32 v[192:193], v[148:149], v[156:157]
	v_pk_add_f32 v[148:149], v[148:149], v[156:157] neg_lo:[0,1] neg_hi:[0,1]
	v_pk_add_f32 v[156:157], v[152:153], v[150:151]
	v_pk_add_f32 v[150:151], v[152:153], v[150:151] neg_lo:[0,1] neg_hi:[0,1]
	v_pk_add_f32 v[152:153], v[140:141], v[158:159]
	v_pk_add_f32 v[140:141], v[140:141], v[158:159] neg_lo:[0,1] neg_hi:[0,1]
	v_pk_add_f32 v[158:159], v[142:143], v[154:155]
	v_pk_add_f32 v[142:143], v[142:143], v[154:155] neg_lo:[0,1] neg_hi:[0,1]
	v_pk_add_f32 v[154:155], v[132:133], v[144:145]
	v_pk_add_f32 v[132:133], v[132:133], v[144:145] neg_lo:[0,1] neg_hi:[0,1]
	v_pk_add_f32 v[144:145], v[136:137], v[134:135]
	v_pk_add_f32 v[134:135], v[136:137], v[134:135] neg_lo:[0,1] neg_hi:[0,1]
	v_pk_add_f32 v[136:137], v[130:131], v[176:177]
	v_pk_mul_f32 v[120:121], v[54:55], v[52:53] op_sel:[0,1] op_sel_hi:[1,0]
	v_pk_mul_f32 v[124:125], v[34:35], v[52:53] op_sel:[0,1] op_sel_hi:[1,0]
	v_pk_mul_f32 v[34:35], v[34:35], v[136:137] op_sel:[0,1] op_sel_hi:[1,0]
	v_xor_b32_e32 v72, 0x80000000, v47
	v_mov_b32_e32 v73, v47
	v_pk_fma_f32 v[8:9], v[44:45], v[4:5], v[8:9] op_sel_hi:[0,1,1]
	v_pk_fma_f32 v[14:15], v[30:31], v[4:5], v[14:15] op_sel_hi:[0,1,1]
	v_xor_b32_e32 v22, 0x80000000, v5
	v_pk_fma_f32 v[32:33], v[44:45], v[10:11], v[32:33] op_sel_hi:[0,1,1]
	v_pk_fma_f32 v[40:41], v[30:31], v[10:11], v[40:41] op_sel_hi:[0,1,1]
	v_pk_fma_f32 v[62:63], v[44:45], v[20:21], v[62:63] op_sel_hi:[0,1,1]
	v_pk_fma_f32 v[66:67], v[30:31], v[20:21], v[66:67] op_sel_hi:[0,1,1]
	v_pk_fma_f32 v[78:79], v[44:45], v[26:27], v[78:79] op_sel_hi:[0,1,1]
	v_pk_fma_f32 v[82:83], v[30:31], v[26:27], v[82:83] op_sel_hi:[0,1,1]
	v_pk_fma_f32 v[92:93], v[44:45], v[36:37], v[92:93] op_sel_hi:[0,1,1]
	v_pk_fma_f32 v[96:97], v[30:31], v[36:37], v[96:97] op_sel_hi:[0,1,1]
	v_pk_fma_f32 v[106:107], v[44:45], v[48:49], v[106:107] op_sel_hi:[0,1,1]
	v_pk_fma_f32 v[110:111], v[30:31], v[48:49], v[110:111] op_sel_hi:[0,1,1]
	v_pk_fma_f32 v[120:121], v[44:45], v[52:53], v[120:121] op_sel_hi:[0,1,1]
	v_pk_fma_f32 v[124:125], v[30:31], v[52:53], v[124:125] op_sel_hi:[0,1,1]
	v_mov_b32_e32 v23, v5
	v_pk_add_f32 v[130:131], v[130:131], v[176:177] neg_lo:[0,1] neg_hi:[0,1]
	v_pk_add_f32 v[176:177], v[138:139], v[182:183]
	v_pk_add_f32 v[138:139], v[138:139], v[182:183] neg_lo:[0,1] neg_hi:[0,1]
	v_pk_add_f32 v[182:183], v[178:179], v[186:187]
	v_pk_add_f32 v[178:179], v[178:179], v[186:187] neg_lo:[0,1] neg_hi:[0,1]
	v_pk_add_f32 v[186:187], v[160:161], v[180:181]
	v_pk_add_f32 v[160:161], v[160:161], v[180:181] neg_lo:[0,1] neg_hi:[0,1]
	v_pk_add_f32 v[180:181], v[168:169], v[188:189]
	v_pk_fma_f32 v[30:31], v[30:31], v[136:137], v[34:35] op_sel_hi:[0,1,1]
	v_pk_mul_f32 v[34:35], v[54:55], v[152:153] op_sel:[0,1] op_sel_hi:[1,0]
	v_pk_mul_f32 v[2:3], v[72:73], v[4:5] op_sel:[0,1] op_sel_hi:[1,0]
	v_xor_b32_e32 v12, 0x80000000, v9
	v_pk_mul_f32 v[24:25], v[72:73], v[10:11] op_sel:[0,1] op_sel_hi:[1,0]
	v_xor_b32_e32 v38, 0x80000000, v33
	v_xor_b32_e32 v50, 0x80000000, v11
	v_pk_mul_f32 v[56:57], v[72:73], v[20:21] op_sel:[0,1] op_sel_hi:[1,0]
	v_xor_b32_e32 v64, 0x80000000, v63
	v_xor_b32_e32 v70, 0x80000000, v21
	v_pk_mul_f32 v[74:75], v[72:73], v[26:27] op_sel:[0,1] op_sel_hi:[1,0]
	v_xor_b32_e32 v80, 0x80000000, v79
	v_xor_b32_e32 v86, 0x80000000, v27
	v_pk_mul_f32 v[88:89], v[72:73], v[36:37] op_sel:[0,1] op_sel_hi:[1,0]
	v_xor_b32_e32 v94, 0x80000000, v93
	v_xor_b32_e32 v100, 0x80000000, v37
	v_pk_mul_f32 v[102:103], v[72:73], v[48:49] op_sel:[0,1] op_sel_hi:[1,0]
	v_xor_b32_e32 v108, 0x80000000, v107
	v_xor_b32_e32 v114, 0x80000000, v49
	v_pk_mul_f32 v[116:117], v[52:53], v[72:73] op_sel:[1,0] op_sel_hi:[0,1]
	v_xor_b32_e32 v122, 0x80000000, v121
	v_mov_b32_e32 v123, v121
	v_mov_b32_e32 v115, v49
	v_mov_b32_e32 v109, v107
	v_mov_b32_e32 v101, v37
	v_mov_b32_e32 v95, v93
	v_mov_b32_e32 v87, v27
	v_mov_b32_e32 v81, v79
	v_mov_b32_e32 v71, v21
	v_mov_b32_e32 v65, v63
	v_mov_b32_e32 v51, v11
	v_mov_b32_e32 v39, v33
	v_mov_b32_e32 v13, v9
	v_pk_fma_f32 v[34:35], v[44:45], v[152:153], v[34:35] op_sel_hi:[0,1,1]
	v_pk_mul_f32 v[44:45], v[72:73], v[180:181] op_sel:[0,1] op_sel_hi:[1,0]
	v_pk_mul_f32 v[22:23], v[150:151], v[22:23] op_sel:[1,0] op_sel_hi:[0,1]
	v_pk_fma_f32 v[2:3], v[46:47], v[4:5], v[2:3] op_sel_hi:[0,1,1]
	v_pk_fma_f32 v[24:25], v[46:47], v[10:11], v[24:25] op_sel_hi:[0,1,1]
	v_pk_fma_f32 v[56:57], v[46:47], v[20:21], v[56:57] op_sel_hi:[0,1,1]
	v_pk_fma_f32 v[74:75], v[46:47], v[26:27], v[74:75] op_sel_hi:[0,1,1]
	v_xor_b32_e32 v84, 0x80000000, v83
	v_pk_fma_f32 v[88:89], v[46:47], v[36:37], v[88:89] op_sel_hi:[0,1,1]
	v_pk_fma_f32 v[102:103], v[46:47], v[48:49], v[102:103] op_sel_hi:[0,1,1]
	v_pk_fma_f32 v[116:117], v[52:53], v[46:47], v[116:117] op_sel_hi:[1,0,1]
	v_mov_b32_e32 v85, v83
	v_pk_fma_f32 v[44:45], v[46:47], v[180:181], v[44:45] op_sel_hi:[0,1,1]
	v_pk_mul_f32 v[46:47], v[58:59], v[192:193] op_sel:[0,1] op_sel_hi:[1,0]
	v_pk_mul_f32 v[54:55], v[122:123], v[154:155] op_sel:[0,1] op_sel_hi:[1,0]
	v_pk_mul_f32 v[72:73], v[114:115], v[194:195] op_sel:[0,1] op_sel_hi:[1,0]
	v_pk_mul_f32 v[108:109], v[108:109], v[158:159] op_sel:[0,1] op_sel_hi:[1,0]
	v_pk_mul_f32 v[100:101], v[100:101], v[156:157] op_sel:[0,1] op_sel_hi:[1,0]
	v_pk_mul_f32 v[94:95], v[94:95], v[144:145] op_sel:[0,1] op_sel_hi:[1,0]
	v_pk_mul_f32 v[86:87], v[174:175], v[86:87] op_sel:[1,0] op_sel_hi:[0,1]
	v_pk_mul_f32 v[80:81], v[140:141], v[80:81] op_sel:[1,0] op_sel_hi:[0,1]
	v_pk_mul_f32 v[70:71], v[148:149], v[70:71] op_sel:[1,0] op_sel_hi:[0,1]
	v_pk_mul_f32 v[64:65], v[132:133], v[64:65] op_sel:[1,0] op_sel_hi:[0,1]
	v_pk_mul_f32 v[50:51], v[190:191], v[50:51] op_sel:[1,0] op_sel_hi:[0,1]
	v_pk_mul_f32 v[38:39], v[142:143], v[38:39] op_sel:[1,0] op_sel_hi:[0,1]
	v_pk_fma_f32 v[4:5], v[150:151], v[4:5], v[22:23] op_sel_hi:[1,0,1]
	v_pk_mul_f32 v[12:13], v[134:135], v[12:13] op_sel:[1,0] op_sel_hi:[0,1]
	v_xor_b32_e32 v112, 0x80000000, v111
	v_mov_b32_e32 v113, v111
	v_pk_fma_f32 v[46:47], v[52:53], v[192:193], v[46:47] op_sel_hi:[0,1,1]
	v_pk_fma_f32 v[54:55], v[120:121], v[154:155], v[54:55] op_sel_hi:[0,1,1]
	v_pk_fma_f32 v[48:49], v[48:49], v[194:195], v[72:73] op_sel_hi:[0,1,1]
	v_pk_fma_f32 v[106:107], v[106:107], v[158:159], v[108:109] op_sel_hi:[0,1,1]
	v_pk_fma_f32 v[36:37], v[36:37], v[156:157], v[100:101] op_sel_hi:[0,1,1]
	v_pk_fma_f32 v[92:93], v[92:93], v[144:145], v[94:95] op_sel_hi:[0,1,1]
	v_pk_fma_f32 v[26:27], v[174:175], v[26:27], v[86:87] op_sel_hi:[1,0,1]
	v_pk_mul_f32 v[84:85], v[130:131], v[84:85] op_sel:[1,0] op_sel_hi:[0,1]
	v_pk_fma_f32 v[78:79], v[140:141], v[78:79], v[80:81] op_sel_hi:[1,0,1]
	v_pk_fma_f32 v[20:21], v[148:149], v[20:21], v[70:71] op_sel_hi:[1,0,1]
	v_pk_fma_f32 v[62:63], v[132:133], v[62:63], v[64:65] op_sel_hi:[1,0,1]
	v_pk_fma_f32 v[10:11], v[190:191], v[10:11], v[50:51] op_sel_hi:[1,0,1]
	v_pk_fma_f32 v[32:33], v[142:143], v[32:33], v[38:39] op_sel_hi:[1,0,1]
	v_pk_fma_f32 v[8:9], v[134:135], v[8:9], v[12:13] op_sel_hi:[1,0,1]
	ds_write_b64 v18, v[162:163]
	ds_write_b64 v18, v[26:27] offset:4224
	ds_write_b64 v18, v[48:49] offset:8448
	ds_write_b64 v18, v[10:11] offset:12672
	ds_write_b64 v18, v[46:47] offset:16896
	ds_write_b64 v18, v[20:21] offset:21120
	ds_write_b64 v18, v[36:37] offset:25344
	ds_write_b64 v18, v[4:5] offset:29568
	ds_write_b64 v18, v[34:35] offset:33792
	ds_write_b64 v18, v[78:79] offset:38016
	ds_write_b64 v18, v[106:107] offset:42240
	ds_write_b64 v18, v[32:33] offset:46464
	ds_write_b64 v18, v[54:55] offset:50688
	ds_write_b64 v18, v[62:63] offset:54912
	ds_write_b64 v18, v[92:93] offset:59136
	ds_write_b64 v18, v[8:9] offset:63360
	v_add_u32_e32 v4, 0x10800, v18
	v_xor_b32_e32 v42, 0x80000000, v41
	v_mov_b32_e32 v43, v41
	v_pk_mul_f32 v[72:73], v[112:113], v[176:177] op_sel:[0,1] op_sel_hi:[1,0]
	v_pk_fma_f32 v[82:83], v[130:131], v[82:83], v[84:85] op_sel_hi:[1,0,1]
	ds_write_b64 v4, v[30:31]
	v_add_u32_e32 v4, 0x11880, v18
	v_xor_b32_e32 v126, 0x80000000, v125
	v_mov_b32_e32 v127, v125
	v_pk_fma_f32 v[72:73], v[110:111], v[176:177], v[72:73] op_sel_hi:[0,1,1]
	v_pk_mul_f32 v[42:43], v[138:139], v[42:43] op_sel:[1,0] op_sel_hi:[0,1]
	ds_write_b64 v4, v[82:83]
	v_add_u32_e32 v4, 0x12900, v18
	v_xor_b32_e32 v68, 0x80000000, v67
	v_mov_b32_e32 v69, v67
	v_pk_mul_f32 v[52:53], v[126:127], v[182:183] op_sel:[0,1] op_sel_hi:[1,0]
	v_pk_fma_f32 v[40:41], v[138:139], v[40:41], v[42:43] op_sel_hi:[1,0,1]
	ds_write_b64 v4, v[72:73]
	v_add_u32_e32 v4, 0x13980, v18
	v_xor_b32_e32 v98, 0x80000000, v97
	v_mov_b32_e32 v99, v97
	v_pk_fma_f32 v[52:53], v[124:125], v[182:183], v[52:53] op_sel_hi:[0,1,1]
	v_pk_mul_f32 v[68:69], v[178:179], v[68:69] op_sel:[1,0] op_sel_hi:[0,1]
	ds_write_b64 v4, v[40:41]
	v_add_u32_e32 v4, 0x14a00, v18
	v_xor_b32_e32 v16, 0x80000000, v15
	v_mov_b32_e32 v17, v15
	v_pk_mul_f32 v[98:99], v[98:99], v[186:187] op_sel:[0,1] op_sel_hi:[1,0]
	v_pk_fma_f32 v[66:67], v[178:179], v[66:67], v[68:69] op_sel_hi:[1,0,1]
	ds_write_b64 v4, v[52:53]
	v_add_u32_e32 v4, 0x15a80, v18
	v_pk_fma_f32 v[96:97], v[96:97], v[186:187], v[98:99] op_sel_hi:[0,1,1]
	v_pk_mul_f32 v[16:17], v[160:161], v[16:17] op_sel:[1,0] op_sel_hi:[0,1]
	ds_write_b64 v4, v[66:67]
	v_add_u32_e32 v4, 0x16b00, v18
	v_xor_b32_e32 v76, 0x80000000, v75
	v_mov_b32_e32 v77, v75
	v_pk_add_f32 v[168:169], v[168:169], v[188:189] neg_lo:[0,1] neg_hi:[0,1]
	v_pk_fma_f32 v[14:15], v[160:161], v[14:15], v[16:17] op_sel_hi:[1,0,1]
	ds_write_b64 v4, v[96:97]
	v_add_u32_e32 v4, 0x17b80, v18
	v_xor_b32_e32 v104, 0x80000000, v103
	v_mov_b32_e32 v105, v103
	v_pk_add_f32 v[188:189], v[170:171], v[184:185]
	v_pk_mul_f32 v[76:77], v[168:169], v[76:77] op_sel:[1,0] op_sel_hi:[0,1]
	ds_write_b64 v4, v[14:15]
	v_add_u32_e32 v4, 0x18c00, v18
	v_xor_b32_e32 v28, 0x80000000, v25
	v_mov_b32_e32 v29, v25
	v_pk_add_f32 v[170:171], v[170:171], v[184:185] neg_lo:[0,1] neg_hi:[0,1]
	v_pk_mul_f32 v[104:105], v[104:105], v[188:189] op_sel:[0,1] op_sel_hi:[1,0]
	v_pk_fma_f32 v[74:75], v[168:169], v[74:75], v[76:77] op_sel_hi:[1,0,1]
	ds_write_b64 v4, v[44:45]
	v_add_u32_e32 v4, 0x19c80, v18
	v_xor_b32_e32 v118, 0x80000000, v117
	v_mov_b32_e32 v119, v117
	v_pk_add_f32 v[184:185], v[164:165], v[172:173]
	v_pk_fma_f32 v[102:103], v[102:103], v[188:189], v[104:105] op_sel_hi:[0,1,1]
	v_pk_mul_f32 v[28:29], v[170:171], v[28:29] op_sel:[1,0] op_sel_hi:[0,1]
	ds_write_b64 v4, v[74:75]
	v_add_u32_e32 v4, 0x1ad00, v18
	v_xor_b32_e32 v60, 0x80000000, v57
	v_mov_b32_e32 v61, v57
	v_pk_add_f32 v[164:165], v[164:165], v[172:173] neg_lo:[0,1] neg_hi:[0,1]
	v_pk_mul_f32 v[58:59], v[118:119], v[184:185] op_sel:[0,1] op_sel_hi:[1,0]
	v_pk_fma_f32 v[24:25], v[170:171], v[24:25], v[28:29] op_sel_hi:[1,0,1]
	ds_write_b64 v4, v[102:103]
	v_add_u32_e32 v4, 0x1bd80, v18
	v_xor_b32_e32 v90, 0x80000000, v89
	v_mov_b32_e32 v91, v89
	v_pk_add_f32 v[172:173], v[128:129], v[166:167]
	v_pk_fma_f32 v[58:59], v[116:117], v[184:185], v[58:59] op_sel_hi:[0,1,1]
	v_pk_mul_f32 v[60:61], v[164:165], v[60:61] op_sel:[1,0] op_sel_hi:[0,1]
	ds_write_b64 v4, v[24:25]
	v_add_u32_e32 v4, 0x1ce00, v18
	v_xor_b32_e32 v6, 0x80000000, v3
	v_mov_b32_e32 v7, v3
	v_pk_add_f32 v[128:129], v[128:129], v[166:167] neg_lo:[0,1] neg_hi:[0,1]
	v_pk_mul_f32 v[90:91], v[90:91], v[172:173] op_sel:[0,1] op_sel_hi:[1,0]
	v_pk_fma_f32 v[56:57], v[164:165], v[56:57], v[60:61] op_sel_hi:[1,0,1]
	ds_write_b64 v4, v[58:59]
	v_add_u32_e32 v4, 0x1de80, v18
	v_pk_fma_f32 v[88:89], v[88:89], v[172:173], v[90:91] op_sel_hi:[0,1,1]
	v_pk_mul_f32 v[6:7], v[128:129], v[6:7] op_sel:[1,0] op_sel_hi:[0,1]
	ds_write_b64 v4, v[56:57]
	v_add_u32_e32 v4, 0x1ef00, v18
	v_pk_fma_f32 v[2:3], v[128:129], v[2:3], v[6:7] op_sel_hi:[1,0,1]
	ds_write_b64 v4, v[88:89]
	v_add_u32_e32 v4, 0x1ff80, v18
	ds_write_b64 v4, v[2:3]
	v_mov_b32_e32 v2, v210
	s_waitcnt lgkmcnt(0)
	s_barrier
	s_ashr_i32 s77, s76, 31
	v_and_b32_e32 v3, 15, v2
	v_lshlrev_b32_e32 v2, 5, v2
	v_and_b32_e32 v4, 0xfffffe00, v2
	v_lshl_add_u32 v5, v4, 3, 0
	v_lshlrev_b32_e32 v6, 3, v3
	v_ashrrev_i32_e32 v7, 2, v4
	v_add3_u32 v18, v5, v6, v7
	v_add_u32_e32 v196, 0x800, v18
	ds_read2_b64 v[128:131], v18 offset1:16
	ds_read2_b64 v[132:135], v18 offset0:33 offset1:49
	ds_read2_b64 v[136:139], v18 offset0:66 offset1:82
	ds_read2_b64 v[140:143], v18 offset0:99 offset1:115
	ds_read2_b64 v[148:151], v18 offset0:132 offset1:148
	ds_read2_b64 v[152:155], v18 offset0:165 offset1:181
	ds_read2_b64 v[156:159], v18 offset0:198 offset1:214
	ds_read2_b64 v[160:163], v18 offset0:231 offset1:247
	ds_read2_b64 v[164:167], v196 offset0:8 offset1:24
	ds_read2_b64 v[168:171], v196 offset0:41 offset1:57
	ds_read2_b64 v[172:175], v196 offset0:74 offset1:90
	ds_read2_b64 v[176:179], v196 offset0:107 offset1:123
	ds_read2_b64 v[180:183], v196 offset0:140 offset1:156
	ds_read2_b64 v[184:187], v196 offset0:173 offset1:189
	ds_read2_b64 v[188:191], v196 offset0:206 offset1:222
	ds_read2_b64 v[192:195], v196 offset0:239 offset1:255
	s_waitcnt lgkmcnt(7)
	v_pk_add_f32 v[144:145], v[128:129], v[164:165]
	v_pk_add_f32 v[128:129], v[128:129], v[164:165] neg_lo:[0,1] neg_hi:[0,1]
	v_pk_add_f32 v[164:165], v[130:131], v[166:167]
	v_pk_add_f32 v[130:131], v[130:131], v[166:167] neg_lo:[0,1] neg_hi:[0,1]
	v_cvt_f32_ubyte0_e32 v2, v3
	v_pk_mul_f32 v[166:167], v[130:131], s[10:11]
	v_mul_f32_e32 v3, 0x3b000000, v2
	v_pk_fma_f32 v[130:131], v[130:131], s[8:9], v[166:167] op_sel:[0,0,1] op_sel_hi:[1,0,0]
	s_waitcnt lgkmcnt(6)
	v_pk_add_f32 v[166:167], v[132:133], v[168:169]
	v_pk_add_f32 v[132:133], v[132:133], v[168:169] neg_lo:[0,1] neg_hi:[0,1]
	v_sin_f32_e32 v2, v3
	v_pk_mul_f32 v[168:169], v[132:133], s[18:19]
	v_cos_f32_e32 v4, v3
	v_pk_fma_f32 v[132:133], v[132:133], s[16:17], v[168:169] op_sel:[0,0,1] op_sel_hi:[1,0,0]
	v_pk_add_f32 v[168:169], v[134:135], v[170:171]
	v_pk_add_f32 v[134:135], v[134:135], v[170:171] neg_lo:[0,1] neg_hi:[0,1]
	v_xor_b32_e32 v5, 0x80000000, v2
	v_pk_mul_f32 v[170:171], v[134:135], s[26:27]
	v_mov_b32_e32 v3, v5
	v_pk_fma_f32 v[134:135], v[134:135], s[24:25], v[170:171] op_sel:[0,0,1] op_sel_hi:[1,0,0]
	s_waitcnt lgkmcnt(5)
	v_pk_add_f32 v[170:171], v[136:137], v[172:173]
	v_pk_add_f32 v[136:137], v[136:137], v[172:173] neg_lo:[0,1] neg_hi:[0,1]
	v_pk_mul_f32 v[6:7], v[4:5], v[2:3] op_sel:[1,0] op_sel_hi:[0,1]
	v_pk_mul_f32 v[172:173], v[136:137], s[36:37]
	v_pk_fma_f32 v[6:7], v[4:5], v[4:5], v[6:7] op_sel_hi:[1,0,1]
	v_pk_fma_f32 v[136:137], v[136:137], s[78:79], v[172:173] op_sel:[0,0,1] op_sel_hi:[1,0,0]
	v_pk_add_f32 v[172:173], v[138:139], v[174:175]
	v_pk_add_f32 v[138:139], v[138:139], v[174:175] neg_lo:[0,1] neg_hi:[0,1]
	v_xor_b32_e32 v12, 0x80000000, v7
	v_pk_mul_f32 v[174:175], v[138:139], s[38:39]
	v_mov_b32_e32 v13, v7
	v_pk_fma_f32 v[138:139], v[138:139], s[0:1], v[174:175] op_sel:[0,0,1] op_sel_hi:[1,0,0]
	s_waitcnt lgkmcnt(4)
	v_pk_add_f32 v[174:175], v[140:141], v[176:177]
	v_pk_add_f32 v[140:141], v[140:141], v[176:177] neg_lo:[0,1] neg_hi:[0,1]
	v_pk_mul_f32 v[10:11], v[6:7], v[12:13] op_sel:[1,0] op_sel_hi:[0,1]
	v_pk_mul_f32 v[176:177], v[140:141], s[40:41]
	v_pk_fma_f32 v[10:11], v[6:7], v[6:7], v[10:11] op_sel_hi:[1,0,1]
	v_pk_fma_f32 v[140:141], v[140:141], s[80:81], v[176:177] op_sel:[0,0,1] op_sel_hi:[1,0,0]
	v_pk_add_f32 v[176:177], v[142:143], v[178:179]
	v_pk_add_f32 v[142:143], v[142:143], v[178:179] neg_lo:[0,1] neg_hi:[0,1]
	v_xor_b32_e32 v14, 0x80000000, v11
	v_pk_mul_f32 v[178:179], v[142:143], s[42:43]
	v_mov_b32_e32 v15, v11
	v_pk_fma_f32 v[142:143], v[142:143], s[74:75], v[178:179] op_sel:[0,0,1] op_sel_hi:[1,0,0]
	s_waitcnt lgkmcnt(3)
	v_pk_add_f32 v[178:179], v[148:149], v[180:181]
	v_pk_add_f32 v[148:149], v[148:149], v[180:181] neg_lo:[0,1] neg_hi:[0,1]
	v_pk_mul_f32 v[28:29], v[10:11], v[14:15] op_sel:[1,0] op_sel_hi:[0,1]
	v_xor_b32_e32 v181, 0x80000000, v148
	v_mov_b32_e32 v180, v149
	v_pk_add_f32 v[148:149], v[150:151], v[182:183]
	v_pk_add_f32 v[150:151], v[150:151], v[182:183] neg_lo:[0,1] neg_hi:[0,1]
	v_pk_fma_f32 v[28:29], v[10:11], v[10:11], v[28:29] op_sel_hi:[1,0,1]
	v_pk_mul_f32 v[182:183], v[150:151], s[42:43]
	v_pk_mul_f32 v[44:45], v[14:15], v[28:29] op_sel:[0,1] op_sel_hi:[1,0]
	v_pk_fma_f32 v[150:151], v[150:151], s[74:75], v[182:183] op_sel:[0,0,1] op_sel_hi:[1,0,0] neg_lo:[1,0,0] neg_hi:[1,0,0]
	s_waitcnt lgkmcnt(2)
	v_pk_add_f32 v[182:183], v[152:153], v[184:185]
	v_pk_add_f32 v[152:153], v[152:153], v[184:185] neg_lo:[0,1] neg_hi:[0,1]
	v_pk_fma_f32 v[44:45], v[10:11], v[28:29], v[44:45] op_sel_hi:[0,1,1]
	v_pk_mul_f32 v[184:185], v[152:153], s[40:41]
	v_pk_mul_f32 v[60:61], v[14:15], v[44:45] op_sel:[0,1] op_sel_hi:[1,0]
	v_pk_fma_f32 v[152:153], v[152:153], s[80:81], v[184:185] op_sel:[0,0,1] op_sel_hi:[1,0,0] neg_lo:[1,0,0] neg_hi:[1,0,0]
	v_pk_add_f32 v[184:185], v[154:155], v[186:187]
	v_pk_add_f32 v[154:155], v[154:155], v[186:187] neg_lo:[0,1] neg_hi:[0,1]
	v_pk_fma_f32 v[60:61], v[10:11], v[44:45], v[60:61] op_sel_hi:[0,1,1]
	v_pk_mul_f32 v[186:187], v[154:155], s[38:39]
	v_pk_mul_f32 v[76:77], v[14:15], v[60:61] op_sel:[0,1] op_sel_hi:[1,0]
	v_pk_fma_f32 v[154:155], v[154:155], s[0:1], v[186:187] op_sel:[0,0,1] op_sel_hi:[1,0,0] neg_lo:[1,0,0] neg_hi:[1,0,0]
	s_waitcnt lgkmcnt(1)
	v_pk_add_f32 v[186:187], v[156:157], v[188:189]
	v_pk_add_f32 v[156:157], v[156:157], v[188:189] neg_lo:[0,1] neg_hi:[0,1]
	v_pk_fma_f32 v[76:77], v[10:11], v[60:61], v[76:77] op_sel_hi:[0,1,1]
	v_pk_mul_f32 v[188:189], v[156:157], s[36:37]
	v_pk_mul_f32 v[92:93], v[14:15], v[76:77] op_sel:[0,1] op_sel_hi:[1,0]
	v_pk_fma_f32 v[156:157], v[156:157], s[78:79], v[188:189] op_sel:[0,0,1] op_sel_hi:[1,0,0] neg_lo:[1,0,0] neg_hi:[1,0,0]
	v_pk_add_f32 v[188:189], v[158:159], v[190:191]
	v_pk_add_f32 v[158:159], v[158:159], v[190:191] neg_lo:[0,1] neg_hi:[0,1]
	v_pk_fma_f32 v[92:93], v[10:11], v[76:77], v[92:93] op_sel_hi:[0,1,1]
	v_pk_mul_f32 v[190:191], v[158:159], s[26:27]
	v_pk_mul_f32 v[108:109], v[14:15], v[92:93] op_sel:[0,1] op_sel_hi:[1,0]
	v_pk_fma_f32 v[158:159], v[158:159], s[24:25], v[190:191] op_sel:[0,0,1] op_sel_hi:[1,0,0] neg_lo:[1,0,0] neg_hi:[1,0,0]
	s_waitcnt lgkmcnt(0)
	v_pk_add_f32 v[190:191], v[160:161], v[192:193]
	v_pk_add_f32 v[160:161], v[160:161], v[192:193] neg_lo:[0,1] neg_hi:[0,1]
	v_pk_mul_f32 v[8:9], v[2:3], v[6:7] op_sel:[0,1] op_sel_hi:[1,0]
	v_pk_mul_f32 v[192:193], v[160:161], s[18:19]
	v_pk_fma_f32 v[108:109], v[10:11], v[92:93], v[108:109] op_sel_hi:[0,1,1]
	v_pk_fma_f32 v[160:161], v[160:161], s[16:17], v[192:193] op_sel:[0,0,1] op_sel_hi:[1,0,0] neg_lo:[1,0,0] neg_hi:[1,0,0]
	v_pk_add_f32 v[192:193], v[162:163], v[194:195]
	v_pk_add_f32 v[162:163], v[162:163], v[194:195] neg_lo:[0,1] neg_hi:[0,1]
	v_pk_fma_f32 v[8:9], v[4:5], v[6:7], v[8:9] op_sel_hi:[0,1,1]
	v_pk_mul_f32 v[194:195], v[162:163], s[10:11]
	v_pk_mul_f32 v[16:17], v[2:3], v[10:11] op_sel:[0,1] op_sel_hi:[1,0]
	v_pk_fma_f32 v[162:163], v[162:163], s[8:9], v[194:195] op_sel:[0,0,1] op_sel_hi:[1,0,0] neg_lo:[1,0,0] neg_hi:[1,0,0]
	v_pk_add_f32 v[194:195], v[144:145], v[178:179]
	v_pk_add_f32 v[144:145], v[144:145], v[178:179] neg_lo:[0,1] neg_hi:[0,1]
	v_pk_add_f32 v[178:179], v[164:165], v[148:149]
	v_pk_add_f32 v[148:149], v[164:165], v[148:149] neg_lo:[0,1] neg_hi:[0,1]
	v_pk_mul_f32 v[32:33], v[2:3], v[28:29] op_sel:[0,1] op_sel_hi:[1,0]
	v_pk_mul_f32 v[164:165], v[148:149], s[18:19]
	v_pk_mul_f32 v[48:49], v[2:3], v[44:45] op_sel:[0,1] op_sel_hi:[1,0]
	v_pk_fma_f32 v[148:149], v[148:149], s[16:17], v[164:165] op_sel:[0,0,1] op_sel_hi:[1,0,0]
	v_pk_add_f32 v[164:165], v[166:167], v[182:183]
	v_pk_add_f32 v[166:167], v[166:167], v[182:183] neg_lo:[0,1] neg_hi:[0,1]
	v_pk_mul_f32 v[64:65], v[2:3], v[60:61] op_sel:[0,1] op_sel_hi:[1,0]
	v_pk_mul_f32 v[182:183], v[166:167], s[36:37]
	v_pk_mul_f32 v[80:81], v[2:3], v[76:77] op_sel:[0,1] op_sel_hi:[1,0]
	v_pk_fma_f32 v[166:167], v[166:167], s[78:79], v[182:183] op_sel:[0,0,1] op_sel_hi:[1,0,0]
	v_pk_add_f32 v[182:183], v[168:169], v[184:185]
	v_pk_add_f32 v[168:169], v[168:169], v[184:185] neg_lo:[0,1] neg_hi:[0,1]
	v_pk_mul_f32 v[96:97], v[2:3], v[92:93] op_sel:[0,1] op_sel_hi:[1,0]
	v_pk_mul_f32 v[184:185], v[168:169], s[40:41]
	v_pk_mul_f32 v[112:113], v[2:3], v[108:109] op_sel:[0,1] op_sel_hi:[1,0]
	v_pk_fma_f32 v[168:169], v[168:169], s[80:81], v[184:185] op_sel:[0,0,1] op_sel_hi:[1,0,0]
	v_pk_add_f32 v[184:185], v[170:171], v[186:187]
	v_pk_add_f32 v[170:171], v[170:171], v[186:187] neg_lo:[0,1] neg_hi:[0,1]
	v_xor_b32_e32 v22, 0x80000000, v9
	v_xor_b32_e32 v187, 0x80000000, v170
	v_mov_b32_e32 v186, v171
	v_pk_add_f32 v[170:171], v[172:173], v[188:189]
	v_pk_add_f32 v[172:173], v[172:173], v[188:189] neg_lo:[0,1] neg_hi:[0,1]
	v_mov_b32_e32 v23, v9
	v_pk_mul_f32 v[188:189], v[172:173], s[40:41]
	v_pk_fma_f32 v[16:17], v[4:5], v[10:11], v[16:17] op_sel_hi:[0,1,1]
	v_pk_fma_f32 v[172:173], v[172:173], s[80:81], v[188:189] op_sel:[0,0,1] op_sel_hi:[1,0,0] neg_lo:[1,0,0] neg_hi:[1,0,0]
	v_pk_add_f32 v[188:189], v[174:175], v[190:191]
	v_pk_add_f32 v[174:175], v[174:175], v[190:191] neg_lo:[0,1] neg_hi:[0,1]
	v_pk_mul_f32 v[20:21], v[12:13], v[10:11] op_sel:[0,1] op_sel_hi:[1,0]
	v_pk_mul_f32 v[190:191], v[174:175], s[36:37]
	v_pk_fma_f32 v[32:33], v[4:5], v[28:29], v[32:33] op_sel_hi:[0,1,1]
	v_pk_fma_f32 v[174:175], v[174:175], s[78:79], v[190:191] op_sel:[0,0,1] op_sel_hi:[1,0,0] neg_lo:[1,0,0] neg_hi:[1,0,0]
	v_pk_add_f32 v[190:191], v[176:177], v[192:193]
	v_pk_add_f32 v[176:177], v[176:177], v[192:193] neg_lo:[0,1] neg_hi:[0,1]
	v_pk_mul_f32 v[36:37], v[12:13], v[28:29] op_sel:[0,1] op_sel_hi:[1,0]
	v_pk_mul_f32 v[192:193], v[176:177], s[18:19]
	v_pk_fma_f32 v[48:49], v[4:5], v[44:45], v[48:49] op_sel_hi:[0,1,1]
	v_pk_fma_f32 v[176:177], v[176:177], s[16:17], v[192:193] op_sel:[0,0,1] op_sel_hi:[1,0,0] neg_lo:[1,0,0] neg_hi:[1,0,0]
	v_pk_add_f32 v[192:193], v[128:129], v[180:181]
	v_pk_add_f32 v[128:129], v[128:129], v[180:181] neg_lo:[0,1] neg_hi:[0,1]
	v_pk_add_f32 v[180:181], v[130:131], v[150:151]
	v_pk_add_f32 v[130:131], v[130:131], v[150:151] neg_lo:[0,1] neg_hi:[0,1]
	v_pk_mul_f32 v[52:53], v[12:13], v[44:45] op_sel:[0,1] op_sel_hi:[1,0]
	v_pk_mul_f32 v[150:151], v[130:131], s[18:19]
	v_pk_fma_f32 v[64:65], v[4:5], v[60:61], v[64:65] op_sel_hi:[0,1,1]
	v_pk_fma_f32 v[130:131], v[130:131], s[16:17], v[150:151] op_sel:[0,0,1] op_sel_hi:[1,0,0]
	v_pk_add_f32 v[150:151], v[132:133], v[152:153]
	v_pk_add_f32 v[132:133], v[132:133], v[152:153] neg_lo:[0,1] neg_hi:[0,1]
	v_pk_mul_f32 v[68:69], v[12:13], v[60:61] op_sel:[0,1] op_sel_hi:[1,0]
	v_pk_mul_f32 v[152:153], v[132:133], s[36:37]
	v_pk_fma_f32 v[80:81], v[4:5], v[76:77], v[80:81] op_sel_hi:[0,1,1]
	v_pk_fma_f32 v[132:133], v[132:133], s[78:79], v[152:153] op_sel:[0,0,1] op_sel_hi:[1,0,0]
	v_pk_add_f32 v[152:153], v[134:135], v[154:155]
	v_pk_add_f32 v[134:135], v[134:135], v[154:155] neg_lo:[0,1] neg_hi:[0,1]
	v_pk_mul_f32 v[84:85], v[12:13], v[76:77] op_sel:[0,1] op_sel_hi:[1,0]
	v_pk_mul_f32 v[154:155], v[134:135], s[40:41]
	v_pk_fma_f32 v[96:97], v[4:5], v[92:93], v[96:97] op_sel_hi:[0,1,1]
	v_pk_fma_f32 v[134:135], v[134:135], s[80:81], v[154:155] op_sel:[0,0,1] op_sel_hi:[1,0,0]
	v_pk_add_f32 v[154:155], v[136:137], v[156:157]
	v_pk_add_f32 v[136:137], v[136:137], v[156:157] neg_lo:[0,1] neg_hi:[0,1]
	v_pk_mul_f32 v[100:101], v[12:13], v[92:93] op_sel:[0,1] op_sel_hi:[1,0]
	v_xor_b32_e32 v157, 0x80000000, v136
	v_mov_b32_e32 v156, v137
	v_pk_add_f32 v[136:137], v[138:139], v[158:159]
	v_pk_add_f32 v[138:139], v[138:139], v[158:159] neg_lo:[0,1] neg_hi:[0,1]
	v_pk_fma_f32 v[112:113], v[4:5], v[108:109], v[112:113] op_sel_hi:[0,1,1]
	v_pk_mul_f32 v[158:159], v[138:139], s[40:41]
	v_pk_mul_f32 v[116:117], v[12:13], v[108:109] op_sel:[0,1] op_sel_hi:[1,0]
	v_pk_fma_f32 v[138:139], v[138:139], s[80:81], v[158:159] op_sel:[0,0,1] op_sel_hi:[1,0,0] neg_lo:[1,0,0] neg_hi:[1,0,0]
	v_pk_add_f32 v[158:159], v[140:141], v[160:161]
	v_pk_add_f32 v[140:141], v[140:141], v[160:161] neg_lo:[0,1] neg_hi:[0,1]
	v_pk_fma_f32 v[20:21], v[6:7], v[10:11], v[20:21] op_sel_hi:[0,1,1]
	v_pk_mul_f32 v[160:161], v[140:141], s[36:37]
	v_pk_mul_f32 v[24:25], v[10:11], v[22:23] op_sel:[1,0] op_sel_hi:[0,1]
	v_pk_fma_f32 v[140:141], v[140:141], s[78:79], v[160:161] op_sel:[0,0,1] op_sel_hi:[1,0,0] neg_lo:[1,0,0] neg_hi:[1,0,0]
	v_pk_add_f32 v[160:161], v[142:143], v[162:163]
	v_pk_add_f32 v[142:143], v[142:143], v[162:163] neg_lo:[0,1] neg_hi:[0,1]
	v_pk_fma_f32 v[36:37], v[6:7], v[28:29], v[36:37] op_sel_hi:[0,1,1]
	v_pk_mul_f32 v[162:163], v[142:143], s[18:19]
	v_pk_mul_f32 v[40:41], v[22:23], v[28:29] op_sel:[0,1] op_sel_hi:[1,0]
	v_pk_fma_f32 v[142:143], v[142:143], s[16:17], v[162:163] op_sel:[0,0,1] op_sel_hi:[1,0,0] neg_lo:[1,0,0] neg_hi:[1,0,0]
	v_pk_add_f32 v[162:163], v[194:195], v[184:185]
	v_pk_add_f32 v[184:185], v[194:195], v[184:185] neg_lo:[0,1] neg_hi:[0,1]
	v_pk_add_f32 v[194:195], v[178:179], v[170:171]
	v_pk_add_f32 v[170:171], v[178:179], v[170:171] neg_lo:[0,1] neg_hi:[0,1]
	v_pk_fma_f32 v[52:53], v[6:7], v[44:45], v[52:53] op_sel_hi:[0,1,1]
	v_pk_mul_f32 v[178:179], v[170:171], s[36:37]
	v_pk_mul_f32 v[56:57], v[22:23], v[44:45] op_sel:[0,1] op_sel_hi:[1,0]
	v_pk_fma_f32 v[170:171], v[170:171], s[78:79], v[178:179] op_sel:[0,0,1] op_sel_hi:[1,0,0]
	v_pk_add_f32 v[178:179], v[164:165], v[188:189]
	v_pk_add_f32 v[164:165], v[164:165], v[188:189] neg_lo:[0,1] neg_hi:[0,1]
	v_pk_fma_f32 v[68:69], v[6:7], v[60:61], v[68:69] op_sel_hi:[0,1,1]
	v_xor_b32_e32 v189, 0x80000000, v164
	v_mov_b32_e32 v188, v165
	v_pk_add_f32 v[164:165], v[182:183], v[190:191]
	v_pk_add_f32 v[182:183], v[182:183], v[190:191] neg_lo:[0,1] neg_hi:[0,1]
	v_pk_mul_f32 v[72:73], v[22:23], v[60:61] op_sel:[0,1] op_sel_hi:[1,0]
	v_pk_mul_f32 v[190:191], v[182:183], s[36:37]
	v_pk_fma_f32 v[84:85], v[6:7], v[76:77], v[84:85] op_sel_hi:[0,1,1]
	v_pk_fma_f32 v[182:183], v[182:183], s[78:79], v[190:191] op_sel:[0,0,1] op_sel_hi:[1,0,0] neg_lo:[1,0,0] neg_hi:[1,0,0]
	v_pk_add_f32 v[190:191], v[144:145], v[186:187]
	v_pk_add_f32 v[144:145], v[144:145], v[186:187] neg_lo:[0,1] neg_hi:[0,1]
	v_pk_add_f32 v[186:187], v[148:149], v[172:173]
	v_pk_add_f32 v[148:149], v[148:149], v[172:173] neg_lo:[0,1] neg_hi:[0,1]
	v_pk_mul_f32 v[88:89], v[22:23], v[76:77] op_sel:[0,1] op_sel_hi:[1,0]
	v_pk_mul_f32 v[172:173], v[148:149], s[36:37]
	v_pk_fma_f32 v[100:101], v[6:7], v[92:93], v[100:101] op_sel_hi:[0,1,1]
	v_pk_fma_f32 v[148:149], v[148:149], s[78:79], v[172:173] op_sel:[0,0,1] op_sel_hi:[1,0,0]
	v_pk_add_f32 v[172:173], v[166:167], v[174:175]
	v_pk_add_f32 v[166:167], v[166:167], v[174:175] neg_lo:[0,1] neg_hi:[0,1]
	v_pk_mul_f32 v[104:105], v[22:23], v[92:93] op_sel:[0,1] op_sel_hi:[1,0]
	v_xor_b32_e32 v175, 0x80000000, v166
	v_mov_b32_e32 v174, v167
	v_pk_add_f32 v[166:167], v[168:169], v[176:177]
	v_pk_add_f32 v[168:169], v[168:169], v[176:177] neg_lo:[0,1] neg_hi:[0,1]
	v_pk_fma_f32 v[116:117], v[6:7], v[108:109], v[116:117] op_sel_hi:[0,1,1]
	v_pk_mul_f32 v[176:177], v[168:169], s[36:37]
	v_pk_mul_f32 v[120:121], v[22:23], v[108:109] op_sel:[0,1] op_sel_hi:[1,0]
	v_pk_fma_f32 v[168:169], v[168:169], s[78:79], v[176:177] op_sel:[0,0,1] op_sel_hi:[1,0,0] neg_lo:[1,0,0] neg_hi:[1,0,0]
	v_pk_add_f32 v[176:177], v[192:193], v[154:155]
	v_pk_add_f32 v[154:155], v[192:193], v[154:155] neg_lo:[0,1] neg_hi:[0,1]
	v_pk_add_f32 v[192:193], v[180:181], v[136:137]
	v_pk_add_f32 v[136:137], v[180:181], v[136:137] neg_lo:[0,1] neg_hi:[0,1]
	v_xor_b32_e32 v26, 0x80000000, v17
	v_pk_mul_f32 v[180:181], v[136:137], s[36:37]
	v_xor_b32_e32 v30, 0x80000000, v21
	v_pk_fma_f32 v[136:137], v[136:137], s[78:79], v[180:181] op_sel:[0,0,1] op_sel_hi:[1,0,0]
	v_pk_add_f32 v[180:181], v[150:151], v[158:159]
	v_pk_add_f32 v[150:151], v[150:151], v[158:159] neg_lo:[0,1] neg_hi:[0,1]
	v_pk_fma_f32 v[24:25], v[10:11], v[8:9], v[24:25] op_sel_hi:[1,0,1]
	v_xor_b32_e32 v159, 0x80000000, v150
	v_mov_b32_e32 v158, v151
	v_pk_add_f32 v[150:151], v[152:153], v[160:161]
	v_pk_add_f32 v[152:153], v[152:153], v[160:161] neg_lo:[0,1] neg_hi:[0,1]
	v_pk_fma_f32 v[40:41], v[8:9], v[28:29], v[40:41] op_sel_hi:[0,1,1]
	v_pk_mul_f32 v[160:161], v[152:153], s[36:37]
	v_pk_fma_f32 v[56:57], v[8:9], v[44:45], v[56:57] op_sel_hi:[0,1,1]
	v_pk_fma_f32 v[152:153], v[152:153], s[78:79], v[160:161] op_sel:[0,0,1] op_sel_hi:[1,0,0] neg_lo:[1,0,0] neg_hi:[1,0,0]
	v_pk_add_f32 v[160:161], v[128:129], v[156:157]
	v_pk_add_f32 v[128:129], v[128:129], v[156:157] neg_lo:[0,1] neg_hi:[0,1]
	v_pk_add_f32 v[156:157], v[130:131], v[138:139]
	v_pk_add_f32 v[130:131], v[130:131], v[138:139] neg_lo:[0,1] neg_hi:[0,1]
	v_pk_fma_f32 v[72:73], v[8:9], v[60:61], v[72:73] op_sel_hi:[0,1,1]
	v_pk_mul_f32 v[138:139], v[130:131], s[36:37]
	v_pk_fma_f32 v[88:89], v[8:9], v[76:77], v[88:89] op_sel_hi:[0,1,1]
	v_pk_fma_f32 v[130:131], v[130:131], s[78:79], v[138:139] op_sel:[0,0,1] op_sel_hi:[1,0,0]
	v_pk_add_f32 v[138:139], v[132:133], v[140:141]
	v_pk_add_f32 v[132:133], v[132:133], v[140:141] neg_lo:[0,1] neg_hi:[0,1]
	v_pk_fma_f32 v[104:105], v[8:9], v[92:93], v[104:105] op_sel_hi:[0,1,1]
	v_xor_b32_e32 v141, 0x80000000, v132
	v_mov_b32_e32 v140, v133
	v_pk_add_f32 v[132:133], v[134:135], v[142:143]
	v_pk_add_f32 v[134:135], v[134:135], v[142:143] neg_lo:[0,1] neg_hi:[0,1]
	v_pk_fma_f32 v[120:121], v[8:9], v[108:109], v[120:121] op_sel_hi:[0,1,1]
	v_pk_mul_f32 v[142:143], v[134:135], s[36:37]
	v_mov_b32_e32 v27, v17
	v_pk_fma_f32 v[134:135], v[134:135], s[78:79], v[142:143] op_sel:[0,0,1] op_sel_hi:[1,0,0] neg_lo:[1,0,0] neg_hi:[1,0,0]
	v_pk_add_f32 v[142:143], v[162:163], v[178:179]
	v_pk_add_f32 v[162:163], v[162:163], v[178:179] neg_lo:[0,1] neg_hi:[0,1]
	v_pk_add_f32 v[178:179], v[194:195], v[164:165]
	v_pk_add_f32 v[164:165], v[194:195], v[164:165] neg_lo:[0,1] neg_hi:[0,1]
	v_mov_b32_e32 v31, v21
	v_xor_b32_e32 v195, 0x80000000, v164
	v_mov_b32_e32 v194, v165
	v_pk_add_f32 v[164:165], v[184:185], v[188:189]
	v_pk_add_f32 v[184:185], v[184:185], v[188:189] neg_lo:[0,1] neg_hi:[0,1]
	v_pk_add_f32 v[188:189], v[170:171], v[182:183]
	v_pk_add_f32 v[170:171], v[170:171], v[182:183] neg_lo:[0,1] neg_hi:[0,1]
	v_xor_b32_e32 v34, 0x80000000, v25
	v_xor_b32_e32 v183, 0x80000000, v170
	v_mov_b32_e32 v182, v171
	v_pk_add_f32 v[170:171], v[190:191], v[172:173]
	v_pk_add_f32 v[172:173], v[190:191], v[172:173] neg_lo:[0,1] neg_hi:[0,1]
	v_pk_add_f32 v[190:191], v[186:187], v[166:167]
	v_pk_add_f32 v[166:167], v[186:187], v[166:167] neg_lo:[0,1] neg_hi:[0,1]
	v_xor_b32_e32 v38, 0x80000000, v29
	v_xor_b32_e32 v187, 0x80000000, v166
	v_mov_b32_e32 v186, v167
	v_pk_add_f32 v[166:167], v[144:145], v[174:175]
	v_pk_add_f32 v[144:145], v[144:145], v[174:175] neg_lo:[0,1] neg_hi:[0,1]
	v_pk_add_f32 v[174:175], v[148:149], v[168:169]
	v_pk_add_f32 v[148:149], v[148:149], v[168:169] neg_lo:[0,1] neg_hi:[0,1]
	v_xor_b32_e32 v42, 0x80000000, v33
	v_xor_b32_e32 v169, 0x80000000, v148
	v_mov_b32_e32 v168, v149
	v_pk_add_f32 v[148:149], v[176:177], v[180:181]
	v_pk_add_f32 v[176:177], v[176:177], v[180:181] neg_lo:[0,1] neg_hi:[0,1]
	v_pk_add_f32 v[180:181], v[192:193], v[150:151]
	v_pk_add_f32 v[150:151], v[192:193], v[150:151] neg_lo:[0,1] neg_hi:[0,1]
	v_xor_b32_e32 v46, 0x80000000, v37
	v_xor_b32_e32 v193, 0x80000000, v150
	v_mov_b32_e32 v192, v151
	v_pk_add_f32 v[150:151], v[154:155], v[158:159]
	v_pk_add_f32 v[154:155], v[154:155], v[158:159] neg_lo:[0,1] neg_hi:[0,1]
	v_pk_add_f32 v[158:159], v[136:137], v[152:153]
	v_pk_add_f32 v[136:137], v[136:137], v[152:153] neg_lo:[0,1] neg_hi:[0,1]
	v_mov_b32_e32 v35, v25
	v_xor_b32_e32 v153, 0x80000000, v136
	v_mov_b32_e32 v152, v137
	v_pk_add_f32 v[136:137], v[160:161], v[138:139]
	v_pk_add_f32 v[138:139], v[160:161], v[138:139] neg_lo:[0,1] neg_hi:[0,1]
	v_pk_add_f32 v[160:161], v[156:157], v[132:133]
	v_pk_add_f32 v[132:133], v[156:157], v[132:133] neg_lo:[0,1] neg_hi:[0,1]
	v_mov_b32_e32 v39, v29
	v_xor_b32_e32 v157, 0x80000000, v132
	v_mov_b32_e32 v156, v133
	v_pk_add_f32 v[132:133], v[128:129], v[140:141]
	v_pk_add_f32 v[128:129], v[128:129], v[140:141] neg_lo:[0,1] neg_hi:[0,1]
	v_pk_add_f32 v[140:141], v[130:131], v[134:135]
	v_pk_add_f32 v[130:131], v[130:131], v[134:135] neg_lo:[0,1] neg_hi:[0,1]
	v_mov_b32_e32 v43, v33
	v_xor_b32_e32 v135, 0x80000000, v130
	v_mov_b32_e32 v134, v131
	v_pk_add_f32 v[130:131], v[142:143], v[178:179]
	v_pk_add_f32 v[142:143], v[142:143], v[178:179] neg_lo:[0,1] neg_hi:[0,1]
	v_pk_add_f32 v[178:179], v[162:163], v[194:195]
	v_pk_add_f32 v[162:163], v[162:163], v[194:195] neg_lo:[0,1] neg_hi:[0,1]
	v_pk_add_f32 v[194:195], v[164:165], v[188:189]
	v_pk_add_f32 v[164:165], v[164:165], v[188:189] neg_lo:[0,1] neg_hi:[0,1]
	v_pk_add_f32 v[188:189], v[184:185], v[182:183]
	v_pk_add_f32 v[182:183], v[184:185], v[182:183] neg_lo:[0,1] neg_hi:[0,1]
	v_pk_add_f32 v[184:185], v[170:171], v[190:191]
	v_pk_add_f32 v[170:171], v[170:171], v[190:191] neg_lo:[0,1] neg_hi:[0,1]
	v_pk_add_f32 v[190:191], v[172:173], v[186:187]
	v_pk_add_f32 v[172:173], v[172:173], v[186:187] neg_lo:[0,1] neg_hi:[0,1]
	v_pk_add_f32 v[186:187], v[166:167], v[174:175]
	v_pk_add_f32 v[166:167], v[166:167], v[174:175] neg_lo:[0,1] neg_hi:[0,1]
	v_pk_add_f32 v[174:175], v[144:145], v[168:169]
	v_pk_add_f32 v[144:145], v[144:145], v[168:169] neg_lo:[0,1] neg_hi:[0,1]
	v_pk_add_f32 v[168:169], v[148:149], v[180:181]
	v_pk_add_f32 v[148:149], v[148:149], v[180:181] neg_lo:[0,1] neg_hi:[0,1]
	v_pk_mul_f32 v[2:3], v[2:3], v[168:169] op_sel:[0,1] op_sel_hi:[1,0]
	v_pk_add_f32 v[180:181], v[176:177], v[192:193]
	v_pk_add_f32 v[176:177], v[176:177], v[192:193] neg_lo:[0,1] neg_hi:[0,1]
	v_pk_add_f32 v[192:193], v[150:151], v[158:159]
	v_pk_add_f32 v[150:151], v[150:151], v[158:159] neg_lo:[0,1] neg_hi:[0,1]
	v_pk_add_f32 v[158:159], v[154:155], v[152:153]
	v_pk_add_f32 v[152:153], v[154:155], v[152:153] neg_lo:[0,1] neg_hi:[0,1]
	v_pk_add_f32 v[154:155], v[136:137], v[160:161]
	v_pk_fma_f32 v[2:3], v[4:5], v[168:169], v[2:3] op_sel_hi:[0,1,1]
	v_pk_mul_f32 v[4:5], v[12:13], v[184:185] op_sel:[0,1] op_sel_hi:[1,0]
	v_mov_b32_e32 v47, v37
	v_pk_fma_f32 v[4:5], v[6:7], v[184:185], v[4:5] op_sel_hi:[0,1,1]
	v_pk_mul_f32 v[6:7], v[22:23], v[154:155] op_sel:[0,1] op_sel_hi:[1,0]
	v_pk_add_f32 v[136:137], v[136:137], v[160:161] neg_lo:[0,1] neg_hi:[0,1]
	v_pk_fma_f32 v[6:7], v[8:9], v[154:155], v[6:7] op_sel_hi:[0,1,1]
	v_pk_mul_f32 v[8:9], v[14:15], v[194:195] op_sel:[0,1] op_sel_hi:[1,0]
	v_pk_add_f32 v[160:161], v[138:139], v[156:157]
	v_pk_add_f32 v[138:139], v[138:139], v[156:157] neg_lo:[0,1] neg_hi:[0,1]
	v_pk_add_f32 v[156:157], v[132:133], v[140:141]
	v_pk_fma_f32 v[8:9], v[10:11], v[194:195], v[8:9] op_sel_hi:[0,1,1]
	v_pk_mul_f32 v[10:11], v[26:27], v[192:193] op_sel:[0,1] op_sel_hi:[1,0]
	v_pk_mul_f32 v[12:13], v[30:31], v[186:187] op_sel:[0,1] op_sel_hi:[1,0]
	v_xor_b32_e32 v50, 0x80000000, v41
	v_xor_b32_e32 v54, 0x80000000, v45
	v_xor_b32_e32 v58, 0x80000000, v49
	v_xor_b32_e32 v62, 0x80000000, v53
	v_xor_b32_e32 v66, 0x80000000, v57
	v_xor_b32_e32 v70, 0x80000000, v61
	v_xor_b32_e32 v74, 0x80000000, v65
	v_mov_b32_e32 v51, v41
	v_mov_b32_e32 v55, v45
	v_mov_b32_e32 v59, v49
	v_mov_b32_e32 v63, v53
	v_mov_b32_e32 v67, v57
	v_mov_b32_e32 v71, v61
	v_mov_b32_e32 v75, v65
	v_pk_add_f32 v[132:133], v[132:133], v[140:141] neg_lo:[0,1] neg_hi:[0,1]
	v_pk_add_f32 v[140:141], v[128:129], v[134:135]
	v_pk_fma_f32 v[10:11], v[16:17], v[192:193], v[10:11] op_sel_hi:[0,1,1]
	v_pk_fma_f32 v[12:13], v[20:21], v[186:187], v[12:13] op_sel_hi:[0,1,1]
	v_pk_mul_f32 v[14:15], v[34:35], v[156:157] op_sel:[0,1] op_sel_hi:[1,0]
	v_pk_mul_f32 v[16:17], v[38:39], v[178:179] op_sel:[0,1] op_sel_hi:[1,0]
	v_pk_mul_f32 v[20:21], v[42:43], v[180:181] op_sel:[0,1] op_sel_hi:[1,0]
	v_pk_mul_f32 v[22:23], v[46:47], v[190:191] op_sel:[0,1] op_sel_hi:[1,0]
	v_xor_b32_e32 v78, 0x80000000, v69
	v_xor_b32_e32 v82, 0x80000000, v73
	v_xor_b32_e32 v86, 0x80000000, v77
	v_xor_b32_e32 v90, 0x80000000, v81
	v_xor_b32_e32 v94, 0x80000000, v85
	v_xor_b32_e32 v98, 0x80000000, v89
	v_xor_b32_e32 v102, 0x80000000, v93
	v_xor_b32_e32 v106, 0x80000000, v97
	v_xor_b32_e32 v110, 0x80000000, v101
	v_xor_b32_e32 v114, 0x80000000, v105
	v_xor_b32_e32 v118, 0x80000000, v109
	v_xor_b32_e32 v122, 0x80000000, v113
	v_xor_b32_e32 v124, 0x80000000, v117
	v_xor_b32_e32 v126, 0x80000000, v121
	v_mov_b32_e32 v79, v69
	v_mov_b32_e32 v83, v73
	v_mov_b32_e32 v87, v77
	v_mov_b32_e32 v91, v81
	v_mov_b32_e32 v95, v85
	v_mov_b32_e32 v99, v89
	v_mov_b32_e32 v103, v93
	v_mov_b32_e32 v107, v97
	v_mov_b32_e32 v111, v101
	v_mov_b32_e32 v115, v105
	v_mov_b32_e32 v119, v109
	v_mov_b32_e32 v123, v113
	v_mov_b32_e32 v125, v117
	v_mov_b32_e32 v127, v121
	v_pk_add_f32 v[128:129], v[128:129], v[134:135] neg_lo:[0,1] neg_hi:[0,1]
	v_pk_fma_f32 v[14:15], v[24:25], v[156:157], v[14:15] op_sel_hi:[0,1,1]
	v_pk_fma_f32 v[16:17], v[28:29], v[178:179], v[16:17] op_sel_hi:[0,1,1]
	v_pk_fma_f32 v[20:21], v[32:33], v[180:181], v[20:21] op_sel_hi:[0,1,1]
	v_pk_fma_f32 v[22:23], v[36:37], v[190:191], v[22:23] op_sel_hi:[0,1,1]
	v_pk_mul_f32 v[24:25], v[50:51], v[160:161] op_sel:[0,1] op_sel_hi:[1,0]
	v_pk_mul_f32 v[26:27], v[54:55], v[188:189] op_sel:[0,1] op_sel_hi:[1,0]
	v_pk_mul_f32 v[28:29], v[58:59], v[158:159] op_sel:[0,1] op_sel_hi:[1,0]
	v_pk_mul_f32 v[30:31], v[62:63], v[174:175] op_sel:[0,1] op_sel_hi:[1,0]
	v_pk_mul_f32 v[32:33], v[66:67], v[140:141] op_sel:[0,1] op_sel_hi:[1,0]
	v_pk_mul_f32 v[34:35], v[70:71], v[142:143] op_sel:[0,1] op_sel_hi:[1,0]
	v_pk_mul_f32 v[36:37], v[74:75], v[148:149] op_sel:[0,1] op_sel_hi:[1,0]
	v_pk_fma_f32 v[24:25], v[40:41], v[160:161], v[24:25] op_sel_hi:[0,1,1]
	v_pk_fma_f32 v[26:27], v[44:45], v[188:189], v[26:27] op_sel_hi:[0,1,1]
	v_pk_fma_f32 v[28:29], v[48:49], v[158:159], v[28:29] op_sel_hi:[0,1,1]
	v_pk_fma_f32 v[30:31], v[52:53], v[174:175], v[30:31] op_sel_hi:[0,1,1]
	v_pk_fma_f32 v[32:33], v[56:57], v[140:141], v[32:33] op_sel_hi:[0,1,1]
	v_pk_fma_f32 v[34:35], v[60:61], v[142:143], v[34:35] op_sel_hi:[0,1,1]
	v_pk_fma_f32 v[36:37], v[64:65], v[148:149], v[36:37] op_sel_hi:[0,1,1]
	v_pk_mul_f32 v[38:39], v[78:79], v[170:171] op_sel:[0,1] op_sel_hi:[1,0]
	v_pk_mul_f32 v[40:41], v[82:83], v[136:137] op_sel:[0,1] op_sel_hi:[1,0]
	v_pk_mul_f32 v[42:43], v[86:87], v[164:165] op_sel:[0,1] op_sel_hi:[1,0]
	v_pk_mul_f32 v[44:45], v[90:91], v[150:151] op_sel:[0,1] op_sel_hi:[1,0]
	v_pk_mul_f32 v[46:47], v[94:95], v[166:167] op_sel:[0,1] op_sel_hi:[1,0]
	v_pk_mul_f32 v[48:49], v[98:99], v[132:133] op_sel:[0,1] op_sel_hi:[1,0]
	v_pk_mul_f32 v[50:51], v[102:103], v[162:163] op_sel:[0,1] op_sel_hi:[1,0]
	v_pk_mul_f32 v[52:53], v[106:107], v[176:177] op_sel:[0,1] op_sel_hi:[1,0]
	v_pk_mul_f32 v[54:55], v[110:111], v[172:173] op_sel:[0,1] op_sel_hi:[1,0]
	v_pk_mul_f32 v[56:57], v[114:115], v[138:139] op_sel:[0,1] op_sel_hi:[1,0]
	v_pk_mul_f32 v[58:59], v[118:119], v[182:183] op_sel:[0,1] op_sel_hi:[1,0]
	v_pk_mul_f32 v[60:61], v[122:123], v[152:153] op_sel:[0,1] op_sel_hi:[1,0]
	v_pk_mul_f32 v[62:63], v[124:125], v[144:145] op_sel:[0,1] op_sel_hi:[1,0]
	v_pk_mul_f32 v[64:65], v[126:127], v[128:129] op_sel:[0,1] op_sel_hi:[1,0]
	v_pk_fma_f32 v[38:39], v[68:69], v[170:171], v[38:39] op_sel_hi:[0,1,1]
	v_pk_fma_f32 v[40:41], v[72:73], v[136:137], v[40:41] op_sel_hi:[0,1,1]
	v_pk_fma_f32 v[42:43], v[76:77], v[164:165], v[42:43] op_sel_hi:[0,1,1]
	v_pk_fma_f32 v[44:45], v[80:81], v[150:151], v[44:45] op_sel_hi:[0,1,1]
	v_pk_fma_f32 v[46:47], v[84:85], v[166:167], v[46:47] op_sel_hi:[0,1,1]
	v_pk_fma_f32 v[48:49], v[88:89], v[132:133], v[48:49] op_sel_hi:[0,1,1]
	v_pk_fma_f32 v[50:51], v[92:93], v[162:163], v[50:51] op_sel_hi:[0,1,1]
	v_pk_fma_f32 v[52:53], v[96:97], v[176:177], v[52:53] op_sel_hi:[0,1,1]
	v_pk_fma_f32 v[54:55], v[100:101], v[172:173], v[54:55] op_sel_hi:[0,1,1]
	v_pk_fma_f32 v[56:57], v[104:105], v[138:139], v[56:57] op_sel_hi:[0,1,1]
	v_pk_fma_f32 v[58:59], v[108:109], v[182:183], v[58:59] op_sel_hi:[0,1,1]
	v_pk_fma_f32 v[60:61], v[112:113], v[152:153], v[60:61] op_sel_hi:[0,1,1]
	v_pk_fma_f32 v[62:63], v[116:117], v[144:145], v[62:63] op_sel_hi:[0,1,1]
	v_pk_fma_f32 v[64:65], v[120:121], v[128:129], v[64:65] op_sel_hi:[0,1,1]
	ds_write2_b64 v18, v[130:131], v[34:35] offset1:16
	ds_write2_b64 v18, v[16:17], v[50:51] offset0:33 offset1:49
	ds_write2_b64 v18, v[8:9], v[42:43] offset0:66 offset1:82
	ds_write2_b64 v18, v[26:27], v[58:59] offset0:99 offset1:115
	ds_write2_b64 v18, v[4:5], v[38:39] offset0:132 offset1:148
	ds_write2_b64 v18, v[22:23], v[54:55] offset0:165 offset1:181
	ds_write2_b64 v18, v[12:13], v[46:47] offset0:198 offset1:214
	ds_write2_b64 v18, v[30:31], v[62:63] offset0:231 offset1:247
	ds_write2_b64 v196, v[2:3], v[36:37] offset0:8 offset1:24
	ds_write2_b64 v196, v[20:21], v[52:53] offset0:41 offset1:57
	ds_write2_b64 v196, v[10:11], v[44:45] offset0:74 offset1:90
	ds_write2_b64 v196, v[28:29], v[60:61] offset0:107 offset1:123
	ds_write2_b64 v196, v[6:7], v[40:41] offset0:140 offset1:156
	ds_write2_b64 v196, v[24:25], v[56:57] offset0:173 offset1:189
	ds_write2_b64 v196, v[14:15], v[48:49] offset0:206 offset1:222
	ds_write2_b64 v196, v[32:33], v[64:65] offset0:239 offset1:255
	v_ashrrev_i32_e32 v2, 31, v210
	v_lshrrev_b32_e32 v2, 23, v2
	v_add_u32_e32 v2, v210, v2
	s_lshl_b64 s[74:75], s[76:77], 16
	v_and_b32_e32 v2, 0xfffffe00, v2
	s_add_u32 s0, s54, s74
	v_sub_u32_e32 v2, v210, v2
	s_addc_u32 s1, s55, s75
	v_ashrrev_i32_e32 v3, 31, v2
	v_lshl_add_u64 v[14:15], v[2:3], 3, s[0:1]
	v_add_co_u32_e32 v2, vcc, s92, v14
	s_mov_b32 s0, 0x8000
	s_nop 0
	v_addc_co_u32_e32 v3, vcc, 0, v15, vcc
	v_add_co_u32_e32 v4, vcc, s95, v14
	s_waitcnt lgkmcnt(0)
	s_nop 0
	v_addc_co_u32_e32 v5, vcc, 0, v15, vcc
	v_add_co_u32_e32 v8, vcc, s96, v14
	s_barrier
	s_waitcnt vmcnt(0)
	s_nop 0
	v_addc_co_u32_e32 v9, vcc, 0, v15, vcc
	v_mov_b64_e32 v[24:25], v[220:221]
	v_mov_b64_e32 v[12:13], v[222:223]
	v_mov_b64_e32 v[6:7], v[224:225]
	s_nop 0
	v_mov_b64_e32 v[4:5], v[226:227]
	v_add_co_u32_e32 v8, vcc, s0, v14
	s_waitcnt vmcnt(3)
	v_cvt_f32_f16_sdwa v174, v24 dst_sel:DWORD dst_unused:UNUSED_PAD src0_sel:WORD_1
	v_addc_co_u32_e32 v9, vcc, 0, v15, vcc
	v_add_co_u32_e32 v10, vcc, s34, v14
	v_cvt_f32_f16_e32 v175, v25
	s_nop 0
	v_addc_co_u32_e32 v11, vcc, 0, v15, vcc
	v_mov_b64_e32 v[16:17], v[228:229]
	v_mov_b64_e32 v[122:123], v[230:231]
	v_mov_b64_e32 v[46:47], v[232:233]
	v_mov_b64_e32 v[36:37], v[234:235]
	v_add_co_u32_e32 v8, vcc, s35, v14
	v_cvt_f32_f16_sdwa v177, v25 dst_sel:DWORD dst_unused:UNUSED_PAD src0_sel:WORD_1
	s_nop 0
	v_addc_co_u32_e32 v9, vcc, 0, v15, vcc
	v_add_co_u32_e32 v22, vcc, s30, v14
	v_cvt_f32_f16_e32 v176, v24
	s_nop 0
	v_addc_co_u32_e32 v23, vcc, 0, v15, vcc
	v_mov_b64_e32 v[26:27], v[236:237]
	v_mov_b64_e32 v[20:21], v[238:239]
	v_mov_b64_e32 v[10:11], v[240:241]
	s_nop 0
	v_mov_b64_e32 v[8:9], v[242:243]
	v_add_co_u32_e32 v22, vcc, s31, v14
	s_waitcnt vmcnt(10)
	v_cvt_f32_f16_sdwa v164, v12 dst_sel:DWORD dst_unused:UNUSED_PAD src0_sel:WORD_1
	v_addc_co_u32_e32 v23, vcc, 0, v15, vcc
	v_mov_b64_e32 v[30:31], v[216:217]
	v_mov_b64_e32 v[28:29], v[218:219]
	s_nop 0
	v_mov_b64_e32 v[2:3], v[246:247]
	v_mov_b64_e32 v[32:33], v[214:215]
	v_mov_b32_e32 v14, v210
	v_cvt_f32_f16_e32 v165, v13
	v_ashrrev_i32_e32 v15, 31, v14
	v_lshrrev_b32_e32 v15, 23, v15
	v_add_u32_e32 v15, v14, v15
	v_ashrrev_i32_e32 v15, 9, v15
	v_mul_i32_i24_e32 v18, 0x200, v15
	v_sub_u32_e32 v18, v14, v18
	v_lshlrev_b32_e32 v14, 14, v15
	v_lshlrev_b32_e32 v15, 1, v18
	v_bfrev_b32_e32 v15, v15
	v_lshrrev_b32_e32 v15, 22, v15
	v_sub_u32_e32 v15, 0x400, v15
	v_bfrev_b32_e32 v15, v15
	v_lshrrev_b32_e32 v15, 18, v15
	v_and_b32_e32 v15, 0x3ff0, v15
	v_cmp_eq_u32_e64 s[0:1], 0, v18
	v_lshl_add_u32 v22, v18, 5, v14
	v_lshl_add_u32 v23, v22, 3, 0
	v_cndmask_b32_e64 v15, v15, 16, s[0:1]
	v_or_b32_e32 v14, v15, v14
	v_ashrrev_i32_e32 v22, 2, v22
	v_ashrrev_i32_e32 v15, 5, v14
	v_add_u32_e32 v211, v23, v22
	v_lshlrev_b32_e32 v14, 3, v14
	v_lshlrev_b32_e32 v15, 3, v15
	v_add3_u32 v212, 0, v14, v15
	ds_read2_b64 v[38:41], v211 offset1:1
	ds_read2_b64 v[42:45], v211 offset0:2 offset1:3
	ds_read2_b64 v[48:51], v212 offset1:1
	ds_read2_b64 v[52:55], v212 offset0:2 offset1:3
	ds_read2_b64 v[56:59], v211 offset0:4 offset1:5
	ds_read2_b64 v[60:63], v211 offset0:6 offset1:7
	ds_read2_b64 v[68:71], v212 offset0:4 offset1:5
	ds_read2_b64 v[72:75], v212 offset0:6 offset1:7
	ds_read2_b64 v[64:67], v211 offset0:8 offset1:9
	ds_read2_b64 v[76:79], v211 offset0:10 offset1:11
	ds_read2_b64 v[80:83], v212 offset0:8 offset1:9
	ds_read2_b64 v[98:101], v212 offset0:10 offset1:11
	ds_read2_b64 v[84:87], v211 offset0:12 offset1:13
	ds_read2_b64 v[88:91], v211 offset0:14 offset1:15
	ds_read2_b64 v[102:105], v212 offset0:12 offset1:13
	ds_read2_b64 v[106:109], v212 offset0:14 offset1:15
	s_waitcnt lgkmcnt(7)
	v_pk_add_f32 v[14:15], v[38:39], v[64:65]
	v_pk_add_f32 v[22:23], v[38:39], v[64:65] neg_lo:[0,1] neg_hi:[0,1]
	v_pk_add_f32 v[38:39], v[40:41], v[66:67] neg_lo:[0,1] neg_hi:[0,1]
	v_pk_add_f32 v[34:35], v[40:41], v[66:67]
	v_pk_mul_f32 v[40:41], v[38:39], s[18:19]
	v_cmp_ne_u32_e32 vcc, 0, v18
	v_pk_fma_f32 v[38:39], v[38:39], s[16:17], v[40:41] op_sel:[0,0,1] op_sel_hi:[1,0,0]
	s_waitcnt lgkmcnt(6)
	v_pk_add_f32 v[40:41], v[42:43], v[76:77]
	v_pk_add_f32 v[42:43], v[42:43], v[76:77] neg_lo:[0,1] neg_hi:[0,1]
	v_bfrev_b32_e32 v18, v18
	v_pk_mul_f32 v[64:65], v[42:43], s[36:37]
	v_lshrrev_b32_e32 v18, 23, v18
	v_pk_fma_f32 v[42:43], v[42:43], s[78:79], v[64:65] op_sel:[0,0,1] op_sel_hi:[1,0,0]
	v_pk_add_f32 v[64:65], v[44:45], v[78:79]
	v_pk_add_f32 v[44:45], v[44:45], v[78:79] neg_lo:[0,1] neg_hi:[0,1]
	s_waitcnt lgkmcnt(3)
	v_pk_add_f32 v[78:79], v[58:59], v[86:87]
	v_pk_mul_f32 v[66:67], v[44:45], s[40:41]
	v_pk_add_f32 v[58:59], v[58:59], v[86:87] neg_lo:[0,1] neg_hi:[0,1]
	v_pk_fma_f32 v[44:45], v[44:45], s[80:81], v[66:67] op_sel:[0,0,1] op_sel_hi:[1,0,0]
	v_pk_add_f32 v[66:67], v[56:57], v[84:85]
	v_pk_add_f32 v[56:57], v[56:57], v[84:85] neg_lo:[0,1] neg_hi:[0,1]
	v_pk_mul_f32 v[84:85], v[58:59], s[40:41]
	v_xor_b32_e32 v77, 0x80000000, v56
	v_pk_fma_f32 v[58:59], v[58:59], s[80:81], v[84:85] op_sel:[0,0,1] op_sel_hi:[1,0,0] neg_lo:[1,0,0] neg_hi:[1,0,0]
	s_waitcnt lgkmcnt(2)
	v_pk_add_f32 v[84:85], v[60:61], v[88:89]
	v_pk_add_f32 v[60:61], v[60:61], v[88:89] neg_lo:[0,1] neg_hi:[0,1]
	v_mov_b32_e32 v76, v57
	v_pk_mul_f32 v[86:87], v[60:61], s[36:37]
	v_pk_add_f32 v[56:57], v[22:23], v[76:77]
	v_pk_fma_f32 v[60:61], v[60:61], s[78:79], v[86:87] op_sel:[0,0,1] op_sel_hi:[1,0,0] neg_lo:[1,0,0] neg_hi:[1,0,0]
	v_pk_add_f32 v[86:87], v[62:63], v[90:91]
	v_pk_add_f32 v[62:63], v[62:63], v[90:91] neg_lo:[0,1] neg_hi:[0,1]
	v_pk_add_f32 v[90:91], v[64:65], v[86:87]
	v_pk_mul_f32 v[88:89], v[62:63], s[18:19]
	v_pk_add_f32 v[64:65], v[64:65], v[86:87] neg_lo:[0,1] neg_hi:[0,1]
	v_pk_fma_f32 v[62:63], v[62:63], s[16:17], v[88:89] op_sel:[0,0,1] op_sel_hi:[1,0,0] neg_lo:[1,0,0] neg_hi:[1,0,0]
	v_pk_add_f32 v[88:89], v[14:15], v[66:67]
	v_pk_add_f32 v[14:15], v[14:15], v[66:67] neg_lo:[0,1] neg_hi:[0,1]
	v_pk_add_f32 v[66:67], v[34:35], v[78:79]
	v_pk_add_f32 v[34:35], v[34:35], v[78:79] neg_lo:[0,1] neg_hi:[0,1]
	v_pk_add_f32 v[22:23], v[22:23], v[76:77] neg_lo:[0,1] neg_hi:[0,1]
	v_pk_mul_f32 v[78:79], v[34:35], s[36:37]
	v_pk_add_f32 v[76:77], v[38:39], v[58:59]
	v_pk_add_f32 v[38:39], v[38:39], v[58:59] neg_lo:[0,1] neg_hi:[0,1]
	v_pk_fma_f32 v[34:35], v[34:35], s[78:79], v[78:79] op_sel:[0,0,1] op_sel_hi:[1,0,0]
	v_pk_add_f32 v[78:79], v[40:41], v[84:85]
	v_pk_add_f32 v[40:41], v[40:41], v[84:85] neg_lo:[0,1] neg_hi:[0,1]
	v_pk_mul_f32 v[86:87], v[64:65], s[36:37]
	v_pk_mul_f32 v[58:59], v[38:39], s[36:37]
	v_xor_b32_e32 v85, 0x80000000, v40
	v_pk_fma_f32 v[64:65], v[64:65], s[78:79], v[86:87] op_sel:[0,0,1] op_sel_hi:[1,0,0] neg_lo:[1,0,0] neg_hi:[1,0,0]
	v_pk_fma_f32 v[38:39], v[38:39], s[78:79], v[58:59] op_sel:[0,0,1] op_sel_hi:[1,0,0]
	v_pk_add_f32 v[58:59], v[42:43], v[60:61]
	v_pk_add_f32 v[86:87], v[44:45], v[62:63]
	v_pk_add_f32 v[44:45], v[44:45], v[62:63] neg_lo:[0,1] neg_hi:[0,1]
	v_mov_b32_e32 v84, v41
	v_pk_mul_f32 v[62:63], v[44:45], s[36:37]
	v_pk_add_f32 v[40:41], v[14:15], v[84:85]
	v_pk_add_f32 v[14:15], v[14:15], v[84:85] neg_lo:[0,1] neg_hi:[0,1]
	v_pk_add_f32 v[84:85], v[34:35], v[64:65]
	v_pk_add_f32 v[34:35], v[34:35], v[64:65] neg_lo:[0,1] neg_hi:[0,1]
	v_pk_add_f32 v[94:95], v[56:57], v[58:59]
	v_pk_add_f32 v[56:57], v[56:57], v[58:59] neg_lo:[0,1] neg_hi:[0,1]
	v_pk_add_f32 v[58:59], v[76:77], v[86:87]
	v_pk_fma_f32 v[44:45], v[44:45], s[78:79], v[62:63] op_sel:[0,0,1] op_sel_hi:[1,0,0] neg_lo:[1,0,0] neg_hi:[1,0,0]
	v_pk_add_f32 v[62:63], v[88:89], v[78:79]
	v_pk_add_f32 v[78:79], v[88:89], v[78:79] neg_lo:[0,1] neg_hi:[0,1]
	v_pk_add_f32 v[88:89], v[66:67], v[90:91]
	v_xor_b32_e32 v65, 0x80000000, v34
	v_pk_add_f32 v[76:77], v[76:77], v[86:87] neg_lo:[0,1] neg_hi:[0,1]
	v_mov_b32_e32 v64, v35
	v_pk_add_f32 v[86:87], v[94:95], v[58:59]
	v_pk_add_f32 v[34:35], v[94:95], v[58:59] neg_lo:[0,1] neg_hi:[0,1]
	v_pk_add_f32 v[58:59], v[50:51], v[82:83]
	v_pk_add_f32 v[50:51], v[50:51], v[82:83] neg_lo:[0,1] neg_hi:[0,1]
	v_pk_add_f32 v[42:43], v[42:43], v[60:61] neg_lo:[0,1] neg_hi:[0,1]
	v_pk_add_f32 v[148:149], v[62:63], v[88:89]
	v_pk_add_f32 v[138:139], v[62:63], v[88:89] neg_lo:[0,1] neg_hi:[0,1]
	v_pk_mul_f32 v[62:63], v[50:51], s[18:19]
	v_xor_b32_e32 v61, 0x80000000, v42
	v_pk_add_f32 v[66:67], v[66:67], v[90:91] neg_lo:[0,1] neg_hi:[0,1]
	v_mov_b32_e32 v60, v43
	v_pk_fma_f32 v[50:51], v[50:51], s[16:17], v[62:63] op_sel:[0,0,1] op_sel_hi:[1,0,0]
	v_pk_add_f32 v[62:63], v[52:53], v[98:99]
	v_pk_add_f32 v[52:53], v[52:53], v[98:99] neg_lo:[0,1] neg_hi:[0,1]
	v_xor_b32_e32 v91, 0x80000000, v66
	v_pk_add_f32 v[112:113], v[22:23], v[60:61]
	v_pk_add_f32 v[114:115], v[22:23], v[60:61] neg_lo:[0,1] neg_hi:[0,1]
	v_mov_b32_e32 v90, v67
	v_pk_add_f32 v[96:97], v[40:41], v[84:85]
	v_pk_add_f32 v[66:67], v[40:41], v[84:85] neg_lo:[0,1] neg_hi:[0,1]
	v_pk_add_f32 v[60:61], v[14:15], v[64:65]
	v_pk_add_f32 v[84:85], v[14:15], v[64:65] neg_lo:[0,1] neg_hi:[0,1]
	v_pk_mul_f32 v[64:65], v[52:53], s[36:37]
	v_xor_b32_e32 v111, 0x80000000, v76
	v_pk_fma_f32 v[52:53], v[52:53], s[78:79], v[64:65] op_sel:[0,0,1] op_sel_hi:[1,0,0]
	v_pk_add_f32 v[64:65], v[54:55], v[100:101]
	v_pk_add_f32 v[54:55], v[54:55], v[100:101] neg_lo:[0,1] neg_hi:[0,1]
	v_mov_b32_e32 v110, v77
	v_pk_mul_f32 v[76:77], v[54:55], s[40:41]
	v_pk_add_f32 v[92:93], v[78:79], v[90:91]
	v_pk_fma_f32 v[54:55], v[54:55], s[80:81], v[76:77] op_sel:[0,0,1] op_sel_hi:[1,0,0]
	s_waitcnt lgkmcnt(1)
	v_pk_add_f32 v[76:77], v[68:69], v[102:103]
	v_pk_add_f32 v[68:69], v[68:69], v[102:103] neg_lo:[0,1] neg_hi:[0,1]
	v_pk_add_f32 v[88:89], v[78:79], v[90:91] neg_lo:[0,1] neg_hi:[0,1]
	v_xor_b32_e32 v79, 0x80000000, v68
	v_mov_b32_e32 v78, v69
	v_pk_add_f32 v[68:69], v[70:71], v[104:105]
	v_pk_add_f32 v[70:71], v[70:71], v[104:105] neg_lo:[0,1] neg_hi:[0,1]
	v_pk_add_f32 v[22:23], v[38:39], v[44:45]
	v_pk_add_f32 v[38:39], v[38:39], v[44:45] neg_lo:[0,1] neg_hi:[0,1]
	v_pk_add_f32 v[40:41], v[56:57], v[110:111]
	v_pk_add_f32 v[44:45], v[56:57], v[110:111] neg_lo:[0,1] neg_hi:[0,1]
	v_pk_add_f32 v[56:57], v[48:49], v[80:81]
	v_pk_add_f32 v[48:49], v[48:49], v[80:81] neg_lo:[0,1] neg_hi:[0,1]
	v_pk_mul_f32 v[80:81], v[70:71], s[40:41]
	v_cvt_f32_u32_e32 v18, v18
	v_pk_fma_f32 v[70:71], v[70:71], s[80:81], v[80:81] op_sel:[0,0,1] op_sel_hi:[1,0,0] neg_lo:[1,0,0] neg_hi:[1,0,0]
	s_waitcnt lgkmcnt(0)
	v_pk_add_f32 v[80:81], v[72:73], v[106:107]
	v_pk_add_f32 v[72:73], v[72:73], v[106:107] neg_lo:[0,1] neg_hi:[0,1]
	v_mul_f32_e32 v18, 0x38000000, v18
	v_pk_mul_f32 v[82:83], v[72:73], s[36:37]
	v_cndmask_b32_e64 v18, v18, v208, s[0:1]
	v_pk_fma_f32 v[72:73], v[72:73], s[78:79], v[82:83] op_sel:[0,0,1] op_sel_hi:[1,0,0] neg_lo:[1,0,0] neg_hi:[1,0,0]
	v_pk_add_f32 v[82:83], v[74:75], v[108:109]
	v_pk_add_f32 v[74:75], v[74:75], v[108:109] neg_lo:[0,1] neg_hi:[0,1]
	v_xor_b32_e32 v117, 0x80000000, v38
	v_pk_mul_f32 v[90:91], v[74:75], s[18:19]
	v_mov_b32_e32 v116, v39
	v_pk_fma_f32 v[74:75], v[74:75], s[16:17], v[90:91] op_sel:[0,0,1] op_sel_hi:[1,0,0] neg_lo:[1,0,0] neg_hi:[1,0,0]
	v_pk_add_f32 v[90:91], v[56:57], v[76:77]
	v_pk_add_f32 v[56:57], v[56:57], v[76:77] neg_lo:[0,1] neg_hi:[0,1]
	v_pk_add_f32 v[76:77], v[58:59], v[68:69]
	v_pk_add_f32 v[58:59], v[58:59], v[68:69] neg_lo:[0,1] neg_hi:[0,1]
	v_pk_add_f32 v[14:15], v[114:115], v[116:117]
	v_pk_mul_f32 v[68:69], v[58:59], s[36:37]
	v_pk_add_f32 v[38:39], v[114:115], v[116:117] neg_lo:[0,1] neg_hi:[0,1]
	v_pk_fma_f32 v[58:59], v[58:59], s[78:79], v[68:69] op_sel:[0,0,1] op_sel_hi:[1,0,0]
	v_pk_add_f32 v[68:69], v[62:63], v[80:81]
	v_pk_add_f32 v[62:63], v[62:63], v[80:81] neg_lo:[0,1] neg_hi:[0,1]
	s_waitcnt vmcnt(0)
	v_cvt_f32_f16_e32 v193, v33
	v_xor_b32_e32 v81, 0x80000000, v62
	v_mov_b32_e32 v80, v63
	v_pk_add_f32 v[62:63], v[64:65], v[82:83]
	v_pk_add_f32 v[64:65], v[64:65], v[82:83] neg_lo:[0,1] neg_hi:[0,1]
	v_cvt_f32_f16_sdwa v192, v32 dst_sel:DWORD dst_unused:UNUSED_PAD src0_sel:WORD_1
	v_pk_mul_f32 v[82:83], v[64:65], s[36:37]
	v_cvt_f32_f16_e32 v194, v32
	v_pk_fma_f32 v[64:65], v[64:65], s[78:79], v[82:83] op_sel:[0,0,1] op_sel_hi:[1,0,0] neg_lo:[1,0,0] neg_hi:[1,0,0]
	v_pk_add_f32 v[82:83], v[48:49], v[78:79]
	v_pk_add_f32 v[48:49], v[48:49], v[78:79] neg_lo:[0,1] neg_hi:[0,1]
	v_pk_add_f32 v[78:79], v[50:51], v[70:71]
	v_pk_add_f32 v[50:51], v[50:51], v[70:71] neg_lo:[0,1] neg_hi:[0,1]
	v_cvt_f32_f16_sdwa v195, v33 dst_sel:DWORD dst_unused:UNUSED_PAD src0_sel:WORD_1
	v_pk_mul_f32 v[70:71], v[50:51], s[36:37]
	v_cvt_f32_f16_sdwa v170, v30 dst_sel:DWORD dst_unused:UNUSED_PAD src0_sel:WORD_1
	v_pk_fma_f32 v[50:51], v[50:51], s[78:79], v[70:71] op_sel:[0,0,1] op_sel_hi:[1,0,0]
	v_pk_add_f32 v[70:71], v[52:53], v[72:73]
	v_pk_add_f32 v[52:53], v[52:53], v[72:73] neg_lo:[0,1] neg_hi:[0,1]
	v_cvt_f32_f16_e32 v171, v31
	v_xor_b32_e32 v73, 0x80000000, v52
	v_mov_b32_e32 v72, v53
	v_pk_add_f32 v[52:53], v[54:55], v[74:75]
	v_pk_add_f32 v[54:55], v[54:55], v[74:75] neg_lo:[0,1] neg_hi:[0,1]
	v_cvt_f32_f16_sdwa v185, v31 dst_sel:DWORD dst_unused:UNUSED_PAD src0_sel:WORD_1
	v_pk_mul_f32 v[74:75], v[54:55], s[36:37]
	v_cvt_f32_f16_e32 v184, v30
	v_pk_fma_f32 v[54:55], v[54:55], s[78:79], v[74:75] op_sel:[0,0,1] op_sel_hi:[1,0,0] neg_lo:[1,0,0] neg_hi:[1,0,0]
	v_pk_add_f32 v[74:75], v[90:91], v[68:69]
	v_pk_add_f32 v[68:69], v[90:91], v[68:69] neg_lo:[0,1] neg_hi:[0,1]
	v_pk_add_f32 v[90:91], v[76:77], v[62:63]
	v_pk_add_f32 v[62:63], v[76:77], v[62:63] neg_lo:[0,1] neg_hi:[0,1]
	v_cvt_f32_f16_sdwa v172, v28 dst_sel:DWORD dst_unused:UNUSED_PAD src0_sel:WORD_1
	v_xor_b32_e32 v77, 0x80000000, v62
	v_mov_b32_e32 v76, v63
	v_pk_add_f32 v[62:63], v[56:57], v[80:81]
	v_pk_add_f32 v[56:57], v[56:57], v[80:81] neg_lo:[0,1] neg_hi:[0,1]
	v_pk_add_f32 v[80:81], v[58:59], v[64:65]
	v_pk_add_f32 v[58:59], v[58:59], v[64:65] neg_lo:[0,1] neg_hi:[0,1]
	v_cvt_f32_f16_e32 v173, v29
	v_xor_b32_e32 v65, 0x80000000, v58
	v_mov_b32_e32 v64, v59
	v_pk_add_f32 v[58:59], v[82:83], v[70:71]
	v_pk_add_f32 v[70:71], v[82:83], v[70:71] neg_lo:[0,1] neg_hi:[0,1]
	v_pk_add_f32 v[82:83], v[78:79], v[52:53]
	v_pk_add_f32 v[52:53], v[78:79], v[52:53] neg_lo:[0,1] neg_hi:[0,1]
	v_pk_add_f32 v[118:119], v[58:59], v[82:83]
	v_pk_add_f32 v[134:135], v[58:59], v[82:83] neg_lo:[0,1] neg_hi:[0,1]
	v_cos_f32_e32 v83, v18
	v_sin_f32_e32 v82, v18
	v_cvt_f32_f16_sdwa v181, v29 dst_sel:DWORD dst_unused:UNUSED_PAD src0_sel:WORD_1
	v_cvt_f32_f16_e32 v180, v28
	v_cvt_f32_f16_sdwa v167, v13 dst_sel:DWORD dst_unused:UNUSED_PAD src0_sel:WORD_1
	v_cvt_f32_f16_e32 v166, v12
	v_cvt_f32_f16_e32 v154, v6
	v_cvt_f32_f16_e32 v155, v7
	v_cvt_f32_f16_sdwa v157, v7 dst_sel:DWORD dst_unused:UNUSED_PAD src0_sel:WORD_1
	v_cvt_f32_f16_sdwa v156, v6 dst_sel:DWORD dst_unused:UNUSED_PAD src0_sel:WORD_1
	v_cvt_f32_f16_sdwa v140, v4 dst_sel:DWORD dst_unused:UNUSED_PAD src0_sel:WORD_1
	v_cvt_f32_f16_e32 v141, v5
	v_cvt_f32_f16_sdwa v143, v5 dst_sel:DWORD dst_unused:UNUSED_PAD src0_sel:WORD_1
	v_cvt_f32_f16_e32 v142, v4
	v_cvt_f32_f16_e32 v124, v16
	v_cvt_f32_f16_e32 v125, v17
	v_cvt_f32_f16_sdwa v127, v17 dst_sel:DWORD dst_unused:UNUSED_PAD src0_sel:WORD_1
	v_cvt_f32_f16_sdwa v126, v16 dst_sel:DWORD dst_unused:UNUSED_PAD src0_sel:WORD_1
	v_cvt_f32_f16_sdwa v114, v122 dst_sel:DWORD dst_unused:UNUSED_PAD src0_sel:WORD_1
	v_cvt_f32_f16_e32 v115, v123
	v_cvt_f32_f16_sdwa v117, v123 dst_sel:DWORD dst_unused:UNUSED_PAD src0_sel:WORD_1
	v_cvt_f32_f16_e32 v116, v122
	v_xor_b32_e32 v79, 0x80000000, v52
	v_mov_b32_e32 v78, v53
	v_pk_add_f32 v[52:53], v[48:49], v[72:73]
	v_pk_add_f32 v[48:49], v[48:49], v[72:73] neg_lo:[0,1] neg_hi:[0,1]
	v_pk_add_f32 v[72:73], v[50:51], v[54:55]
	v_pk_add_f32 v[50:51], v[50:51], v[54:55] neg_lo:[0,1] neg_hi:[0,1]
	v_pk_fma_f32 v[160:161], v[82:83], 0, v[82:83] op_sel:[0,0,1] op_sel_hi:[1,0,0] neg_lo:[1,0,0] neg_hi:[1,0,0]
	v_xor_b32_e32 v55, 0x80000000, v50
	v_mov_b32_e32 v54, v51
	v_pk_fma_f32 v[198:199], v[82:83], 0, v[82:83] op_sel:[0,0,1] op_sel_hi:[1,0,0]
	v_pk_add_f32 v[42:43], v[112:113], v[22:23]
	v_pk_add_f32 v[22:23], v[112:113], v[22:23] neg_lo:[0,1] neg_hi:[0,1]
	v_pk_add_f32 v[98:99], v[74:75], v[90:91]
	v_pk_add_f32 v[100:101], v[74:75], v[90:91] neg_lo:[0,1] neg_hi:[0,1]
	v_pk_add_f32 v[102:103], v[68:69], v[76:77]
	v_pk_add_f32 v[106:107], v[68:69], v[76:77] neg_lo:[0,1] neg_hi:[0,1]
	v_pk_add_f32 v[104:105], v[62:63], v[80:81]
	v_pk_add_f32 v[108:109], v[62:63], v[80:81] neg_lo:[0,1] neg_hi:[0,1]
	v_pk_add_f32 v[110:111], v[56:57], v[64:65]
	v_pk_add_f32 v[112:113], v[56:57], v[64:65] neg_lo:[0,1] neg_hi:[0,1]
	v_pk_add_f32 v[152:153], v[70:71], v[78:79]
	v_pk_add_f32 v[162:163], v[70:71], v[78:79] neg_lo:[0,1] neg_hi:[0,1]
	v_pk_add_f32 v[178:179], v[52:53], v[72:73]
	v_pk_add_f32 v[182:183], v[52:53], v[72:73] neg_lo:[0,1] neg_hi:[0,1]
	v_pk_add_f32 v[188:189], v[48:49], v[54:55]
	v_pk_add_f32 v[196:197], v[48:49], v[54:55] neg_lo:[0,1] neg_hi:[0,1]
	v_pk_mul_f32 v[186:187], v[82:83], 0 op_sel_hi:[1,0]
	v_mov_b32_e32 v190, v160
	v_mov_b32_e32 v191, v199
	v_mul_f32_e32 v18, 0x3f3504f3, v83
	v_mul_f32_e32 v158, 0xbec3ef15, v83
	v_mul_f32_e32 v132, 0xbf6c835e, v83
	s_and_saveexec_b64 s[0:1], vcc
	s_xor_b64 s[0:1], exec, s[0:1]
	s_cbranch_execz .LBB0_501
	v_pk_add_f32 v[4:5], v[148:149], v[196:197]
	v_pk_add_f32 v[6:7], v[148:149], v[196:197] neg_lo:[0,1] neg_hi:[0,1]
	v_mul_f32_e32 v4, 0.5, v4
	v_mul_f32_e32 v12, 0.5, v7
	v_mov_b32_e32 v7, v5
	v_pk_mul_f32 v[6:7], v[6:7], s[44:45]
	v_pk_mov_b32 v[16:17], v[198:199], v[160:161] op_sel:[1,0]
	v_pk_mul_f32 v[24:25], v[190:191], v[6:7] op_sel:[0,1] op_sel_hi:[1,0]
	v_pk_mul_f32 v[6:7], v[190:191], v[6:7]
	v_pk_add_f32 v[24:25], v[24:25], v[24:25] op_sel:[0,1] op_sel_hi:[0,1]
	v_pk_add_f32 v[28:29], v[4:5], v[24:25]
	v_pk_add_f32 v[4:5], v[4:5], v[24:25] op_sel_hi:[0,1] neg_lo:[0,1] neg_hi:[0,1]
	v_mov_b32_e32 v29, v5
	v_pk_add_f32 v[4:5], v[6:7], v[6:7] op_sel:[0,1] op_sel_hi:[0,1] neg_lo:[0,1] neg_hi:[0,1]
	v_pk_add_f32 v[6:7], v[12:13], v[4:5]
	v_pk_add_f32 v[4:5], v[12:13], v[4:5] op_sel_hi:[0,1] neg_lo:[0,1] neg_hi:[0,1]
	v_mov_b32_e32 v7, v5
	v_pk_mul_f32 v[4:5], v[6:7], v[194:195]
	v_pk_mul_f32 v[6:7], v[6:7], v[192:193]
	v_pk_fma_f32 v[4:5], v[28:29], v[192:193], v[4:5]
	v_pk_fma_f32 v[6:7], v[28:29], v[194:195], v[6:7] neg_lo:[0,0,1] neg_hi:[0,0,1]
	s_mov_b32 s78, s19
	v_pk_add_f32 v[12:13], v[6:7], v[4:5] op_sel:[0,1] op_sel_hi:[1,0] neg_lo:[0,1] neg_hi:[0,1]
	v_pk_add_f32 v[28:29], v[6:7], v[4:5] op_sel:[0,1] op_sel_hi:[1,0]
	v_pk_add_f32 v[4:5], v[4:5], v[6:7] op_sel:[1,0] op_sel_hi:[0,1] neg_lo:[0,1] neg_hi:[0,1]
	v_mov_b32_e32 v13, v29
	v_pk_mul_f32 v[12:13], v[12:13], 0.5 op_sel_hi:[1,0]
	v_mov_b32_e32 v29, v5
	v_mul_f32_e32 v24, v190, v12
	v_pk_fma_f32 v[30:31], v[190:191], v[12:13], v[24:25] op_sel_hi:[1,1,0] neg_lo:[1,0,0] neg_hi:[1,0,0]
	v_mul_f32_e32 v24, v160, v13
	v_pk_fma_f32 v[12:13], v[16:17], v[12:13], v[24:25] op_sel_hi:[1,1,0]
	v_mov_b32_e32 v16, v83
	v_mov_b32_e32 v30, v12
	v_pk_fma_f32 v[4:5], v[28:29], 0.5, v[12:13] op_sel_hi:[1,0,1] neg_lo:[0,0,1] neg_hi:[0,0,1]
	v_pk_fma_f32 v[122:123], v[28:29], 0.5, v[30:31] op_sel_hi:[1,0,1]
	v_pk_fma_f32 v[6:7], v[28:29], 0.5, v[30:31] op_sel_hi:[1,0,1] neg_lo:[1,0,0] neg_hi:[1,0,0]
	v_mov_b32_e32 v5, v123
	v_pk_mul_f32 v[24:25], v[4:5], s[6:7] op_sel_hi:[1,0]
	v_pk_add_f32 v[4:5], v[138:139], v[188:189]
	v_pk_add_f32 v[12:13], v[138:139], v[188:189] neg_lo:[0,1] neg_hi:[0,1]
	v_mov_b32_e32 v17, v82
	v_mul_f32_e32 v6, 0.5, v13
	v_pk_add_f32 v[28:29], v[186:187], v[16:17] neg_lo:[0,1] neg_hi:[0,1]
	v_pk_add_f32 v[30:31], v[186:187], v[16:17]
	v_mov_b32_e32 v13, v5
	v_pk_mov_b32 v[32:33], v[28:29], v[30:31] op_sel:[1,0]
	v_pk_mul_f32 v[12:13], v[12:13], s[44:45]
	v_mul_f32_e32 v4, 0.5, v4
	v_pk_mul_f32 v[48:49], v[32:33], v[12:13] op_sel:[0,1] op_sel_hi:[1,0]
	v_pk_mul_f32 v[12:13], v[32:33], v[12:13]
	v_pk_add_f32 v[48:49], v[48:49], v[48:49] op_sel:[0,1] op_sel_hi:[0,1]
	v_pk_add_f32 v[50:51], v[4:5], v[48:49]
	v_pk_add_f32 v[4:5], v[4:5], v[48:49] op_sel_hi:[0,1] neg_lo:[0,1] neg_hi:[0,1]
	v_mov_b32_e32 v51, v5
	v_pk_add_f32 v[4:5], v[12:13], v[12:13] op_sel:[0,1] op_sel_hi:[0,1] neg_lo:[0,1] neg_hi:[0,1]
	v_pk_add_f32 v[12:13], v[6:7], v[4:5]
	v_pk_add_f32 v[4:5], v[6:7], v[4:5] op_sel_hi:[0,1] neg_lo:[0,1] neg_hi:[0,1]
	v_mov_b32_e32 v13, v5
	v_pk_mul_f32 v[4:5], v[12:13], v[184:185]
	v_pk_mul_f32 v[12:13], v[12:13], v[170:171]
	v_pk_fma_f32 v[4:5], v[50:51], v[170:171], v[4:5]
	v_pk_fma_f32 v[12:13], v[50:51], v[184:185], v[12:13] neg_lo:[0,0,1] neg_hi:[0,0,1]
	v_mov_b32_e32 v31, v29
	v_pk_add_f32 v[48:49], v[12:13], v[4:5] op_sel:[0,1] op_sel_hi:[1,0] neg_lo:[0,1] neg_hi:[0,1]
	v_pk_add_f32 v[50:51], v[12:13], v[4:5] op_sel:[0,1] op_sel_hi:[1,0]
	v_pk_add_f32 v[4:5], v[4:5], v[12:13] op_sel:[1,0] op_sel_hi:[0,1] neg_lo:[0,1] neg_hi:[0,1]
	v_mov_b32_e32 v49, v51
	v_pk_mul_f32 v[48:49], v[48:49], 0.5 op_sel_hi:[1,0]
	v_mov_b32_e32 v51, v5
	v_mul_f32_e32 v6, v29, v48
	v_pk_fma_f32 v[32:33], v[32:33], v[48:49], v[6:7] op_sel_hi:[1,1,0] neg_lo:[1,0,0] neg_hi:[1,0,0]
	v_mul_f32_e32 v6, v29, v49
	v_pk_fma_f32 v[28:29], v[30:31], v[48:49], v[6:7] op_sel_hi:[1,1,0]
	v_pk_mul_f32 v[12:13], v[16:17], s[36:37]
	v_mov_b32_e32 v32, v28
	v_pk_fma_f32 v[4:5], v[50:51], 0.5, v[28:29] op_sel_hi:[1,0,1] neg_lo:[0,0,1] neg_hi:[0,0,1]
	v_pk_fma_f32 v[138:139], v[50:51], 0.5, v[32:33] op_sel_hi:[1,0,1]
	v_pk_add_f32 v[16:17], v[92:93], v[182:183]
	v_mov_b32_e32 v5, v139
	v_pk_add_f32 v[28:29], v[92:93], v[182:183] neg_lo:[0,1] neg_hi:[0,1]
	v_pk_mul_f32 v[30:31], v[4:5], s[6:7] op_sel_hi:[1,0]
	v_pk_fma_f32 v[4:5], v[50:51], 0.5, v[32:33] op_sel_hi:[1,0,1] neg_lo:[1,0,0] neg_hi:[1,0,0]
	v_mul_f32_e32 v6, 0.5, v29
	v_pk_add_f32 v[32:33], v[18:19], v[12:13] op_sel:[0,1] op_sel_hi:[0,1] neg_lo:[0,1] neg_hi:[0,1]
	v_pk_add_f32 v[48:49], v[18:19], v[12:13] op_sel:[0,1] op_sel_hi:[0,1]
	v_mov_b32_e32 v29, v17
	v_mul_f32_e32 v4, 0.5, v16
	v_mov_b32_e32 v50, v32
	v_mov_b32_e32 v51, v49
	v_pk_mul_f32 v[16:17], v[28:29], s[44:45]
	v_pk_mov_b32 v[48:49], v[48:49], v[32:33] op_sel:[1,0]
	v_pk_mul_f32 v[28:29], v[50:51], v[16:17] op_sel:[0,1] op_sel_hi:[1,0]
	v_pk_mul_f32 v[16:17], v[50:51], v[16:17]
	v_pk_add_f32 v[28:29], v[28:29], v[28:29] op_sel:[0,1] op_sel_hi:[0,1]
	v_pk_add_f32 v[52:53], v[4:5], v[28:29]
	v_pk_add_f32 v[28:29], v[4:5], v[28:29] op_sel_hi:[0,1] neg_lo:[0,1] neg_hi:[0,1]
	v_pk_add_f32 v[16:17], v[16:17], v[16:17] op_sel:[0,1] op_sel_hi:[0,1] neg_lo:[0,1] neg_hi:[0,1]
	v_mov_b32_e32 v53, v29
	v_pk_add_f32 v[28:29], v[6:7], v[16:17]
	v_pk_add_f32 v[16:17], v[6:7], v[16:17] op_sel_hi:[0,1] neg_lo:[0,1] neg_hi:[0,1]
	v_mov_b32_e32 v29, v17
	v_pk_mul_f32 v[16:17], v[28:29], v[180:181]
	v_pk_mul_f32 v[28:29], v[28:29], v[172:173]
	v_pk_fma_f32 v[16:17], v[52:53], v[172:173], v[16:17]
	v_pk_fma_f32 v[28:29], v[52:53], v[180:181], v[28:29] neg_lo:[0,0,1] neg_hi:[0,0,1]
	v_sub_f32_e32 v6, v89, v179
	v_pk_add_f32 v[52:53], v[28:29], v[16:17] op_sel:[0,1] op_sel_hi:[1,0] neg_lo:[0,1] neg_hi:[0,1]
	v_pk_add_f32 v[54:55], v[28:29], v[16:17] op_sel:[0,1] op_sel_hi:[1,0]
	v_pk_add_f32 v[16:17], v[16:17], v[28:29] op_sel:[1,0] op_sel_hi:[0,1] neg_lo:[0,1] neg_hi:[0,1]
	v_mov_b32_e32 v53, v55
	v_pk_mul_f32 v[52:53], v[52:53], 0.5 op_sel_hi:[1,0]
	v_mov_b32_e32 v55, v17
	v_mul_f32_e32 v4, v32, v52
	v_pk_fma_f32 v[56:57], v[50:51], v[52:53], v[4:5] op_sel_hi:[1,1,0] neg_lo:[1,0,0] neg_hi:[1,0,0]
	v_mul_f32_e32 v4, v32, v53
	v_pk_fma_f32 v[48:49], v[48:49], v[52:53], v[4:5] op_sel_hi:[1,1,0]
	v_pk_add_f32 v[28:29], v[88:89], v[178:179]
	v_mov_b32_e32 v56, v48
	v_pk_fma_f32 v[16:17], v[54:55], 0.5, v[48:49] op_sel_hi:[1,0,1] neg_lo:[0,0,1] neg_hi:[0,0,1]
	v_mov_b32_e32 v48, v12
	v_mov_b32_e32 v49, v88
	v_pk_mov_b32 v[12:13], v[12:13], v[178:179] op_sel:[1,0]
	v_mul_f32_e32 v18, 0.5, v29
	v_pk_add_f32 v[12:13], v[48:49], v[12:13] neg_lo:[0,1] neg_hi:[0,1]
	v_mul_f32_e32 v4, 0.5, v28
	v_pk_mul_f32 v[48:49], v[12:13], v[18:19]
	v_mov_b32_e32 v13, v32
	v_pk_fma_f32 v[50:51], v[50:51], v[48:49], v[48:49] op_sel:[0,1,0] op_sel_hi:[1,0,1]
	v_mov_b32_e32 v48, v49
	v_mov_b32_e32 v49, v18
	v_pk_mul_f32 v[48:49], v[12:13], v[48:49]
	v_pk_add_f32 v[52:53], v[4:5], v[50:51]
	v_mul_f32_e32 v6, 0.5, v6
	v_fma_f32 v53, v28, 0.5, -v50
	v_pk_add_f32 v[28:29], v[48:49], v[48:49] op_sel:[0,1] op_sel_hi:[0,1] neg_lo:[0,1] neg_hi:[0,1]
	v_pk_add_f32 v[48:49], v[6:7], v[28:29]
	v_pk_add_f32 v[28:29], v[6:7], v[28:29] op_sel_hi:[0,1] neg_lo:[0,1] neg_hi:[0,1]
	v_mov_b32_e32 v49, v29
	v_pk_mul_f32 v[28:29], v[48:49], v[176:177]
	v_pk_mul_f32 v[48:49], v[48:49], v[174:175]
	v_pk_fma_f32 v[28:29], v[52:53], v[174:175], v[28:29]
	v_pk_fma_f32 v[48:49], v[52:53], v[176:177], v[48:49] neg_lo:[0,0,1] neg_hi:[0,0,1]
	v_pk_fma_f32 v[92:93], v[54:55], 0.5, v[56:57] op_sel_hi:[1,0,1]
	v_pk_add_f32 v[50:51], v[48:49], v[28:29] op_sel:[0,1] op_sel_hi:[1,0] neg_lo:[0,1] neg_hi:[0,1]
	v_pk_add_f32 v[52:53], v[48:49], v[28:29] op_sel:[0,1] op_sel_hi:[1,0]
	v_mov_b32_e32 v17, v93
	v_mov_b32_e32 v51, v53
	v_pk_mul_f32 v[50:51], v[50:51], 0.5 op_sel_hi:[1,0]
	v_pk_mul_f32 v[64:65], v[16:17], s[6:7] op_sel_hi:[1,0]
	v_mul_f32_e32 v4, v12, v50
	v_pk_fma_f32 v[16:17], v[54:55], 0.5, v[56:57] op_sel_hi:[1,0,1] neg_lo:[1,0,0] neg_hi:[1,0,0]
	v_pk_fma_f32 v[54:55], v[12:13], v[50:51], v[4:5] op_sel_hi:[1,1,0] neg_lo:[1,0,0] neg_hi:[1,0,0]
	v_mov_b32_e32 v33, v12
	v_mul_f32_e32 v4, v12, v51
	v_pk_fma_f32 v[12:13], v[32:33], v[50:51], v[4:5] op_sel_hi:[1,1,0]
	v_pk_add_f32 v[28:29], v[28:29], v[48:49] op_sel:[1,0] op_sel_hi:[0,1] neg_lo:[0,1] neg_hi:[0,1]
	v_mov_b32_e32 v53, v29
	v_mov_b32_e32 v54, v12
	v_pk_fma_f32 v[12:13], v[52:53], 0.5, v[12:13] op_sel_hi:[1,0,1] neg_lo:[0,0,1] neg_hi:[0,0,1]
	v_pk_fma_f32 v[88:89], v[52:53], 0.5, v[54:55] op_sel_hi:[1,0,1]
	s_mov_b32 s79, s16
	v_mov_b32_e32 v13, v89
	v_pk_mul_f32 v[68:69], v[12:13], s[6:7] op_sel_hi:[1,0]
	v_pk_fma_f32 v[12:13], v[52:53], 0.5, v[54:55] op_sel_hi:[1,0,1] neg_lo:[1,0,0] neg_hi:[1,0,0]
	v_mov_b32_e32 v4, v83
	s_mov_b32 s17, s19
	v_pk_mul_f32 v[48:49], v[82:83], s[78:79] op_sel_hi:[0,1]
	v_pk_add_f32 v[28:29], v[96:97], v[162:163]
	v_pk_add_f32 v[32:33], v[96:97], v[162:163] neg_lo:[0,1] neg_hi:[0,1]
	v_pk_fma_f32 v[52:53], v[4:5], s[16:17], v[48:49] op_sel_hi:[0,1,1] neg_lo:[0,0,1] neg_hi:[0,0,1]
	v_mul_f32_e32 v12, 0.5, v33
	v_pk_fma_f32 v[50:51], v[4:5], s[16:17], v[48:49] op_sel_hi:[0,1,1]
	v_mov_b32_e32 v33, v29
	v_mul_f32_e32 v6, 0.5, v28
	v_mov_b32_e32 v54, v52
	v_mov_b32_e32 v55, v51
	v_pk_mul_f32 v[28:29], v[32:33], s[44:45]
	v_pk_mov_b32 v[56:57], v[50:51], v[52:53] op_sel:[1,0]
	v_pk_mul_f32 v[32:33], v[54:55], v[28:29] op_sel:[0,1] op_sel_hi:[1,0]
	v_pk_mul_f32 v[28:29], v[54:55], v[28:29]
	v_pk_add_f32 v[32:33], v[32:33], v[32:33] op_sel:[0,1] op_sel_hi:[0,1]
	v_pk_add_f32 v[58:59], v[6:7], v[32:33]
	v_pk_add_f32 v[32:33], v[6:7], v[32:33] op_sel_hi:[0,1] neg_lo:[0,1] neg_hi:[0,1]
	v_pk_add_f32 v[28:29], v[28:29], v[28:29] op_sel:[0,1] op_sel_hi:[0,1] neg_lo:[0,1] neg_hi:[0,1]
	v_mov_b32_e32 v59, v33
	v_pk_add_f32 v[32:33], v[12:13], v[28:29]
	v_pk_add_f32 v[28:29], v[12:13], v[28:29] op_sel_hi:[0,1] neg_lo:[0,1] neg_hi:[0,1]
	v_mov_b32_e32 v33, v29
	v_pk_mul_f32 v[28:29], v[32:33], v[166:167]
	v_pk_mul_f32 v[32:33], v[32:33], v[164:165]
	v_pk_fma_f32 v[28:29], v[58:59], v[164:165], v[28:29]
	v_pk_fma_f32 v[32:33], v[58:59], v[166:167], v[32:33] neg_lo:[0,0,1] neg_hi:[0,0,1]
	v_mov_b32_e32 v159, v66
	v_pk_add_f32 v[58:59], v[32:33], v[28:29] op_sel:[0,1] op_sel_hi:[1,0] neg_lo:[0,1] neg_hi:[0,1]
	v_pk_add_f32 v[70:71], v[32:33], v[28:29] op_sel:[0,1] op_sel_hi:[1,0]
	v_pk_add_f32 v[28:29], v[28:29], v[32:33] op_sel:[1,0] op_sel_hi:[0,1] neg_lo:[0,1] neg_hi:[0,1]
	v_mov_b32_e32 v59, v71
	v_pk_mul_f32 v[58:59], v[58:59], 0.5 op_sel_hi:[1,0]
	v_mov_b32_e32 v71, v29
	v_mul_f32_e32 v6, v52, v58
	v_pk_fma_f32 v[72:73], v[54:55], v[58:59], v[6:7] op_sel_hi:[1,1,0] neg_lo:[1,0,0] neg_hi:[1,0,0]
	v_mul_f32_e32 v6, v52, v59
	v_pk_fma_f32 v[56:57], v[56:57], v[58:59], v[6:7] op_sel_hi:[1,1,0]
	v_sub_f32_e32 v12, v67, v153
	v_mov_b32_e32 v72, v56
	v_pk_fma_f32 v[28:29], v[70:71], 0.5, v[56:57] op_sel_hi:[1,0,1] neg_lo:[0,0,1] neg_hi:[0,0,1]
	v_pk_fma_f32 v[96:97], v[70:71], 0.5, v[72:73] op_sel_hi:[1,0,1]
	v_pk_mov_b32 v[56:57], v[48:49], v[152:153] op_sel:[1,0]
	v_mov_b32_e32 v29, v97
	v_pk_mul_f32 v[62:63], v[28:29], s[6:7] op_sel_hi:[1,0]
	v_pk_add_f32 v[28:29], v[66:67], v[152:153]
	v_pk_add_f32 v[56:57], v[158:159], v[56:57] neg_lo:[0,1] neg_hi:[0,1]
	v_mul_f32_e32 v18, 0.5, v29
	v_pk_mul_f32 v[58:59], v[56:57], v[18:19]
	v_mul_f32_e32 v6, 0.5, v28
	v_pk_fma_f32 v[54:55], v[54:55], v[58:59], v[58:59] op_sel:[0,1,0] op_sel_hi:[1,0,1]
	v_mov_b32_e32 v66, v56
	v_mov_b32_e32 v67, v52
	v_mov_b32_e32 v58, v59
	v_mov_b32_e32 v59, v18
	v_pk_mul_f32 v[58:59], v[66:67], v[58:59]
	v_pk_add_f32 v[66:67], v[6:7], v[54:55]
	v_mul_f32_e32 v12, 0.5, v12
	v_fma_f32 v67, v28, 0.5, -v54
	v_pk_add_f32 v[28:29], v[58:59], v[58:59] op_sel:[0,1] op_sel_hi:[0,1] neg_lo:[0,1] neg_hi:[0,1]
	v_pk_add_f32 v[54:55], v[12:13], v[28:29]
	v_pk_add_f32 v[28:29], v[12:13], v[28:29] op_sel_hi:[0,1] neg_lo:[0,1] neg_hi:[0,1]
	v_mov_b32_e32 v55, v29
	v_pk_mul_f32 v[28:29], v[54:55], v[156:157]
	v_pk_mul_f32 v[54:55], v[54:55], v[154:155]
	v_pk_fma_f32 v[32:33], v[70:71], 0.5, v[72:73] op_sel_hi:[1,0,1] neg_lo:[1,0,0] neg_hi:[1,0,0]
	v_pk_fma_f32 v[58:59], v[66:67], v[154:155], v[28:29] neg_lo:[0,0,1] neg_hi:[0,0,1]
	v_pk_fma_f32 v[28:29], v[66:67], v[154:155], v[28:29]
	v_pk_fma_f32 v[70:71], v[66:67], v[156:157], v[54:55]
	v_pk_fma_f32 v[54:55], v[66:67], v[156:157], v[54:55] neg_lo:[0,0,1] neg_hi:[0,0,1]
	v_pk_add_f32 v[72:73], v[58:59], v[28:29] op_sel:[0,1] op_sel_hi:[1,0]
	v_pk_add_f32 v[66:67], v[70:71], v[54:55] op_sel_hi:[0,1] neg_lo:[0,1] neg_hi:[0,1]
	v_pk_add_f32 v[28:29], v[58:59], v[28:29] op_sel_hi:[0,1] neg_lo:[0,1] neg_hi:[0,1]
	v_pk_add_f32 v[54:55], v[70:71], v[54:55] op_sel:[0,1] op_sel_hi:[1,0]
	v_mov_b32_e32 v73, v67
	v_mov_b32_e32 v55, v29
	v_pk_mul_f32 v[28:29], v[54:55], 0.5 op_sel_hi:[1,0]
	v_mov_b32_e32 v133, v84
	v_pk_mul_f32 v[54:55], v[52:53], v[28:29] op_sel:[0,1] op_sel_hi:[0,0]
	v_pk_fma_f32 v[58:59], v[56:57], v[28:29], v[54:55] op_sel_hi:[0,1,1]
	v_pk_fma_f32 v[28:29], v[56:57], v[28:29], v[54:55] op_sel_hi:[0,1,1] neg_lo:[0,0,1] neg_hi:[0,0,1]
	v_mov_b32_e32 v28, v58
	v_pk_fma_f32 v[54:55], v[72:73], 0.5, v[58:59] op_sel_hi:[1,0,1] neg_lo:[0,0,1] neg_hi:[0,0,1]
	v_pk_fma_f32 v[66:67], v[72:73], 0.5, v[28:29] op_sel_hi:[1,0,1]
	v_pk_add_f32 v[56:57], v[60:61], v[134:135] neg_lo:[0,1] neg_hi:[0,1]
	v_mov_b32_e32 v55, v67
	v_pk_mul_f32 v[90:91], v[54:55], s[6:7] op_sel_hi:[1,0]
	v_pk_add_f32 v[54:55], v[134:135], v[60:61]
	v_mul_f32_e32 v12, 0.5, v57
	v_mov_b32_e32 v57, v55
	v_mul_f32_e32 v6, 0.5, v54
	v_pk_mov_b32 v[58:59], v[52:53], v[50:51] op_sel:[1,0]
	v_pk_mul_f32 v[54:55], v[56:57], s[44:45]
	v_pk_fma_f32 v[28:29], v[72:73], 0.5, v[28:29] op_sel_hi:[1,0,1] neg_lo:[1,0,0] neg_hi:[1,0,0]
	v_pk_mul_f32 v[56:57], v[58:59], v[54:55] op_sel:[0,1] op_sel_hi:[1,0]
	v_pk_mul_f32 v[54:55], v[58:59], v[54:55]
	v_pk_add_f32 v[56:57], v[56:57], v[56:57] op_sel:[0,1] op_sel_hi:[0,1]
	v_pk_add_f32 v[60:61], v[6:7], v[56:57]
	v_pk_add_f32 v[56:57], v[6:7], v[56:57] op_sel_hi:[0,1] neg_lo:[0,1] neg_hi:[0,1]
	v_pk_add_f32 v[54:55], v[54:55], v[54:55] op_sel:[0,1] op_sel_hi:[0,1] neg_lo:[0,1] neg_hi:[0,1]
	v_mov_b32_e32 v61, v57
	v_pk_add_f32 v[56:57], v[12:13], v[54:55]
	v_pk_add_f32 v[54:55], v[12:13], v[54:55] op_sel_hi:[0,1] neg_lo:[0,1] neg_hi:[0,1]
	v_mov_b32_e32 v57, v55
	v_pk_mul_f32 v[54:55], v[56:57], v[142:143]
	v_pk_mul_f32 v[56:57], v[56:57], v[140:141]
	v_pk_fma_f32 v[54:55], v[60:61], v[140:141], v[54:55]
	v_pk_fma_f32 v[56:57], v[60:61], v[142:143], v[56:57] neg_lo:[0,0,1] neg_hi:[0,0,1]
	v_mov_b32_e32 v51, v53
	v_pk_add_f32 v[60:61], v[56:57], v[54:55] op_sel:[0,1] op_sel_hi:[1,0] neg_lo:[0,1] neg_hi:[0,1]
	v_pk_add_f32 v[70:71], v[56:57], v[54:55] op_sel:[0,1] op_sel_hi:[1,0]
	v_pk_add_f32 v[54:55], v[54:55], v[56:57] op_sel:[1,0] op_sel_hi:[0,1] neg_lo:[0,1] neg_hi:[0,1]
	v_mov_b32_e32 v61, v71
	v_pk_mul_f32 v[60:61], v[60:61], 0.5 op_sel_hi:[1,0]
	v_mov_b32_e32 v71, v55
	v_mul_f32_e32 v6, v53, v60
	v_pk_fma_f32 v[72:73], v[58:59], v[60:61], v[6:7] op_sel_hi:[1,1,0] neg_lo:[1,0,0] neg_hi:[1,0,0]
	v_mul_f32_e32 v6, v53, v61
	v_pk_fma_f32 v[50:51], v[50:51], v[60:61], v[6:7] op_sel_hi:[1,1,0]
	v_pk_add_f32 v[54:55], v[118:119], v[84:85]
	v_mov_b32_e32 v72, v50
	v_mov_b32_e32 v49, v118
	v_pk_fma_f32 v[50:51], v[70:71], 0.5, v[50:51] op_sel_hi:[1,0,1] neg_lo:[0,0,1] neg_hi:[0,0,1]
	v_pk_fma_f32 v[60:61], v[70:71], 0.5, v[72:73] op_sel_hi:[1,0,1]
	v_mul_f32_e32 v18, 0.5, v55
	v_pk_add_f32 v[48:49], v[132:133], v[48:49] neg_lo:[0,1] neg_hi:[0,1]
	v_mov_b32_e32 v51, v61
	v_pk_mul_f32 v[56:57], v[48:49], v[18:19]
	v_pk_mul_f32 v[94:95], v[50:51], s[6:7] op_sel_hi:[1,0]
	v_pk_fma_f32 v[50:51], v[70:71], 0.5, v[72:73] op_sel_hi:[1,0,1] neg_lo:[1,0,0] neg_hi:[1,0,0]
	v_mul_f32_e32 v6, 0.5, v54
	v_pk_fma_f32 v[58:59], v[58:59], v[56:57], v[56:57] op_sel:[0,1,0] op_sel_hi:[1,0,1]
	v_mov_b32_e32 v70, v48
	v_mov_b32_e32 v71, v53
	v_mov_b32_e32 v56, v57
	v_mov_b32_e32 v57, v18
	v_sub_f32_e32 v12, v85, v119
	v_pk_mul_f32 v[56:57], v[70:71], v[56:57]
	v_pk_add_f32 v[70:71], v[6:7], v[58:59]
	v_mul_f32_e32 v12, 0.5, v12
	v_fma_f32 v71, v54, 0.5, -v58
	v_pk_add_f32 v[54:55], v[56:57], v[56:57] op_sel:[0,1] op_sel_hi:[0,1] neg_lo:[0,1] neg_hi:[0,1]
	v_pk_add_f32 v[56:57], v[12:13], v[54:55]
	v_pk_add_f32 v[54:55], v[12:13], v[54:55] op_sel_hi:[0,1] neg_lo:[0,1] neg_hi:[0,1]
	v_mov_b32_e32 v57, v55
	v_pk_mul_f32 v[54:55], v[56:57], v[126:127]
	v_pk_mul_f32 v[56:57], v[56:57], v[124:125]
	v_pk_fma_f32 v[58:59], v[70:71], v[124:125], v[54:55] neg_lo:[0,0,1] neg_hi:[0,0,1]
	v_pk_fma_f32 v[54:55], v[70:71], v[124:125], v[54:55]
	v_pk_fma_f32 v[72:73], v[70:71], v[126:127], v[56:57]
	v_pk_fma_f32 v[56:57], v[70:71], v[126:127], v[56:57] neg_lo:[0,0,1] neg_hi:[0,0,1]
	v_pk_add_f32 v[70:71], v[58:59], v[54:55] op_sel:[0,1] op_sel_hi:[1,0]
	v_pk_add_f32 v[74:75], v[72:73], v[56:57] op_sel_hi:[0,1] neg_lo:[0,1] neg_hi:[0,1]
	v_pk_add_f32 v[54:55], v[58:59], v[54:55] op_sel_hi:[0,1] neg_lo:[0,1] neg_hi:[0,1]
	v_pk_add_f32 v[56:57], v[72:73], v[56:57] op_sel:[0,1] op_sel_hi:[1,0]
	v_mov_b32_e32 v71, v75
	v_mov_b32_e32 v57, v55
	v_pk_mul_f32 v[54:55], v[56:57], 0.5 op_sel_hi:[1,0]
	s_mov_b32 s78, s11
	v_pk_mul_f32 v[52:53], v[52:53], v[54:55] op_sel:[1,1] op_sel_hi:[1,0]
	s_mov_b32 s79, s8
	v_pk_fma_f32 v[56:57], v[48:49], v[54:55], v[52:53] op_sel_hi:[0,1,1]
	v_pk_fma_f32 v[48:49], v[48:49], v[54:55], v[52:53] op_sel_hi:[0,1,1] neg_lo:[0,0,1] neg_hi:[0,0,1]
	v_mov_b32_e32 v48, v56
	v_pk_fma_f32 v[52:53], v[70:71], 0.5, v[56:57] op_sel_hi:[1,0,1] neg_lo:[0,0,1] neg_hi:[0,0,1]
	v_pk_fma_f32 v[84:85], v[70:71], 0.5, v[48:49] op_sel_hi:[1,0,1]
	s_mov_b32 s9, s11
	v_mov_b32_e32 v53, v85
	v_pk_mul_f32 v[80:81], v[52:53], s[6:7] op_sel_hi:[1,0]
	v_pk_mul_f32 v[118:119], v[82:83], s[78:79] op_sel_hi:[0,1]
	v_pk_add_f32 v[52:53], v[86:87], v[112:113]
	v_pk_add_f32 v[54:55], v[86:87], v[112:113] neg_lo:[0,1] neg_hi:[0,1]
	v_pk_fma_f32 v[58:59], v[4:5], s[8:9], v[118:119] op_sel_hi:[0,1,1] neg_lo:[0,0,1] neg_hi:[0,0,1]
	v_mul_f32_e32 v12, 0.5, v55
	v_pk_fma_f32 v[72:73], v[4:5], s[8:9], v[118:119] op_sel_hi:[0,1,1]
	v_mov_b32_e32 v55, v53
	v_mul_f32_e32 v6, 0.5, v52
	v_mov_b32_e32 v56, v58
	v_mov_b32_e32 v57, v73
	v_pk_mul_f32 v[52:53], v[54:55], s[44:45]
	v_pk_fma_f32 v[48:49], v[70:71], 0.5, v[48:49] op_sel_hi:[1,0,1] neg_lo:[1,0,0] neg_hi:[1,0,0]
	v_pk_mul_f32 v[54:55], v[56:57], v[52:53] op_sel:[0,1] op_sel_hi:[1,0]
	v_pk_mul_f32 v[52:53], v[56:57], v[52:53]
	v_pk_add_f32 v[54:55], v[54:55], v[54:55] op_sel:[0,1] op_sel_hi:[0,1]
	v_pk_add_f32 v[74:75], v[6:7], v[54:55]
	v_pk_add_f32 v[54:55], v[6:7], v[54:55] op_sel_hi:[0,1] neg_lo:[0,1] neg_hi:[0,1]
	v_pk_add_f32 v[52:53], v[52:53], v[52:53] op_sel:[0,1] op_sel_hi:[0,1] neg_lo:[0,1] neg_hi:[0,1]
	v_mov_b32_e32 v75, v55
	v_pk_add_f32 v[54:55], v[12:13], v[52:53]
	v_pk_add_f32 v[52:53], v[12:13], v[52:53] op_sel_hi:[0,1] neg_lo:[0,1] neg_hi:[0,1]
	v_mov_b32_e32 v55, v53
	v_pk_mul_f32 v[52:53], v[54:55], v[116:117]
	v_pk_mul_f32 v[54:55], v[54:55], v[114:115]
	v_pk_fma_f32 v[52:53], v[74:75], v[114:115], v[52:53]
	v_pk_fma_f32 v[54:55], v[74:75], v[116:117], v[54:55] neg_lo:[0,0,1] neg_hi:[0,0,1]
	v_pk_mov_b32 v[70:71], v[72:73], v[58:59] op_sel:[1,0]
	v_pk_add_f32 v[74:75], v[54:55], v[52:53] op_sel:[0,1] op_sel_hi:[1,0] neg_lo:[0,1] neg_hi:[0,1]
	v_pk_add_f32 v[76:77], v[54:55], v[52:53] op_sel:[0,1] op_sel_hi:[1,0]
	v_pk_add_f32 v[52:53], v[52:53], v[54:55] op_sel:[1,0] op_sel_hi:[0,1] neg_lo:[0,1] neg_hi:[0,1]
	v_mov_b32_e32 v75, v77
	v_pk_mul_f32 v[74:75], v[74:75], 0.5 op_sel_hi:[1,0]
	v_mov_b32_e32 v77, v53
	v_mul_f32_e32 v6, v58, v74
	v_pk_fma_f32 v[112:113], v[56:57], v[74:75], v[6:7] op_sel_hi:[1,1,0] neg_lo:[1,0,0] neg_hi:[1,0,0]
	v_mul_f32_e32 v6, v58, v75
	v_pk_fma_f32 v[70:71], v[70:71], v[74:75], v[6:7] op_sel_hi:[1,1,0]
	v_pk_add_f32 v[54:55], v[34:35], v[110:111]
	v_mov_b32_e32 v112, v70
	v_pk_fma_f32 v[52:53], v[76:77], 0.5, v[70:71] op_sel_hi:[1,0,1] neg_lo:[0,0,1] neg_hi:[0,0,1]
	v_pk_fma_f32 v[86:87], v[76:77], 0.5, v[112:113] op_sel_hi:[1,0,1]
	v_sub_f32_e32 v12, v35, v111
	v_mov_b32_e32 v53, v87
	v_pk_mul_f32 v[78:79], v[52:53], s[6:7] op_sel_hi:[1,0]
	v_mul_f32_e32 v52, 0xbe47c5c2, v83
	v_mov_b32_e32 v53, v34
	v_pk_mov_b32 v[34:35], v[118:119], v[110:111] op_sel:[1,0]
	v_mul_f32_e32 v18, 0.5, v55
	v_pk_add_f32 v[34:35], v[52:53], v[34:35] neg_lo:[0,1] neg_hi:[0,1]
	v_mov_b32_e32 v71, v58
	v_pk_mul_f32 v[52:53], v[34:35], v[18:19]
	v_mov_b32_e32 v70, v34
	v_pk_fma_f32 v[56:57], v[56:57], v[52:53], v[52:53] op_sel:[0,1,0] op_sel_hi:[1,0,1]
	v_mov_b32_e32 v52, v53
	v_mov_b32_e32 v53, v18
	v_mul_f32_e32 v6, 0.5, v54
	v_pk_mul_f32 v[52:53], v[70:71], v[52:53]
	v_cvt_f32_f16_e32 v70, v46
	v_cvt_f32_f16_e32 v71, v47
	v_cvt_f32_f16_sdwa v47, v47 dst_sel:DWORD dst_unused:UNUSED_PAD src0_sel:WORD_1
	v_cvt_f32_f16_sdwa v46, v46 dst_sel:DWORD dst_unused:UNUSED_PAD src0_sel:WORD_1
	v_pk_fma_f32 v[74:75], v[76:77], 0.5, v[112:113] op_sel_hi:[1,0,1] neg_lo:[1,0,0] neg_hi:[1,0,0]
	v_mul_f32_e32 v12, 0.5, v12
	v_pk_add_f32 v[76:77], v[6:7], v[56:57]
	v_pk_add_f32 v[52:53], v[52:53], v[52:53] op_sel:[0,1] op_sel_hi:[0,1] neg_lo:[0,1] neg_hi:[0,1]
	v_fma_f32 v77, v54, 0.5, -v56
	v_pk_add_f32 v[54:55], v[12:13], v[52:53]
	v_pk_add_f32 v[52:53], v[12:13], v[52:53] op_sel_hi:[0,1] neg_lo:[0,1] neg_hi:[0,1]
	v_mov_b32_e32 v55, v53
	v_pk_mul_f32 v[52:53], v[54:55], v[46:47]
	v_pk_mul_f32 v[54:55], v[54:55], v[70:71]
	v_pk_fma_f32 v[56:57], v[76:77], v[70:71], v[52:53] neg_lo:[0,0,1] neg_hi:[0,0,1]
	v_pk_fma_f32 v[52:53], v[76:77], v[70:71], v[52:53]
	v_pk_fma_f32 v[70:71], v[76:77], v[46:47], v[54:55]
	v_pk_fma_f32 v[46:47], v[76:77], v[46:47], v[54:55] neg_lo:[0,0,1] neg_hi:[0,0,1]
	v_pk_add_f32 v[54:55], v[56:57], v[52:53] op_sel:[0,1] op_sel_hi:[1,0]
	v_pk_add_f32 v[76:77], v[70:71], v[46:47] op_sel_hi:[0,1] neg_lo:[0,1] neg_hi:[0,1]
	v_pk_add_f32 v[52:53], v[56:57], v[52:53] op_sel_hi:[0,1] neg_lo:[0,1] neg_hi:[0,1]
	v_pk_add_f32 v[46:47], v[70:71], v[46:47] op_sel:[0,1] op_sel_hi:[1,0]
	v_mov_b32_e32 v55, v77
	v_mov_b32_e32 v47, v53
	v_pk_mul_f32 v[46:47], v[46:47], 0.5 op_sel_hi:[1,0]
	s_mov_b32 s25, s27
	v_pk_mul_f32 v[52:53], v[58:59], v[46:47] op_sel:[0,1] op_sel_hi:[0,0]
	v_pk_fma_f32 v[56:57], v[34:35], v[46:47], v[52:53] op_sel_hi:[0,1,1]
	v_pk_fma_f32 v[46:47], v[34:35], v[46:47], v[52:53] op_sel_hi:[0,1,1] neg_lo:[0,0,1] neg_hi:[0,0,1]
	v_mov_b32_e32 v46, v56
	v_pk_fma_f32 v[52:53], v[54:55], 0.5, v[56:57] op_sel_hi:[1,0,1] neg_lo:[0,0,1] neg_hi:[0,0,1]
	v_pk_fma_f32 v[34:35], v[54:55], 0.5, v[46:47] op_sel_hi:[1,0,1]
	s_mov_b32 s78, s27
	v_mov_b32_e32 v53, v35
	v_pk_mul_f32 v[136:137], v[52:53], s[6:7] op_sel_hi:[1,0]
	v_pk_fma_f32 v[52:53], v[54:55], 0.5, v[46:47] op_sel_hi:[1,0,1] neg_lo:[1,0,0] neg_hi:[1,0,0]
	s_mov_b32 s79, s24
	v_pk_mul_f32 v[46:47], v[82:83], s[24:25] op_sel_hi:[0,1]
	v_pk_add_f32 v[54:55], v[108:109], v[40:41]
	v_pk_add_f32 v[40:41], v[40:41], v[108:109] neg_lo:[0,1] neg_hi:[0,1]
	v_pk_fma_f32 v[108:109], v[4:5], s[78:79], v[46:47] op_sel_hi:[0,1,1] neg_lo:[0,0,1] neg_hi:[0,0,1]
	v_mul_f32_e32 v12, 0.5, v41
	v_pk_fma_f32 v[70:71], v[4:5], s[78:79], v[46:47] op_sel_hi:[0,1,1]
	v_mov_b32_e32 v41, v55
	v_mov_b32_e32 v56, v108
	v_mov_b32_e32 v57, v71
	v_pk_mul_f32 v[40:41], v[40:41], s[44:45]
	v_mul_f32_e32 v6, 0.5, v54
	v_pk_mul_f32 v[54:55], v[56:57], v[40:41] op_sel:[0,1] op_sel_hi:[1,0]
	v_cvt_f32_f16_sdwa v76, v36 dst_sel:DWORD dst_unused:UNUSED_PAD src0_sel:WORD_1
	v_cvt_f32_f16_e32 v77, v37
	v_cvt_f32_f16_sdwa v37, v37 dst_sel:DWORD dst_unused:UNUSED_PAD src0_sel:WORD_1
	v_cvt_f32_f16_e32 v36, v36
	v_pk_mul_f32 v[40:41], v[56:57], v[40:41]
	v_pk_add_f32 v[54:55], v[54:55], v[54:55] op_sel:[0,1] op_sel_hi:[0,1]
	v_pk_add_f32 v[112:113], v[6:7], v[54:55]
	v_pk_add_f32 v[54:55], v[6:7], v[54:55] op_sel_hi:[0,1] neg_lo:[0,1] neg_hi:[0,1]
	v_pk_add_f32 v[40:41], v[40:41], v[40:41] op_sel:[0,1] op_sel_hi:[0,1] neg_lo:[0,1] neg_hi:[0,1]
	v_mov_b32_e32 v113, v55
	v_pk_add_f32 v[54:55], v[12:13], v[40:41]
	v_pk_add_f32 v[40:41], v[12:13], v[40:41] op_sel_hi:[0,1] neg_lo:[0,1] neg_hi:[0,1]
	v_mov_b32_e32 v55, v41
	v_pk_mul_f32 v[40:41], v[54:55], v[36:37]
	v_pk_mul_f32 v[54:55], v[54:55], v[76:77]
	v_pk_fma_f32 v[40:41], v[112:113], v[76:77], v[40:41]
	v_pk_fma_f32 v[36:37], v[112:113], v[36:37], v[54:55] neg_lo:[0,0,1] neg_hi:[0,0,1]
	v_pk_mov_b32 v[110:111], v[70:71], v[108:109] op_sel:[1,0]
	v_pk_add_f32 v[54:55], v[36:37], v[40:41] op_sel:[0,1] op_sel_hi:[1,0] neg_lo:[0,1] neg_hi:[0,1]
	v_pk_add_f32 v[76:77], v[36:37], v[40:41] op_sel:[0,1] op_sel_hi:[1,0]
	v_pk_add_f32 v[36:37], v[40:41], v[36:37] op_sel:[1,0] op_sel_hi:[0,1] neg_lo:[0,1] neg_hi:[0,1]
	v_mov_b32_e32 v55, v77
	v_pk_mul_f32 v[54:55], v[54:55], 0.5 op_sel_hi:[1,0]
	v_mov_b32_e32 v77, v37
	v_mul_f32_e32 v4, v108, v54
	v_pk_fma_f32 v[112:113], v[56:57], v[54:55], v[4:5] op_sel_hi:[1,1,0] neg_lo:[1,0,0] neg_hi:[1,0,0]
	v_mul_f32_e32 v4, v108, v55
	v_pk_fma_f32 v[54:55], v[110:111], v[54:55], v[4:5] op_sel_hi:[1,1,0]
	v_sub_f32_e32 v6, v45, v105
	v_mov_b32_e32 v112, v54
	v_pk_fma_f32 v[40:41], v[76:77], 0.5, v[54:55] op_sel_hi:[1,0,1] neg_lo:[0,0,1] neg_hi:[0,0,1]
	v_pk_fma_f32 v[36:37], v[76:77], 0.5, v[112:113] op_sel_hi:[1,0,1]
	v_pk_add_f32 v[54:55], v[104:105], v[44:45]
	v_mov_b32_e32 v41, v37
	v_pk_mul_f32 v[130:131], v[40:41], s[6:7] op_sel_hi:[1,0]
	v_mul_f32_e32 v40, 0xbf54db31, v83
	v_mov_b32_e32 v41, v44
	v_pk_mov_b32 v[44:45], v[46:47], v[104:105] op_sel:[1,0]
	v_mul_f32_e32 v18, 0.5, v55
	v_pk_add_f32 v[40:41], v[40:41], v[44:45] neg_lo:[0,1] neg_hi:[0,1]
	v_mov_b32_e32 v105, v108
	v_pk_mul_f32 v[44:45], v[40:41], v[18:19]
	v_mov_b32_e32 v104, v40
	v_pk_fma_f32 v[56:57], v[56:57], v[44:45], v[44:45] op_sel:[0,1,0] op_sel_hi:[1,0,1]
	v_mov_b32_e32 v44, v45
	v_mov_b32_e32 v45, v18
	v_mul_f32_e32 v4, 0.5, v54
	v_pk_mul_f32 v[44:45], v[104:105], v[44:45]
	v_cvt_f32_f16_e32 v104, v26
	v_cvt_f32_f16_e32 v105, v27
	v_cvt_f32_f16_sdwa v27, v27 dst_sel:DWORD dst_unused:UNUSED_PAD src0_sel:WORD_1
	v_cvt_f32_f16_sdwa v26, v26 dst_sel:DWORD dst_unused:UNUSED_PAD src0_sel:WORD_1
	v_mul_f32_e32 v6, 0.5, v6
	v_pk_add_f32 v[110:111], v[4:5], v[56:57]
	v_pk_add_f32 v[44:45], v[44:45], v[44:45] op_sel:[0,1] op_sel_hi:[0,1] neg_lo:[0,1] neg_hi:[0,1]
	v_fma_f32 v111, v54, 0.5, -v56
	v_pk_add_f32 v[54:55], v[6:7], v[44:45]
	v_pk_add_f32 v[44:45], v[6:7], v[44:45] op_sel_hi:[0,1] neg_lo:[0,1] neg_hi:[0,1]
	v_mov_b32_e32 v55, v45
	v_pk_mul_f32 v[44:45], v[54:55], v[26:27]
	v_pk_mul_f32 v[54:55], v[54:55], v[104:105]
	v_pk_fma_f32 v[56:57], v[110:111], v[104:105], v[44:45] neg_lo:[0,0,1] neg_hi:[0,0,1]
	v_pk_fma_f32 v[44:45], v[110:111], v[104:105], v[44:45]
	v_pk_fma_f32 v[104:105], v[110:111], v[26:27], v[54:55]
	v_pk_fma_f32 v[26:27], v[110:111], v[26:27], v[54:55] neg_lo:[0,0,1] neg_hi:[0,0,1]
	v_pk_add_f32 v[54:55], v[56:57], v[44:45] op_sel:[0,1] op_sel_hi:[1,0]
	v_pk_add_f32 v[110:111], v[104:105], v[26:27] op_sel_hi:[0,1] neg_lo:[0,1] neg_hi:[0,1]
	v_pk_add_f32 v[44:45], v[56:57], v[44:45] op_sel_hi:[0,1] neg_lo:[0,1] neg_hi:[0,1]
	v_pk_add_f32 v[26:27], v[104:105], v[26:27] op_sel:[0,1] op_sel_hi:[1,0]
	v_mov_b32_e32 v55, v111
	v_mov_b32_e32 v27, v45
	v_pk_mul_f32 v[26:27], v[26:27], 0.5 op_sel_hi:[1,0]
	v_mov_b32_e32 v47, v102
	v_pk_mul_f32 v[44:45], v[108:109], v[26:27] op_sel:[0,1] op_sel_hi:[0,0]
	v_pk_fma_f32 v[56:57], v[40:41], v[26:27], v[44:45] op_sel_hi:[0,1,1]
	v_pk_fma_f32 v[40:41], v[40:41], v[26:27], v[44:45] op_sel_hi:[0,1,1] neg_lo:[0,0,1] neg_hi:[0,0,1]
	v_mov_b32_e32 v40, v56
	v_pk_fma_f32 v[44:45], v[54:55], 0.5, v[56:57] op_sel_hi:[1,0,1] neg_lo:[0,0,1] neg_hi:[0,0,1]
	v_pk_fma_f32 v[26:27], v[54:55], 0.5, v[40:41] op_sel_hi:[1,0,1]
	v_pk_fma_f32 v[56:57], v[54:55], 0.5, v[40:41] op_sel_hi:[1,0,1] neg_lo:[1,0,0] neg_hi:[1,0,0]
	v_pk_add_f32 v[40:41], v[106:107], v[42:43]
	v_pk_add_f32 v[42:43], v[42:43], v[106:107] neg_lo:[0,1] neg_hi:[0,1]
	v_mov_b32_e32 v45, v27
	v_mul_f32_e32 v6, 0.5, v43
	v_mov_b32_e32 v43, v41
	v_pk_mul_f32 v[120:121], v[44:45], s[6:7] op_sel_hi:[1,0]
	v_mul_f32_e32 v4, 0.5, v40
	v_pk_mov_b32 v[44:45], v[108:109], v[70:71] op_sel:[1,0]
	v_pk_mul_f32 v[40:41], v[42:43], s[44:45]
	v_cvt_f32_f16_sdwa v54, v20 dst_sel:DWORD dst_unused:UNUSED_PAD src0_sel:WORD_1
	v_pk_mul_f32 v[42:43], v[44:45], v[40:41] op_sel:[0,1] op_sel_hi:[1,0]
	v_cvt_f32_f16_e32 v55, v21
	v_cvt_f32_f16_sdwa v21, v21 dst_sel:DWORD dst_unused:UNUSED_PAD src0_sel:WORD_1
	v_cvt_f32_f16_e32 v20, v20
	v_pk_mul_f32 v[40:41], v[44:45], v[40:41]
	v_pk_add_f32 v[42:43], v[42:43], v[42:43] op_sel:[0,1] op_sel_hi:[0,1]
	v_pk_add_f32 v[104:105], v[4:5], v[42:43]
	v_pk_add_f32 v[42:43], v[4:5], v[42:43] op_sel_hi:[0,1] neg_lo:[0,1] neg_hi:[0,1]
	v_pk_add_f32 v[40:41], v[40:41], v[40:41] op_sel:[0,1] op_sel_hi:[0,1] neg_lo:[0,1] neg_hi:[0,1]
	v_mov_b32_e32 v105, v43
	v_pk_add_f32 v[42:43], v[6:7], v[40:41]
	v_pk_add_f32 v[40:41], v[6:7], v[40:41] op_sel_hi:[0,1] neg_lo:[0,1] neg_hi:[0,1]
	v_mov_b32_e32 v43, v41
	v_pk_mul_f32 v[40:41], v[42:43], v[20:21]
	v_pk_mul_f32 v[42:43], v[42:43], v[54:55]
	v_pk_fma_f32 v[40:41], v[104:105], v[54:55], v[40:41]
	v_pk_fma_f32 v[20:21], v[104:105], v[20:21], v[42:43] neg_lo:[0,0,1] neg_hi:[0,0,1]
	v_mov_b32_e32 v71, v109
	v_pk_add_f32 v[42:43], v[20:21], v[40:41] op_sel:[0,1] op_sel_hi:[1,0] neg_lo:[0,1] neg_hi:[0,1]
	v_pk_add_f32 v[54:55], v[20:21], v[40:41] op_sel:[0,1] op_sel_hi:[1,0]
	v_pk_add_f32 v[20:21], v[40:41], v[20:21] op_sel:[1,0] op_sel_hi:[0,1] neg_lo:[0,1] neg_hi:[0,1]
	v_mov_b32_e32 v43, v55
	v_pk_mul_f32 v[42:43], v[42:43], 0.5 op_sel_hi:[1,0]
	v_mov_b32_e32 v55, v21
	v_mul_f32_e32 v4, v109, v42
	v_pk_fma_f32 v[104:105], v[44:45], v[42:43], v[4:5] op_sel_hi:[1,1,0] neg_lo:[1,0,0] neg_hi:[1,0,0]
	v_mul_f32_e32 v4, v109, v43
	v_pk_fma_f32 v[42:43], v[70:71], v[42:43], v[4:5] op_sel_hi:[1,1,0]
	v_sub_f32_e32 v6, v23, v103
	v_mov_b32_e32 v104, v42
	v_pk_fma_f32 v[40:41], v[54:55], 0.5, v[42:43] op_sel_hi:[1,0,1] neg_lo:[0,0,1] neg_hi:[0,0,1]
	v_pk_fma_f32 v[20:21], v[54:55], 0.5, v[104:105] op_sel_hi:[1,0,1]
	v_pk_add_f32 v[42:43], v[102:103], v[22:23]
	v_mov_b32_e32 v41, v21
	v_pk_mul_f32 v[128:129], v[40:41], s[6:7] op_sel_hi:[1,0]
	v_mul_f32_e32 v40, 0xbf0e39da, v83
	v_mov_b32_e32 v41, v22
	v_mul_f32_e32 v18, 0.5, v43
	v_pk_add_f32 v[22:23], v[40:41], v[46:47] neg_lo:[0,1] neg_hi:[0,1]
	v_mov_b32_e32 v47, v109
	v_pk_mul_f32 v[40:41], v[22:23], v[18:19]
	v_mov_b32_e32 v46, v22
	v_pk_fma_f32 v[44:45], v[44:45], v[40:41], v[40:41] op_sel:[0,1,0] op_sel_hi:[1,0,1]
	v_mov_b32_e32 v40, v41
	v_mov_b32_e32 v41, v18
	v_mul_f32_e32 v4, 0.5, v42
	v_pk_mul_f32 v[40:41], v[46:47], v[40:41]
	v_cvt_f32_f16_e32 v46, v10
	v_cvt_f32_f16_e32 v47, v11
	v_cvt_f32_f16_sdwa v11, v11 dst_sel:DWORD dst_unused:UNUSED_PAD src0_sel:WORD_1
	v_cvt_f32_f16_sdwa v10, v10 dst_sel:DWORD dst_unused:UNUSED_PAD src0_sel:WORD_1
	v_pk_fma_f32 v[70:71], v[54:55], 0.5, v[104:105] op_sel_hi:[1,0,1] neg_lo:[1,0,0] neg_hi:[1,0,0]
	v_mul_f32_e32 v6, 0.5, v6
	v_pk_add_f32 v[54:55], v[4:5], v[44:45]
	v_pk_add_f32 v[40:41], v[40:41], v[40:41] op_sel:[0,1] op_sel_hi:[0,1] neg_lo:[0,1] neg_hi:[0,1]
	v_fma_f32 v55, v42, 0.5, -v44
	v_pk_add_f32 v[42:43], v[6:7], v[40:41]
	v_pk_add_f32 v[40:41], v[6:7], v[40:41] op_sel_hi:[0,1] neg_lo:[0,1] neg_hi:[0,1]
	v_mov_b32_e32 v43, v41
	v_pk_mul_f32 v[40:41], v[42:43], v[10:11]
	v_pk_mul_f32 v[42:43], v[42:43], v[46:47]
	v_pk_fma_f32 v[44:45], v[54:55], v[46:47], v[40:41] neg_lo:[0,0,1] neg_hi:[0,0,1]
	v_pk_fma_f32 v[40:41], v[54:55], v[46:47], v[40:41]
	v_pk_fma_f32 v[46:47], v[54:55], v[10:11], v[42:43]
	v_pk_fma_f32 v[10:11], v[54:55], v[10:11], v[42:43] neg_lo:[0,0,1] neg_hi:[0,0,1]
	v_pk_add_f32 v[42:43], v[44:45], v[40:41] op_sel:[0,1] op_sel_hi:[1,0]
	v_pk_add_f32 v[54:55], v[46:47], v[10:11] op_sel_hi:[0,1] neg_lo:[0,1] neg_hi:[0,1]
	v_pk_add_f32 v[40:41], v[44:45], v[40:41] op_sel_hi:[0,1] neg_lo:[0,1] neg_hi:[0,1]
	v_pk_add_f32 v[10:11], v[46:47], v[10:11] op_sel:[0,1] op_sel_hi:[1,0]
	v_mov_b32_e32 v43, v55
	v_mov_b32_e32 v11, v41
	v_pk_mul_f32 v[10:11], v[10:11], 0.5 op_sel_hi:[1,0]
	v_mov_b32_e32 v119, v98
	v_pk_mul_f32 v[40:41], v[108:109], v[10:11] op_sel:[1,1] op_sel_hi:[1,0]
	v_pk_fma_f32 v[76:77], v[76:77], 0.5, v[112:113] op_sel_hi:[1,0,1] neg_lo:[1,0,0] neg_hi:[1,0,0]
	v_pk_fma_f32 v[44:45], v[22:23], v[10:11], v[40:41] op_sel_hi:[0,1,1]
	v_pk_fma_f32 v[10:11], v[22:23], v[10:11], v[40:41] op_sel_hi:[0,1,1] neg_lo:[0,0,1] neg_hi:[0,0,1]
	v_mov_b32_e32 v10, v44
	v_pk_fma_f32 v[22:23], v[42:43], 0.5, v[44:45] op_sel_hi:[1,0,1] neg_lo:[0,0,1] neg_hi:[0,0,1]
	v_pk_fma_f32 v[40:41], v[42:43], 0.5, v[10:11] op_sel_hi:[1,0,1]
	v_pk_fma_f32 v[54:55], v[42:43], 0.5, v[10:11] op_sel_hi:[1,0,1] neg_lo:[1,0,0] neg_hi:[1,0,0]
	v_pk_add_f32 v[10:11], v[100:101], v[14:15]
	v_pk_add_f32 v[14:15], v[14:15], v[100:101] neg_lo:[0,1] neg_hi:[0,1]
	v_mov_b32_e32 v23, v41
	v_mul_f32_e32 v6, 0.5, v15
	v_mov_b32_e32 v15, v11
	v_pk_mul_f32 v[150:151], v[22:23], s[6:7] op_sel_hi:[1,0]
	v_mul_f32_e32 v4, 0.5, v10
	v_pk_mov_b32 v[22:23], v[58:59], v[72:73] op_sel:[1,0]
	v_pk_mul_f32 v[10:11], v[14:15], s[44:45]
	v_cvt_f32_f16_sdwa v42, v8 dst_sel:DWORD dst_unused:UNUSED_PAD src0_sel:WORD_1
	v_pk_mul_f32 v[14:15], v[22:23], v[10:11] op_sel:[0,1] op_sel_hi:[1,0]
	v_cvt_f32_f16_e32 v43, v9
	v_cvt_f32_f16_sdwa v9, v9 dst_sel:DWORD dst_unused:UNUSED_PAD src0_sel:WORD_1
	v_cvt_f32_f16_e32 v8, v8
	v_pk_mul_f32 v[10:11], v[22:23], v[10:11]
	v_pk_add_f32 v[14:15], v[14:15], v[14:15] op_sel:[0,1] op_sel_hi:[0,1]
	v_pk_add_f32 v[44:45], v[4:5], v[14:15]
	v_pk_add_f32 v[14:15], v[4:5], v[14:15] op_sel_hi:[0,1] neg_lo:[0,1] neg_hi:[0,1]
	v_pk_add_f32 v[10:11], v[10:11], v[10:11] op_sel:[0,1] op_sel_hi:[0,1] neg_lo:[0,1] neg_hi:[0,1]
	v_mov_b32_e32 v45, v15
	v_pk_add_f32 v[14:15], v[6:7], v[10:11]
	v_pk_add_f32 v[10:11], v[6:7], v[10:11] op_sel_hi:[0,1] neg_lo:[0,1] neg_hi:[0,1]
	v_mov_b32_e32 v15, v11
	v_pk_mul_f32 v[10:11], v[14:15], v[8:9]
	v_pk_mul_f32 v[14:15], v[14:15], v[42:43]
	v_pk_fma_f32 v[10:11], v[44:45], v[42:43], v[10:11]
	v_pk_fma_f32 v[8:9], v[44:45], v[8:9], v[14:15] neg_lo:[0,0,1] neg_hi:[0,0,1]
	v_mov_b32_e32 v73, v59
	v_pk_add_f32 v[14:15], v[8:9], v[10:11] op_sel:[0,1] op_sel_hi:[1,0] neg_lo:[0,1] neg_hi:[0,1]
	v_pk_add_f32 v[42:43], v[8:9], v[10:11] op_sel:[0,1] op_sel_hi:[1,0]
	v_pk_add_f32 v[8:9], v[10:11], v[8:9] op_sel:[1,0] op_sel_hi:[0,1] neg_lo:[0,1] neg_hi:[0,1]
	v_mov_b32_e32 v15, v43
	v_pk_mul_f32 v[14:15], v[14:15], 0.5 op_sel_hi:[1,0]
	v_mov_b32_e32 v43, v9
	v_mul_f32_e32 v4, v59, v14
	v_pk_fma_f32 v[44:45], v[22:23], v[14:15], v[4:5] op_sel_hi:[1,1,0] neg_lo:[1,0,0] neg_hi:[1,0,0]
	v_mul_f32_e32 v4, v59, v15
	v_pk_fma_f32 v[14:15], v[72:73], v[14:15], v[4:5] op_sel_hi:[1,1,0]
	v_sub_f32_e32 v6, v39, v99
	v_mov_b32_e32 v44, v14
	v_pk_fma_f32 v[8:9], v[42:43], 0.5, v[14:15] op_sel_hi:[1,0,1] neg_lo:[0,0,1] neg_hi:[0,0,1]
	v_pk_fma_f32 v[10:11], v[42:43], 0.5, v[44:45] op_sel_hi:[1,0,1]
	v_pk_add_f32 v[14:15], v[98:99], v[38:39]
	v_mov_b32_e32 v9, v11
	v_pk_mul_f32 v[168:169], v[8:9], s[6:7] op_sel_hi:[1,0]
	v_mul_f32_e32 v8, 0xbf7b14be, v83
	v_mov_b32_e32 v9, v38
	v_mul_f32_e32 v18, 0.5, v15
	v_pk_add_f32 v[8:9], v[8:9], v[118:119] neg_lo:[0,1] neg_hi:[0,1]
	v_pk_fma_f32 v[72:73], v[42:43], 0.5, v[44:45] op_sel_hi:[1,0,1] neg_lo:[1,0,0] neg_hi:[1,0,0]
	v_pk_mul_f32 v[38:39], v[8:9], v[18:19]
	v_mov_b32_e32 v42, v8
	v_pk_fma_f32 v[22:23], v[22:23], v[38:39], v[38:39] op_sel:[0,1,0] op_sel_hi:[1,0,1]
	v_mov_b32_e32 v43, v59
	v_mov_b32_e32 v38, v39
	v_mov_b32_e32 v39, v18
	v_mul_f32_e32 v4, 0.5, v14
	v_pk_mul_f32 v[38:39], v[42:43], v[38:39]
	v_cvt_f32_f16_e32 v44, v2
	v_cvt_f32_f16_e32 v45, v3
	v_cvt_f32_f16_sdwa v3, v3 dst_sel:DWORD dst_unused:UNUSED_PAD src0_sel:WORD_1
	v_cvt_f32_f16_sdwa v2, v2 dst_sel:DWORD dst_unused:UNUSED_PAD src0_sel:WORD_1
	v_mul_f32_e32 v6, 0.5, v6
	v_pk_add_f32 v[46:47], v[4:5], v[22:23]
	v_fma_f32 v4, v14, 0.5, -v22
	v_pk_add_f32 v[22:23], v[38:39], v[38:39] op_sel:[0,1] op_sel_hi:[0,1] neg_lo:[0,1] neg_hi:[0,1]
	v_pk_add_f32 v[38:39], v[6:7], v[22:23]
	v_pk_add_f32 v[22:23], v[6:7], v[22:23] op_sel_hi:[0,1] neg_lo:[0,1] neg_hi:[0,1]
	v_mov_b32_e32 v39, v23
	v_mov_b32_e32 v14, v46
	v_mov_b32_e32 v15, v4
	v_pk_mul_f32 v[22:23], v[4:5], v[44:45] op_sel_hi:[0,1]
	v_pk_mul_f32 v[82:83], v[38:39], v[2:3]
	v_pk_mul_f32 v[46:47], v[46:47], v[2:3]
	v_pk_mul_f32 v[38:39], v[38:39], v[44:45]
	v_pk_fma_f32 v[98:99], v[14:15], v[44:45], v[82:83] neg_lo:[0,0,1] neg_hi:[0,0,1]
	v_pk_fma_f32 v[2:3], v[14:15], v[2:3], v[38:39] neg_lo:[0,0,1] neg_hi:[0,0,1]
	v_add_f32_e32 v4, v23, v83
	v_add_f32_e32 v6, v46, v38
	v_pk_add_f32 v[22:23], v[6:7], v[2:3] op_sel_hi:[0,1] neg_lo:[0,1] neg_hi:[0,1]
	v_pk_add_f32 v[38:39], v[98:99], v[4:5] op_sel_hi:[1,0] neg_lo:[0,1] neg_hi:[0,1]
	v_pk_add_f32 v[2:3], v[6:7], v[2:3] op_sel_hi:[0,1]
	v_mov_b32_e32 v39, v3
	v_pk_mul_f32 v[2:3], v[38:39], 0.5 op_sel_hi:[1,0]
	v_pk_add_f32 v[14:15], v[98:99], v[4:5] op_sel_hi:[1,0]
	v_mul_f32_e32 v4, v59, v3
	v_pk_fma_f32 v[38:39], v[42:43], v[2:3], v[4:5] op_sel_hi:[1,1,0] neg_lo:[0,0,1] neg_hi:[0,0,1]
	v_pk_mov_b32 v[42:43], v[58:59], v[8:9] op_sel:[1,0]
	v_mul_f32_e32 v4, v8, v3
	v_pk_fma_f32 v[2:3], v[42:43], v[2:3], v[4:5] op_sel_hi:[1,1,0]
	v_mov_b32_e32 v15, v23
	v_pk_fma_f32 v[8:9], v[14:15], 0.5, v[2:3] op_sel_hi:[1,0,1] neg_lo:[0,0,1] neg_hi:[0,0,1]
	v_pk_fma_f32 v[42:43], v[14:15], 0.5, v[38:39] op_sel_hi:[1,0,0]
	v_pk_fma_f32 v[2:3], v[14:15], 0.5, v[2:3] op_sel_hi:[1,0,1]
	v_mov_b32_e32 v9, v43
	v_pk_fma_f32 v[58:59], v[22:23], 0.5, v[38:39] op_sel_hi:[1,0,0] neg_lo:[1,0,0] neg_hi:[1,0,0]
	v_pk_mul_f32 v[144:145], v[8:9], s[6:7] op_sel_hi:[1,0]
	v_mov_b32_e32 v58, v2
	v_mov_b32_e32 v72, v10
	v_mov_b32_e32 v54, v40
	v_mov_b32_e32 v70, v20
	v_mov_b32_e32 v56, v26
	v_mov_b32_e32 v76, v36
	v_mov_b32_e32 v52, v34
	v_mov_b32_e32 v74, v86
	v_mov_b32_e32 v48, v84
	v_mov_b32_e32 v50, v60
	v_mov_b32_e32 v28, v66
	v_mov_b32_e32 v32, v96
	v_mov_b32_e32 v12, v88
	v_mov_b32_e32 v16, v92
	v_mov_b32_e32 v4, v138
	v_mov_b32_e32 v6, v122

.LBB0_534:
	s_add_i32 s100, s62, s48
	s_lshl_b32 s100, s100, 15
	s_add_u32 s100, s29, s100
	s_addc_u32 s101, s85, 0
	v_and_b32_e32 v245, 0xff, v210
	v_lshlrev_b32_e32 v245, 3, v245
	s_add_u32 s100, s100, 0x1000
	s_addc_u32 s101, s101, 0
	global_load_dwordx2 v[214:215], v245, s[100:101] offset:-4096 nt
	global_load_dwordx2 v[216:217], v245, s[100:101] offset:-2048 nt
	global_load_dwordx2 v[218:219], v245, s[100:101] nt
	global_load_dwordx2 v[220:221], v245, s[100:101] offset:2048 nt
	s_add_u32 s100, s100, 0x2000
	s_addc_u32 s101, s101, 0
	global_load_dwordx2 v[222:223], v245, s[100:101] offset:-4096 nt
	global_load_dwordx2 v[224:225], v245, s[100:101] offset:-2048 nt
	global_load_dwordx2 v[226:227], v245, s[100:101] nt
	global_load_dwordx2 v[228:229], v245, s[100:101] offset:2048 nt
	s_add_u32 s100, s100, 0x2000
	s_addc_u32 s101, s101, 0
	global_load_dwordx2 v[230:231], v245, s[100:101] offset:-4096 nt
	global_load_dwordx2 v[232:233], v245, s[100:101] offset:-2048 nt
	global_load_dwordx2 v[234:235], v245, s[100:101] nt
	global_load_dwordx2 v[236:237], v245, s[100:101] offset:2048 nt
	s_add_u32 s100, s100, 0x2000
	s_addc_u32 s101, s101, 0
	global_load_dwordx2 v[238:239], v245, s[100:101] offset:-4096 nt
	global_load_dwordx2 v[240:241], v245, s[100:101] offset:-2048 nt
	global_load_dwordx2 v[242:243], v245, s[100:101] nt
	global_load_dwordx2 v[246:247], v245, s[100:101] offset:2048 nt
	v_mov_b32_e32 v2, v210
	s_mov_b32 s43, s8
	v_and_b32_e32 v3, 0xff, v2
	v_lshlrev_b32_e32 v4, 5, v2
	v_and_or_b32 v3, v4, s33, v3
	v_ashrrev_i32_e32 v4, 5, v3
	v_lshlrev_b32_e32 v3, 3, v3
	v_lshlrev_b32_e32 v4, 3, v4
	v_add3_u32 v18, 0, v3, v4
	ds_read_b64 v[128:129], v18
	ds_read_b64 v[132:133], v18 offset:2112
	ds_read_b64 v[134:135], v18 offset:4224
	ds_read_b64 v[136:137], v18 offset:6336
	ds_read_b64 v[138:139], v18 offset:8448
	ds_read_b64 v[140:141], v18 offset:10560
	ds_read_b64 v[142:143], v18 offset:12672
	ds_read_b64 v[130:131], v18 offset:14784
	ds_read_b64 v[144:145], v18 offset:16896
	ds_read_b64 v[148:149], v18 offset:19008
	ds_read_b64 v[150:151], v18 offset:21120
	ds_read_b64 v[152:153], v18 offset:23232
	s_waitcnt lgkmcnt(10)
	v_pk_mul_f32 v[162:163], v[132:133], s[10:11]
	s_mov_b32 s64, s11
	v_pk_fma_f32 v[162:163], v[132:133], s[8:9], v[162:163] op_sel:[0,0,1] op_sel_hi:[1,0,0]
	s_waitcnt lgkmcnt(2)
	v_pk_mul_f32 v[178:179], v[148:149], s[42:43]
	v_pk_add_f32 v[194:195], v[132:133], v[148:149]
	v_pk_add_f32 v[132:133], v[132:133], v[148:149] neg_lo:[0,1] neg_hi:[0,1]
	v_pk_mul_f32 v[164:165], v[134:135], s[18:19]
	s_mov_b32 s41, s16
	v_pk_fma_f32 v[178:179], v[148:149], s[64:65], v[178:179] op_sel:[0,0,1] op_sel_hi:[1,0,0] neg_lo:[1,0,0] neg_hi:[1,0,0]
	v_pk_mul_f32 v[148:149], v[132:133], s[18:19]
	v_pk_fma_f32 v[164:165], v[134:135], s[16:17], v[164:165] op_sel:[0,0,1] op_sel_hi:[1,0,0]
	s_mov_b32 s68, s19
	s_waitcnt lgkmcnt(1)
	v_pk_mul_f32 v[180:181], v[150:151], s[40:41]
	v_pk_fma_f32 v[132:133], v[132:133], s[16:17], v[148:149] op_sel:[0,0,1] op_sel_hi:[1,0,0]
	v_pk_add_f32 v[148:149], v[134:135], v[150:151]
	v_pk_add_f32 v[134:135], v[134:135], v[150:151] neg_lo:[0,1] neg_hi:[0,1]
	v_pk_mul_f32 v[166:167], v[136:137], s[26:27]
	s_mov_b32 s66, s37
	s_mov_b32 s39, s24
	v_pk_fma_f32 v[180:181], v[150:151], s[68:69], v[180:181] op_sel:[0,0,1] op_sel_hi:[1,0,0] neg_lo:[1,0,0] neg_hi:[1,0,0]
	v_pk_mul_f32 v[150:151], v[134:135], s[36:37]
	ds_read_b64 v[154:155], v18 offset:25344
	ds_read_b64 v[156:157], v18 offset:27456
	ds_read_b64 v[158:159], v18 offset:29568
	ds_read_b64 v[160:161], v18 offset:31680
	v_pk_fma_f32 v[166:167], v[136:137], s[24:25], v[166:167] op_sel:[0,0,1] op_sel_hi:[1,0,0]
	s_mov_b32 s0, s27
	s_waitcnt lgkmcnt(4)
	v_pk_mul_f32 v[182:183], v[152:153], s[38:39]
	v_pk_fma_f32 v[134:135], v[134:135], s[66:67], v[150:151] op_sel:[0,0,1] op_sel_hi:[1,0,0]
	v_pk_add_f32 v[150:151], v[136:137], v[152:153]
	v_pk_add_f32 v[136:137], v[136:137], v[152:153] neg_lo:[0,1] neg_hi:[0,1]
	v_pk_mul_f32 v[168:169], v[138:139], s[36:37]
	v_pk_fma_f32 v[182:183], v[152:153], s[0:1], v[182:183] op_sel:[0,0,1] op_sel_hi:[1,0,0] neg_lo:[1,0,0] neg_hi:[1,0,0]
	v_pk_mul_f32 v[152:153], v[136:137], s[40:41]
	v_pk_fma_f32 v[168:169], v[138:139], s[66:67], v[168:169] op_sel:[0,0,1] op_sel_hi:[1,0,0]
	v_pk_mul_f32 v[170:171], v[140:141], s[38:39]
	s_waitcnt lgkmcnt(3)
	v_pk_mul_f32 v[184:185], v[154:155], s[36:37]
	v_pk_fma_f32 v[136:137], v[136:137], s[68:69], v[152:153] op_sel:[0,0,1] op_sel_hi:[1,0,0]
	v_pk_add_f32 v[152:153], v[138:139], v[154:155]
	v_pk_add_f32 v[138:139], v[138:139], v[154:155] neg_lo:[0,1] neg_hi:[0,1]
	v_pk_fma_f32 v[170:171], v[140:141], s[0:1], v[170:171] op_sel:[0,0,1] op_sel_hi:[1,0,0]
	v_pk_fma_f32 v[184:185], v[154:155], s[66:67], v[184:185] op_sel:[0,0,1] op_sel_hi:[1,0,0] neg_lo:[1,0,0] neg_hi:[1,0,0]
	s_waitcnt lgkmcnt(2)
	v_pk_mul_f32 v[186:187], v[156:157], s[26:27]
	v_xor_b32_e32 v155, 0x80000000, v138
	v_mov_b32_e32 v154, v139
	v_pk_add_f32 v[138:139], v[140:141], v[156:157]
	v_pk_add_f32 v[140:141], v[140:141], v[156:157] neg_lo:[0,1] neg_hi:[0,1]
	v_pk_mul_f32 v[172:173], v[142:143], s[40:41]
	v_pk_fma_f32 v[186:187], v[156:157], s[24:25], v[186:187] op_sel:[0,0,1] op_sel_hi:[1,0,0] neg_lo:[1,0,0] neg_hi:[1,0,0]
	v_pk_mul_f32 v[156:157], v[140:141], s[40:41]
	v_pk_fma_f32 v[172:173], v[142:143], s[68:69], v[172:173] op_sel:[0,0,1] op_sel_hi:[1,0,0]
	s_waitcnt lgkmcnt(1)
	v_pk_mul_f32 v[188:189], v[158:159], s[18:19]
	v_pk_fma_f32 v[140:141], v[140:141], s[68:69], v[156:157] op_sel:[0,0,1] op_sel_hi:[1,0,0] neg_lo:[1,0,0] neg_hi:[1,0,0]
	v_pk_add_f32 v[156:157], v[142:143], v[158:159]
	v_pk_add_f32 v[142:143], v[142:143], v[158:159] neg_lo:[0,1] neg_hi:[0,1]
	v_pk_mul_f32 v[174:175], v[130:131], s[42:43]
	v_pk_fma_f32 v[188:189], v[158:159], s[16:17], v[188:189] op_sel:[0,0,1] op_sel_hi:[1,0,0] neg_lo:[1,0,0] neg_hi:[1,0,0]
	v_pk_mul_f32 v[158:159], v[142:143], s[36:37]
	v_pk_fma_f32 v[174:175], v[130:131], s[64:65], v[174:175] op_sel:[0,0,1] op_sel_hi:[1,0,0]
	s_waitcnt lgkmcnt(0)
	v_pk_mul_f32 v[190:191], v[160:161], s[10:11]
	v_pk_fma_f32 v[142:143], v[142:143], s[66:67], v[158:159] op_sel:[0,0,1] op_sel_hi:[1,0,0] neg_lo:[1,0,0] neg_hi:[1,0,0]
	v_pk_add_f32 v[158:159], v[130:131], v[160:161]
	v_pk_add_f32 v[130:131], v[130:131], v[160:161] neg_lo:[0,1] neg_hi:[0,1]
	v_xor_b32_e32 v177, 0x80000000, v144
	v_mov_b32_e32 v176, v145
	v_pk_fma_f32 v[190:191], v[160:161], s[8:9], v[190:191] op_sel:[0,0,1] op_sel_hi:[1,0,0] neg_lo:[1,0,0] neg_hi:[1,0,0]
	v_pk_mul_f32 v[160:161], v[130:131], s[18:19]
	v_pk_add_f32 v[192:193], v[128:129], v[144:145]
	v_pk_add_f32 v[144:145], v[128:129], v[144:145] neg_lo:[0,1] neg_hi:[0,1]
	v_pk_fma_f32 v[130:131], v[130:131], s[16:17], v[160:161] op_sel:[0,0,1] op_sel_hi:[1,0,0] neg_lo:[1,0,0] neg_hi:[1,0,0]
	v_pk_add_f32 v[160:161], v[128:129], v[176:177]
	v_pk_add_f32 v[128:129], v[128:129], v[176:177] neg_lo:[0,1] neg_hi:[0,1]
	v_pk_add_f32 v[176:177], v[162:163], v[178:179]
	v_pk_add_f32 v[162:163], v[162:163], v[178:179] neg_lo:[0,1] neg_hi:[0,1]
	v_cvt_f32_ubyte0_e32 v2, v2
	v_pk_mul_f32 v[178:179], v[162:163], s[18:19]
	v_mul_f32_e32 v2, 0x39000000, v2
	v_pk_fma_f32 v[162:163], v[162:163], s[16:17], v[178:179] op_sel:[0,0,1] op_sel_hi:[1,0,0]
	v_pk_add_f32 v[178:179], v[164:165], v[180:181]
	v_pk_add_f32 v[164:165], v[164:165], v[180:181] neg_lo:[0,1] neg_hi:[0,1]
	v_sin_f32_e32 v34, v2
	v_pk_mul_f32 v[180:181], v[164:165], s[36:37]
	v_cos_f32_e32 v30, v2
	v_pk_fma_f32 v[164:165], v[164:165], s[66:67], v[180:181] op_sel:[0,0,1] op_sel_hi:[1,0,0]
	v_pk_add_f32 v[180:181], v[166:167], v[182:183]
	v_pk_add_f32 v[166:167], v[166:167], v[182:183] neg_lo:[0,1] neg_hi:[0,1]
	v_xor_b32_e32 v31, 0x80000000, v34
	v_pk_mul_f32 v[182:183], v[166:167], s[40:41]
	v_mov_b32_e32 v35, v31
	v_pk_fma_f32 v[166:167], v[166:167], s[68:69], v[182:183] op_sel:[0,0,1] op_sel_hi:[1,0,0]
	v_pk_add_f32 v[182:183], v[168:169], v[184:185]
	v_pk_add_f32 v[168:169], v[168:169], v[184:185] neg_lo:[0,1] neg_hi:[0,1]
	v_pk_mul_f32 v[2:3], v[30:31], v[34:35] op_sel:[1,0] op_sel_hi:[0,1]
	v_xor_b32_e32 v185, 0x80000000, v168
	v_mov_b32_e32 v184, v169
	v_pk_add_f32 v[168:169], v[170:171], v[186:187]
	v_pk_add_f32 v[170:171], v[170:171], v[186:187] neg_lo:[0,1] neg_hi:[0,1]
	v_pk_fma_f32 v[44:45], v[30:31], v[30:31], v[2:3] op_sel_hi:[1,0,1]
	v_pk_mul_f32 v[186:187], v[170:171], s[40:41]
	v_pk_mul_f32 v[2:3], v[34:35], v[44:45] op_sel:[0,1] op_sel_hi:[1,0]
	v_pk_fma_f32 v[170:171], v[170:171], s[68:69], v[186:187] op_sel:[0,0,1] op_sel_hi:[1,0,0] neg_lo:[1,0,0] neg_hi:[1,0,0]
	v_pk_add_f32 v[186:187], v[172:173], v[188:189]
	v_pk_add_f32 v[172:173], v[172:173], v[188:189] neg_lo:[0,1] neg_hi:[0,1]
	v_xor_b32_e32 v54, 0x80000000, v45
	v_pk_mul_f32 v[188:189], v[172:173], s[36:37]
	v_mov_b32_e32 v55, v45
	v_pk_fma_f32 v[172:173], v[172:173], s[66:67], v[188:189] op_sel:[0,0,1] op_sel_hi:[1,0,0] neg_lo:[1,0,0] neg_hi:[1,0,0]
	v_pk_add_f32 v[188:189], v[174:175], v[190:191]
	v_pk_add_f32 v[174:175], v[174:175], v[190:191] neg_lo:[0,1] neg_hi:[0,1]
	v_pk_fma_f32 v[46:47], v[30:31], v[44:45], v[2:3] op_sel_hi:[0,1,1]
	v_pk_mul_f32 v[190:191], v[174:175], s[18:19]
	v_pk_mul_f32 v[2:3], v[44:45], v[54:55] op_sel:[1,0] op_sel_hi:[0,1]
	v_pk_fma_f32 v[174:175], v[174:175], s[16:17], v[190:191] op_sel:[0,0,1] op_sel_hi:[1,0,0] neg_lo:[1,0,0] neg_hi:[1,0,0]
	v_pk_add_f32 v[190:191], v[192:193], v[152:153]
	v_pk_add_f32 v[152:153], v[192:193], v[152:153] neg_lo:[0,1] neg_hi:[0,1]
	v_pk_add_f32 v[192:193], v[194:195], v[138:139]
	v_pk_add_f32 v[138:139], v[194:195], v[138:139] neg_lo:[0,1] neg_hi:[0,1]
	v_pk_fma_f32 v[52:53], v[44:45], v[44:45], v[2:3] op_sel_hi:[1,0,1]
	v_pk_mul_f32 v[194:195], v[138:139], s[36:37]
	v_xor_b32_e32 v58, 0x80000000, v53
	v_pk_fma_f32 v[138:139], v[138:139], s[66:67], v[194:195] op_sel:[0,0,1] op_sel_hi:[1,0,0]
	v_pk_add_f32 v[194:195], v[148:149], v[156:157]
	v_pk_add_f32 v[148:149], v[148:149], v[156:157] neg_lo:[0,1] neg_hi:[0,1]
	v_mov_b32_e32 v59, v53
	v_xor_b32_e32 v157, 0x80000000, v148
	v_mov_b32_e32 v156, v149
	v_pk_add_f32 v[148:149], v[150:151], v[158:159]
	v_pk_add_f32 v[150:151], v[150:151], v[158:159] neg_lo:[0,1] neg_hi:[0,1]
	v_pk_mul_f32 v[2:3], v[52:53], v[58:59] op_sel:[1,0] op_sel_hi:[0,1]
	v_pk_mul_f32 v[158:159], v[150:151], s[36:37]
	v_pk_fma_f32 v[48:49], v[52:53], v[52:53], v[2:3] op_sel_hi:[1,0,1]
	v_pk_fma_f32 v[150:151], v[150:151], s[66:67], v[158:159] op_sel:[0,0,1] op_sel_hi:[1,0,0] neg_lo:[1,0,0] neg_hi:[1,0,0]
	v_pk_add_f32 v[158:159], v[144:145], v[154:155]
	v_pk_add_f32 v[144:145], v[144:145], v[154:155] neg_lo:[0,1] neg_hi:[0,1]
	v_pk_add_f32 v[154:155], v[132:133], v[140:141]
	v_pk_add_f32 v[132:133], v[132:133], v[140:141] neg_lo:[0,1] neg_hi:[0,1]
	v_pk_mul_f32 v[2:3], v[58:59], v[48:49] op_sel:[0,1] op_sel_hi:[1,0]
	v_pk_mul_f32 v[140:141], v[132:133], s[36:37]
	v_pk_fma_f32 v[36:37], v[52:53], v[48:49], v[2:3] op_sel_hi:[0,1,1]
	v_pk_fma_f32 v[132:133], v[132:133], s[66:67], v[140:141] op_sel:[0,0,1] op_sel_hi:[1,0,0]
	v_pk_add_f32 v[140:141], v[134:135], v[142:143]
	v_pk_add_f32 v[134:135], v[134:135], v[142:143] neg_lo:[0,1] neg_hi:[0,1]
	v_pk_mul_f32 v[2:3], v[58:59], v[36:37] op_sel:[0,1] op_sel_hi:[1,0]
	v_xor_b32_e32 v143, 0x80000000, v134
	v_mov_b32_e32 v142, v135
	v_pk_add_f32 v[134:135], v[136:137], v[130:131]
	v_pk_add_f32 v[130:131], v[136:137], v[130:131] neg_lo:[0,1] neg_hi:[0,1]
	v_pk_fma_f32 v[26:27], v[52:53], v[36:37], v[2:3] op_sel_hi:[0,1,1]
	v_pk_mul_f32 v[136:137], v[130:131], s[36:37]
	v_pk_mul_f32 v[2:3], v[58:59], v[26:27] op_sel:[0,1] op_sel_hi:[1,0]
	v_pk_fma_f32 v[130:131], v[130:131], s[66:67], v[136:137] op_sel:[0,0,1] op_sel_hi:[1,0,0] neg_lo:[1,0,0] neg_hi:[1,0,0]
	v_pk_add_f32 v[136:137], v[160:161], v[182:183]
	v_pk_add_f32 v[160:161], v[160:161], v[182:183] neg_lo:[0,1] neg_hi:[0,1]
	v_pk_add_f32 v[182:183], v[176:177], v[168:169]
	v_pk_add_f32 v[168:169], v[176:177], v[168:169] neg_lo:[0,1] neg_hi:[0,1]
	v_pk_fma_f32 v[20:21], v[52:53], v[26:27], v[2:3] op_sel_hi:[0,1,1]
	v_pk_mul_f32 v[176:177], v[168:169], s[36:37]
	v_pk_mul_f32 v[2:3], v[58:59], v[20:21] op_sel:[0,1] op_sel_hi:[1,0]
	v_pk_fma_f32 v[168:169], v[168:169], s[66:67], v[176:177] op_sel:[0,0,1] op_sel_hi:[1,0,0]
	v_pk_add_f32 v[176:177], v[178:179], v[186:187]
	v_pk_add_f32 v[178:179], v[178:179], v[186:187] neg_lo:[0,1] neg_hi:[0,1]
	v_pk_fma_f32 v[10:11], v[52:53], v[20:21], v[2:3] op_sel_hi:[0,1,1]
	v_xor_b32_e32 v187, 0x80000000, v178
	v_mov_b32_e32 v186, v179
	v_pk_add_f32 v[178:179], v[180:181], v[188:189]
	v_pk_add_f32 v[180:181], v[180:181], v[188:189] neg_lo:[0,1] neg_hi:[0,1]
	v_pk_mul_f32 v[2:3], v[58:59], v[10:11] op_sel:[0,1] op_sel_hi:[1,0]
	v_pk_mul_f32 v[188:189], v[180:181], s[36:37]
	v_pk_fma_f32 v[4:5], v[52:53], v[10:11], v[2:3] op_sel_hi:[0,1,1]
	v_pk_fma_f32 v[180:181], v[180:181], s[66:67], v[188:189] op_sel:[0,0,1] op_sel_hi:[1,0,0] neg_lo:[1,0,0] neg_hi:[1,0,0]
	v_pk_add_f32 v[188:189], v[128:129], v[184:185]
	v_pk_add_f32 v[128:129], v[128:129], v[184:185] neg_lo:[0,1] neg_hi:[0,1]
	v_pk_add_f32 v[184:185], v[162:163], v[170:171]
	v_pk_add_f32 v[162:163], v[162:163], v[170:171] neg_lo:[0,1] neg_hi:[0,1]
	v_xor_b32_e32 v72, 0x80000000, v47
	v_pk_mul_f32 v[170:171], v[162:163], s[36:37]
	v_mov_b32_e32 v73, v47
	v_pk_fma_f32 v[162:163], v[162:163], s[66:67], v[170:171] op_sel:[0,0,1] op_sel_hi:[1,0,0]
	v_pk_add_f32 v[170:171], v[164:165], v[172:173]
	v_pk_add_f32 v[164:165], v[164:165], v[172:173] neg_lo:[0,1] neg_hi:[0,1]
	v_pk_mul_f32 v[2:3], v[72:73], v[4:5] op_sel:[0,1] op_sel_hi:[1,0]
	v_xor_b32_e32 v173, 0x80000000, v164
	v_mov_b32_e32 v172, v165
	v_pk_add_f32 v[164:165], v[166:167], v[174:175]
	v_pk_add_f32 v[166:167], v[166:167], v[174:175] neg_lo:[0,1] neg_hi:[0,1]
	v_pk_mul_f32 v[14:15], v[34:35], v[4:5] op_sel:[0,1] op_sel_hi:[1,0]
	v_pk_mul_f32 v[174:175], v[166:167], s[36:37]
	v_pk_mul_f32 v[40:41], v[34:35], v[10:11] op_sel:[0,1] op_sel_hi:[1,0]
	v_pk_fma_f32 v[166:167], v[166:167], s[66:67], v[174:175] op_sel:[0,0,1] op_sel_hi:[1,0,0] neg_lo:[1,0,0] neg_hi:[1,0,0]
	v_pk_add_f32 v[174:175], v[190:191], v[194:195]
	v_pk_add_f32 v[190:191], v[190:191], v[194:195] neg_lo:[0,1] neg_hi:[0,1]
	v_pk_add_f32 v[194:195], v[192:193], v[148:149]
	v_pk_add_f32 v[148:149], v[192:193], v[148:149] neg_lo:[0,1] neg_hi:[0,1]
	v_pk_mul_f32 v[66:67], v[34:35], v[20:21] op_sel:[0,1] op_sel_hi:[1,0]
	v_xor_b32_e32 v193, 0x80000000, v148
	v_mov_b32_e32 v192, v149
	v_pk_add_f32 v[148:149], v[152:153], v[156:157]
	v_pk_add_f32 v[152:153], v[152:153], v[156:157] neg_lo:[0,1] neg_hi:[0,1]
	v_pk_add_f32 v[156:157], v[138:139], v[150:151]
	v_pk_add_f32 v[138:139], v[138:139], v[150:151] neg_lo:[0,1] neg_hi:[0,1]
	v_pk_mul_f32 v[82:83], v[34:35], v[26:27] op_sel:[0,1] op_sel_hi:[1,0]
	v_xor_b32_e32 v151, 0x80000000, v138
	v_mov_b32_e32 v150, v139
	v_pk_add_f32 v[138:139], v[158:159], v[140:141]
	v_pk_add_f32 v[140:141], v[158:159], v[140:141] neg_lo:[0,1] neg_hi:[0,1]
	v_pk_add_f32 v[158:159], v[154:155], v[134:135]
	v_pk_add_f32 v[134:135], v[154:155], v[134:135] neg_lo:[0,1] neg_hi:[0,1]
	v_pk_mul_f32 v[96:97], v[34:35], v[36:37] op_sel:[0,1] op_sel_hi:[1,0]
	v_xor_b32_e32 v155, 0x80000000, v134
	v_mov_b32_e32 v154, v135
	v_pk_add_f32 v[134:135], v[144:145], v[142:143]
	v_pk_add_f32 v[142:143], v[144:145], v[142:143] neg_lo:[0,1] neg_hi:[0,1]
	v_pk_add_f32 v[144:145], v[132:133], v[130:131]
	v_pk_add_f32 v[130:131], v[132:133], v[130:131] neg_lo:[0,1] neg_hi:[0,1]
	v_pk_mul_f32 v[110:111], v[34:35], v[48:49] op_sel:[0,1] op_sel_hi:[1,0]
	v_xor_b32_e32 v133, 0x80000000, v130
	v_mov_b32_e32 v132, v131
	v_pk_add_f32 v[130:131], v[136:137], v[176:177]
	v_pk_add_f32 v[136:137], v[136:137], v[176:177] neg_lo:[0,1] neg_hi:[0,1]
	v_pk_add_f32 v[176:177], v[182:183], v[178:179]
	v_pk_add_f32 v[178:179], v[182:183], v[178:179] neg_lo:[0,1] neg_hi:[0,1]
	v_pk_mul_f32 v[124:125], v[34:35], v[52:53] op_sel:[0,1] op_sel_hi:[1,0]
	v_xor_b32_e32 v183, 0x80000000, v178
	v_mov_b32_e32 v182, v179
	v_pk_add_f32 v[178:179], v[160:161], v[186:187]
	v_pk_add_f32 v[160:161], v[160:161], v[186:187] neg_lo:[0,1] neg_hi:[0,1]
	v_pk_add_f32 v[186:187], v[168:169], v[180:181]
	v_pk_add_f32 v[168:169], v[168:169], v[180:181] neg_lo:[0,1] neg_hi:[0,1]
	v_pk_fma_f32 v[2:3], v[46:47], v[4:5], v[2:3] op_sel_hi:[0,1,1]
	v_xor_b32_e32 v181, 0x80000000, v168
	v_mov_b32_e32 v180, v169
	v_pk_add_f32 v[168:169], v[188:189], v[170:171]
	v_pk_add_f32 v[170:171], v[188:189], v[170:171] neg_lo:[0,1] neg_hi:[0,1]
	v_pk_add_f32 v[188:189], v[184:185], v[164:165]
	v_pk_add_f32 v[164:165], v[184:185], v[164:165] neg_lo:[0,1] neg_hi:[0,1]
	v_pk_mul_f32 v[8:9], v[54:55], v[4:5] op_sel:[0,1] op_sel_hi:[1,0]
	v_xor_b32_e32 v185, 0x80000000, v164
	v_mov_b32_e32 v184, v165
	v_pk_add_f32 v[164:165], v[128:129], v[172:173]
	v_pk_add_f32 v[128:129], v[128:129], v[172:173] neg_lo:[0,1] neg_hi:[0,1]
	v_pk_add_f32 v[172:173], v[162:163], v[166:167]
	v_pk_add_f32 v[162:163], v[162:163], v[166:167] neg_lo:[0,1] neg_hi:[0,1]
	v_pk_fma_f32 v[14:15], v[30:31], v[4:5], v[14:15] op_sel_hi:[0,1,1]
	v_xor_b32_e32 v167, 0x80000000, v162
	v_mov_b32_e32 v166, v163
	v_pk_add_f32 v[162:163], v[174:175], v[194:195]
	v_pk_add_f32 v[174:175], v[174:175], v[194:195] neg_lo:[0,1] neg_hi:[0,1]
	v_pk_add_f32 v[194:195], v[190:191], v[192:193]
	v_pk_add_f32 v[190:191], v[190:191], v[192:193] neg_lo:[0,1] neg_hi:[0,1]
	v_pk_add_f32 v[192:193], v[148:149], v[156:157]
	v_pk_add_f32 v[148:149], v[148:149], v[156:157] neg_lo:[0,1] neg_hi:[0,1]
	v_pk_add_f32 v[156:157], v[152:153], v[150:151]
	v_pk_add_f32 v[150:151], v[152:153], v[150:151] neg_lo:[0,1] neg_hi:[0,1]
	v_pk_add_f32 v[152:153], v[138:139], v[158:159]
	v_pk_add_f32 v[138:139], v[138:139], v[158:159] neg_lo:[0,1] neg_hi:[0,1]
	v_pk_add_f32 v[158:159], v[140:141], v[154:155]
	v_pk_add_f32 v[140:141], v[140:141], v[154:155] neg_lo:[0,1] neg_hi:[0,1]
	v_pk_add_f32 v[154:155], v[134:135], v[144:145]
	v_pk_add_f32 v[134:135], v[134:135], v[144:145] neg_lo:[0,1] neg_hi:[0,1]
	v_pk_add_f32 v[144:145], v[142:143], v[132:133]
	v_pk_add_f32 v[132:133], v[142:143], v[132:133] neg_lo:[0,1] neg_hi:[0,1]
	v_pk_add_f32 v[142:143], v[130:131], v[176:177]
	v_pk_mul_f32 v[24:25], v[72:73], v[10:11] op_sel:[0,1] op_sel_hi:[1,0]
	v_pk_mul_f32 v[34:35], v[34:35], v[142:143] op_sel:[0,1] op_sel_hi:[1,0]
	v_pk_mul_f32 v[32:33], v[54:55], v[10:11] op_sel:[0,1] op_sel_hi:[1,0]
	v_pk_fma_f32 v[40:41], v[30:31], v[10:11], v[40:41] op_sel_hi:[0,1,1]
	v_pk_mul_f32 v[56:57], v[72:73], v[20:21] op_sel:[0,1] op_sel_hi:[1,0]
	v_pk_mul_f32 v[62:63], v[54:55], v[20:21] op_sel:[0,1] op_sel_hi:[1,0]
	v_pk_fma_f32 v[66:67], v[30:31], v[20:21], v[66:67] op_sel_hi:[0,1,1]
	v_pk_mul_f32 v[74:75], v[72:73], v[26:27] op_sel:[0,1] op_sel_hi:[1,0]
	v_pk_mul_f32 v[78:79], v[54:55], v[26:27] op_sel:[0,1] op_sel_hi:[1,0]
	v_pk_fma_f32 v[82:83], v[30:31], v[26:27], v[82:83] op_sel_hi:[0,1,1]
	v_pk_mul_f32 v[88:89], v[72:73], v[36:37] op_sel:[0,1] op_sel_hi:[1,0]
	v_pk_mul_f32 v[92:93], v[54:55], v[36:37] op_sel:[0,1] op_sel_hi:[1,0]
	v_pk_fma_f32 v[96:97], v[30:31], v[36:37], v[96:97] op_sel_hi:[0,1,1]
	v_pk_mul_f32 v[102:103], v[72:73], v[48:49] op_sel:[0,1] op_sel_hi:[1,0]
	v_pk_mul_f32 v[106:107], v[54:55], v[48:49] op_sel:[0,1] op_sel_hi:[1,0]
	v_pk_fma_f32 v[110:111], v[30:31], v[48:49], v[110:111] op_sel_hi:[0,1,1]
	v_pk_mul_f32 v[116:117], v[52:53], v[72:73] op_sel:[1,0] op_sel_hi:[0,1]
	v_pk_mul_f32 v[120:121], v[54:55], v[52:53] op_sel:[0,1] op_sel_hi:[1,0]
	v_pk_fma_f32 v[124:125], v[30:31], v[52:53], v[124:125] op_sel_hi:[0,1,1]
	v_pk_add_f32 v[130:131], v[130:131], v[176:177] neg_lo:[0,1] neg_hi:[0,1]
	v_pk_add_f32 v[176:177], v[136:137], v[182:183]
	v_pk_add_f32 v[136:137], v[136:137], v[182:183] neg_lo:[0,1] neg_hi:[0,1]
	v_pk_add_f32 v[182:183], v[178:179], v[186:187]
	v_pk_add_f32 v[178:179], v[178:179], v[186:187] neg_lo:[0,1] neg_hi:[0,1]
	v_pk_add_f32 v[186:187], v[160:161], v[180:181]
	v_pk_add_f32 v[160:161], v[160:161], v[180:181] neg_lo:[0,1] neg_hi:[0,1]
	v_pk_add_f32 v[180:181], v[168:169], v[188:189]
	v_pk_fma_f32 v[30:31], v[30:31], v[142:143], v[34:35] op_sel_hi:[0,1,1]
	v_pk_mul_f32 v[34:35], v[54:55], v[152:153] op_sel:[0,1] op_sel_hi:[1,0]
	v_xor_b32_e32 v6, 0x80000000, v3
	v_pk_fma_f32 v[8:9], v[44:45], v[4:5], v[8:9] op_sel_hi:[0,1,1]
	v_pk_fma_f32 v[24:25], v[46:47], v[10:11], v[24:25] op_sel_hi:[0,1,1]
	v_pk_fma_f32 v[32:33], v[44:45], v[10:11], v[32:33] op_sel_hi:[0,1,1]
	v_pk_fma_f32 v[56:57], v[46:47], v[20:21], v[56:57] op_sel_hi:[0,1,1]
	v_pk_fma_f32 v[62:63], v[44:45], v[20:21], v[62:63] op_sel_hi:[0,1,1]
	v_pk_fma_f32 v[74:75], v[46:47], v[26:27], v[74:75] op_sel_hi:[0,1,1]
	v_pk_fma_f32 v[78:79], v[44:45], v[26:27], v[78:79] op_sel_hi:[0,1,1]
	v_pk_fma_f32 v[88:89], v[46:47], v[36:37], v[88:89] op_sel_hi:[0,1,1]
	v_pk_fma_f32 v[92:93], v[44:45], v[36:37], v[92:93] op_sel_hi:[0,1,1]
	v_pk_fma_f32 v[102:103], v[46:47], v[48:49], v[102:103] op_sel_hi:[0,1,1]
	v_pk_fma_f32 v[106:107], v[44:45], v[48:49], v[106:107] op_sel_hi:[0,1,1]
	v_xor_b32_e32 v114, 0x80000000, v49
	v_pk_fma_f32 v[116:117], v[52:53], v[46:47], v[116:117] op_sel_hi:[1,0,1]
	v_pk_fma_f32 v[120:121], v[44:45], v[52:53], v[120:121] op_sel_hi:[0,1,1]
	v_mov_b32_e32 v115, v49
	v_mov_b32_e32 v7, v3
	v_pk_add_f32 v[168:169], v[168:169], v[188:189] neg_lo:[0,1] neg_hi:[0,1]
	v_pk_add_f32 v[188:189], v[170:171], v[184:185]
	v_pk_add_f32 v[170:171], v[170:171], v[184:185] neg_lo:[0,1] neg_hi:[0,1]
	v_pk_add_f32 v[184:185], v[164:165], v[172:173]
	v_pk_add_f32 v[164:165], v[164:165], v[172:173] neg_lo:[0,1] neg_hi:[0,1]
	v_pk_add_f32 v[172:173], v[128:129], v[166:167]
	v_pk_add_f32 v[128:129], v[128:129], v[166:167] neg_lo:[0,1] neg_hi:[0,1]
	v_pk_fma_f32 v[34:35], v[44:45], v[152:153], v[34:35] op_sel_hi:[0,1,1]
	v_pk_mul_f32 v[44:45], v[72:73], v[180:181] op_sel:[0,1] op_sel_hi:[1,0]
	v_xor_b32_e32 v12, 0x80000000, v9
	v_xor_b32_e32 v16, 0x80000000, v15
	v_xor_b32_e32 v22, 0x80000000, v5
	v_xor_b32_e32 v28, 0x80000000, v25
	v_xor_b32_e32 v38, 0x80000000, v33
	v_xor_b32_e32 v42, 0x80000000, v41
	v_xor_b32_e32 v50, 0x80000000, v11
	v_xor_b32_e32 v60, 0x80000000, v57
	v_xor_b32_e32 v64, 0x80000000, v63
	v_xor_b32_e32 v68, 0x80000000, v67
	v_xor_b32_e32 v70, 0x80000000, v21
	v_xor_b32_e32 v76, 0x80000000, v75
	v_xor_b32_e32 v80, 0x80000000, v79
	v_xor_b32_e32 v84, 0x80000000, v83
	v_xor_b32_e32 v86, 0x80000000, v27
	v_xor_b32_e32 v90, 0x80000000, v89
	v_xor_b32_e32 v94, 0x80000000, v93
	v_xor_b32_e32 v98, 0x80000000, v97
	v_xor_b32_e32 v100, 0x80000000, v37
	v_xor_b32_e32 v104, 0x80000000, v103
	v_xor_b32_e32 v108, 0x80000000, v107
	v_xor_b32_e32 v112, 0x80000000, v111
	v_xor_b32_e32 v118, 0x80000000, v117
	v_xor_b32_e32 v122, 0x80000000, v121
	v_xor_b32_e32 v126, 0x80000000, v125
	v_mov_b32_e32 v127, v125
	v_mov_b32_e32 v123, v121
	v_mov_b32_e32 v119, v117
	v_mov_b32_e32 v113, v111
	v_mov_b32_e32 v109, v107
	v_mov_b32_e32 v105, v103
	v_mov_b32_e32 v101, v37
	v_mov_b32_e32 v99, v97
	v_mov_b32_e32 v95, v93
	v_mov_b32_e32 v91, v89
	v_mov_b32_e32 v87, v27
	v_mov_b32_e32 v85, v83
	v_mov_b32_e32 v81, v79
	v_mov_b32_e32 v77, v75
	v_mov_b32_e32 v71, v21
	v_mov_b32_e32 v69, v67
	v_mov_b32_e32 v65, v63
	v_mov_b32_e32 v61, v57
	v_mov_b32_e32 v51, v11
	v_mov_b32_e32 v43, v41
	v_mov_b32_e32 v39, v33
	v_mov_b32_e32 v29, v25
	v_mov_b32_e32 v23, v5
	v_mov_b32_e32 v17, v15
	v_mov_b32_e32 v13, v9
	v_pk_fma_f32 v[44:45], v[46:47], v[180:181], v[44:45] op_sel_hi:[0,1,1]
	v_pk_mul_f32 v[46:47], v[58:59], v[192:193] op_sel:[0,1] op_sel_hi:[1,0]
	v_pk_mul_f32 v[72:73], v[114:115], v[194:195] op_sel:[0,1] op_sel_hi:[1,0]
	v_pk_mul_f32 v[6:7], v[128:129], v[6:7] op_sel:[1,0] op_sel_hi:[0,1]
	v_pk_fma_f32 v[46:47], v[52:53], v[192:193], v[46:47] op_sel_hi:[0,1,1]
	v_pk_mul_f32 v[52:53], v[126:127], v[182:183] op_sel:[0,1] op_sel_hi:[1,0]
	v_pk_mul_f32 v[54:55], v[122:123], v[154:155] op_sel:[0,1] op_sel_hi:[1,0]
	v_pk_mul_f32 v[58:59], v[118:119], v[184:185] op_sel:[0,1] op_sel_hi:[1,0]
	v_pk_fma_f32 v[48:49], v[48:49], v[194:195], v[72:73] op_sel_hi:[0,1,1]
	v_pk_mul_f32 v[72:73], v[112:113], v[176:177] op_sel:[0,1] op_sel_hi:[1,0]
	v_pk_mul_f32 v[108:109], v[108:109], v[158:159] op_sel:[0,1] op_sel_hi:[1,0]
	v_pk_mul_f32 v[104:105], v[104:105], v[188:189] op_sel:[0,1] op_sel_hi:[1,0]
	v_pk_mul_f32 v[100:101], v[100:101], v[156:157] op_sel:[0,1] op_sel_hi:[1,0]
	v_pk_mul_f32 v[98:99], v[98:99], v[186:187] op_sel:[0,1] op_sel_hi:[1,0]
	v_pk_mul_f32 v[94:95], v[94:95], v[144:145] op_sel:[0,1] op_sel_hi:[1,0]
	v_pk_mul_f32 v[90:91], v[90:91], v[172:173] op_sel:[0,1] op_sel_hi:[1,0]
	v_pk_mul_f32 v[86:87], v[174:175], v[86:87] op_sel:[1,0] op_sel_hi:[0,1]
	v_pk_mul_f32 v[84:85], v[130:131], v[84:85] op_sel:[1,0] op_sel_hi:[0,1]
	v_pk_mul_f32 v[80:81], v[138:139], v[80:81] op_sel:[1,0] op_sel_hi:[0,1]
	v_pk_mul_f32 v[76:77], v[168:169], v[76:77] op_sel:[1,0] op_sel_hi:[0,1]
	v_pk_mul_f32 v[70:71], v[148:149], v[70:71] op_sel:[1,0] op_sel_hi:[0,1]
	v_pk_mul_f32 v[68:69], v[178:179], v[68:69] op_sel:[1,0] op_sel_hi:[0,1]
	v_pk_mul_f32 v[64:65], v[134:135], v[64:65] op_sel:[1,0] op_sel_hi:[0,1]
	v_pk_mul_f32 v[60:61], v[164:165], v[60:61] op_sel:[1,0] op_sel_hi:[0,1]
	v_pk_mul_f32 v[50:51], v[190:191], v[50:51] op_sel:[1,0] op_sel_hi:[0,1]
	v_pk_mul_f32 v[42:43], v[136:137], v[42:43] op_sel:[1,0] op_sel_hi:[0,1]
	v_pk_mul_f32 v[38:39], v[140:141], v[38:39] op_sel:[1,0] op_sel_hi:[0,1]
	v_pk_mul_f32 v[28:29], v[170:171], v[28:29] op_sel:[1,0] op_sel_hi:[0,1]
	v_pk_mul_f32 v[22:23], v[150:151], v[22:23] op_sel:[1,0] op_sel_hi:[0,1]
	v_pk_mul_f32 v[16:17], v[160:161], v[16:17] op_sel:[1,0] op_sel_hi:[0,1]
	v_pk_mul_f32 v[12:13], v[132:133], v[12:13] op_sel:[1,0] op_sel_hi:[0,1]
	v_pk_fma_f32 v[2:3], v[128:129], v[2:3], v[6:7] op_sel_hi:[1,0,1]
	v_pk_fma_f32 v[52:53], v[124:125], v[182:183], v[52:53] op_sel_hi:[0,1,1]
	v_pk_fma_f32 v[54:55], v[120:121], v[154:155], v[54:55] op_sel_hi:[0,1,1]
	v_pk_fma_f32 v[58:59], v[116:117], v[184:185], v[58:59] op_sel_hi:[0,1,1]
	v_pk_fma_f32 v[72:73], v[110:111], v[176:177], v[72:73] op_sel_hi:[0,1,1]
	v_pk_fma_f32 v[106:107], v[106:107], v[158:159], v[108:109] op_sel_hi:[0,1,1]
	v_pk_fma_f32 v[102:103], v[102:103], v[188:189], v[104:105] op_sel_hi:[0,1,1]
	v_pk_fma_f32 v[36:37], v[36:37], v[156:157], v[100:101] op_sel_hi:[0,1,1]
	v_pk_fma_f32 v[96:97], v[96:97], v[186:187], v[98:99] op_sel_hi:[0,1,1]
	v_pk_fma_f32 v[92:93], v[92:93], v[144:145], v[94:95] op_sel_hi:[0,1,1]
	v_pk_fma_f32 v[88:89], v[88:89], v[172:173], v[90:91] op_sel_hi:[0,1,1]
	v_pk_fma_f32 v[26:27], v[174:175], v[26:27], v[86:87] op_sel_hi:[1,0,1]
	v_pk_fma_f32 v[82:83], v[130:131], v[82:83], v[84:85] op_sel_hi:[1,0,1]
	v_pk_fma_f32 v[78:79], v[138:139], v[78:79], v[80:81] op_sel_hi:[1,0,1]
	v_pk_fma_f32 v[74:75], v[168:169], v[74:75], v[76:77] op_sel_hi:[1,0,1]
	v_pk_fma_f32 v[20:21], v[148:149], v[20:21], v[70:71] op_sel_hi:[1,0,1]
	v_pk_fma_f32 v[66:67], v[178:179], v[66:67], v[68:69] op_sel_hi:[1,0,1]
	v_pk_fma_f32 v[62:63], v[134:135], v[62:63], v[64:65] op_sel_hi:[1,0,1]
	v_pk_fma_f32 v[56:57], v[164:165], v[56:57], v[60:61] op_sel_hi:[1,0,1]
	v_pk_fma_f32 v[10:11], v[190:191], v[10:11], v[50:51] op_sel_hi:[1,0,1]
	v_pk_fma_f32 v[40:41], v[136:137], v[40:41], v[42:43] op_sel_hi:[1,0,1]
	v_pk_fma_f32 v[32:33], v[140:141], v[32:33], v[38:39] op_sel_hi:[1,0,1]
	v_pk_fma_f32 v[24:25], v[170:171], v[24:25], v[28:29] op_sel_hi:[1,0,1]
	v_pk_fma_f32 v[4:5], v[150:151], v[4:5], v[22:23] op_sel_hi:[1,0,1]
	v_pk_fma_f32 v[14:15], v[160:161], v[14:15], v[16:17] op_sel_hi:[1,0,1]
	v_pk_fma_f32 v[8:9], v[132:133], v[8:9], v[12:13] op_sel_hi:[1,0,1]
	ds_write_b64 v18, v[162:163]
	ds_write_b64 v18, v[26:27] offset:2112
	ds_write_b64 v18, v[48:49] offset:4224
	ds_write_b64 v18, v[10:11] offset:6336
	ds_write_b64 v18, v[46:47] offset:8448
	ds_write_b64 v18, v[20:21] offset:10560
	ds_write_b64 v18, v[36:37] offset:12672
	ds_write_b64 v18, v[4:5] offset:14784
	ds_write_b64 v18, v[34:35] offset:16896
	ds_write_b64 v18, v[78:79] offset:19008
	ds_write_b64 v18, v[106:107] offset:21120
	ds_write_b64 v18, v[32:33] offset:23232
	ds_write_b64 v18, v[54:55] offset:25344
	ds_write_b64 v18, v[62:63] offset:27456
	ds_write_b64 v18, v[92:93] offset:29568
	ds_write_b64 v18, v[8:9] offset:31680
	ds_write_b64 v18, v[30:31] offset:33792
	ds_write_b64 v18, v[82:83] offset:35904
	ds_write_b64 v18, v[72:73] offset:38016
	ds_write_b64 v18, v[40:41] offset:40128
	ds_write_b64 v18, v[52:53] offset:42240
	ds_write_b64 v18, v[66:67] offset:44352
	ds_write_b64 v18, v[96:97] offset:46464
	ds_write_b64 v18, v[14:15] offset:48576
	ds_write_b64 v18, v[44:45] offset:50688
	ds_write_b64 v18, v[74:75] offset:52800
	ds_write_b64 v18, v[102:103] offset:54912
	ds_write_b64 v18, v[24:25] offset:57024
	ds_write_b64 v18, v[58:59] offset:59136
	ds_write_b64 v18, v[56:57] offset:61248
	ds_write_b64 v18, v[88:89] offset:63360
	ds_write_b64 v18, v[2:3] offset:65472
	v_mov_b32_e32 v3, v210
	s_waitcnt lgkmcnt(0)
	s_barrier
	s_add_i32 s64, s62, s48
	v_and_b32_e32 v5, 15, v3
	v_cvt_f32_ubyte0_e32 v2, v5
	v_mul_f32_e32 v4, 0x3b800000, v2
	v_sin_f32_e32 v2, v4
	v_cos_f32_e32 v4, v4
	v_lshlrev_b32_e32 v64, 3, v5
	v_lshlrev_b32_e32 v18, 4, v3
	v_xor_b32_e32 v5, 0x80000000, v2
	v_mov_b32_e32 v3, v5
	v_pk_mul_f32 v[6:7], v[4:5], v[2:3] op_sel:[1,0] op_sel_hi:[0,1]
	v_pk_fma_f32 v[6:7], v[4:5], v[4:5], v[6:7] op_sel_hi:[1,0,1]
	s_ashr_i32 s65, s64, 31
	v_xor_b32_e32 v12, 0x80000000, v7
	v_mov_b32_e32 v13, v7
	v_pk_mul_f32 v[10:11], v[6:7], v[12:13] op_sel:[1,0] op_sel_hi:[0,1]
	v_pk_fma_f32 v[10:11], v[6:7], v[6:7], v[10:11] op_sel_hi:[1,0,1]
	v_pk_mul_f32 v[8:9], v[2:3], v[6:7] op_sel:[0,1] op_sel_hi:[1,0]
	v_xor_b32_e32 v14, 0x80000000, v11
	v_mov_b32_e32 v15, v11
	v_pk_mul_f32 v[32:33], v[10:11], v[14:15] op_sel:[1,0] op_sel_hi:[0,1]
	v_pk_fma_f32 v[32:33], v[10:11], v[10:11], v[32:33] op_sel_hi:[1,0,1]
	v_pk_mul_f32 v[16:17], v[2:3], v[10:11] op_sel:[0,1] op_sel_hi:[1,0]
	v_pk_mul_f32 v[48:49], v[14:15], v[32:33] op_sel:[0,1] op_sel_hi:[1,0]
	v_pk_mul_f32 v[36:37], v[2:3], v[32:33] op_sel:[0,1] op_sel_hi:[1,0]
	v_pk_fma_f32 v[48:49], v[10:11], v[32:33], v[48:49] op_sel_hi:[0,1,1]
	v_pk_mul_f32 v[52:53], v[2:3], v[48:49] op_sel:[0,1] op_sel_hi:[1,0]
	v_pk_fma_f32 v[8:9], v[4:5], v[6:7], v[8:9] op_sel_hi:[0,1,1]
	v_pk_fma_f32 v[16:17], v[4:5], v[10:11], v[16:17] op_sel_hi:[0,1,1]
	v_pk_fma_f32 v[36:37], v[4:5], v[32:33], v[36:37] op_sel_hi:[0,1,1]
	v_pk_fma_f32 v[52:53], v[4:5], v[48:49], v[52:53] op_sel_hi:[0,1,1]
	v_and_b32_e32 v5, 0xffffff00, v18
	v_lshlrev_b32_e32 v18, 3, v5
	v_add3_u32 v18, 0, v64, v18
	v_ashrrev_i32_e32 v64, 2, v5
	v_add_u32_e32 v106, v18, v64
	ds_read2_b64 v[64:67], v106 offset1:16
	ds_read2_b64 v[68:71], v106 offset0:33 offset1:49
	ds_read2_b64 v[72:75], v106 offset0:66 offset1:82
	ds_read2_b64 v[76:79], v106 offset0:132 offset1:148
	ds_read2_b64 v[80:83], v106 offset0:99 offset1:115
	ds_read2_b64 v[84:87], v106 offset0:165 offset1:181
	ds_read2_b64 v[88:91], v106 offset0:198 offset1:214
	ds_read2_b64 v[92:95], v106 offset0:231 offset1:247
	s_waitcnt lgkmcnt(4)
	v_pk_add_f32 v[96:97], v[64:65], v[76:77]
	v_pk_add_f32 v[64:65], v[64:65], v[76:77] neg_lo:[0,1] neg_hi:[0,1]
	v_pk_add_f32 v[76:77], v[66:67], v[78:79]
	v_pk_add_f32 v[66:67], v[66:67], v[78:79] neg_lo:[0,1] neg_hi:[0,1]
	s_waitcnt lgkmcnt(1)
	v_pk_add_f32 v[98:99], v[74:75], v[90:91]
	v_pk_mul_f32 v[78:79], v[66:67], s[18:19]
	v_pk_add_f32 v[74:75], v[74:75], v[90:91] neg_lo:[0,1] neg_hi:[0,1]
	v_pk_fma_f32 v[66:67], v[66:67], s[16:17], v[78:79] op_sel:[0,0,1] op_sel_hi:[1,0,0]
	v_pk_add_f32 v[78:79], v[68:69], v[84:85]
	v_pk_add_f32 v[68:69], v[68:69], v[84:85] neg_lo:[0,1] neg_hi:[0,1]
	v_pk_mul_f32 v[90:91], v[74:75], s[40:41]
	v_pk_mul_f32 v[84:85], v[68:69], s[36:37]
	v_pk_fma_f32 v[74:75], v[74:75], s[68:69], v[90:91] op_sel:[0,0,1] op_sel_hi:[1,0,0] neg_lo:[1,0,0] neg_hi:[1,0,0]
	v_pk_fma_f32 v[68:69], v[68:69], s[66:67], v[84:85] op_sel:[0,0,1] op_sel_hi:[1,0,0]
	v_pk_add_f32 v[84:85], v[70:71], v[86:87]
	v_pk_add_f32 v[70:71], v[70:71], v[86:87] neg_lo:[0,1] neg_hi:[0,1]
	s_waitcnt lgkmcnt(0)
	v_pk_add_f32 v[90:91], v[80:81], v[92:93]
	v_pk_add_f32 v[80:81], v[80:81], v[92:93] neg_lo:[0,1] neg_hi:[0,1]
	v_pk_mul_f32 v[86:87], v[70:71], s[40:41]
	v_pk_mul_f32 v[92:93], v[80:81], s[36:37]
	v_pk_fma_f32 v[70:71], v[70:71], s[68:69], v[86:87] op_sel:[0,0,1] op_sel_hi:[1,0,0]
	v_pk_add_f32 v[86:87], v[72:73], v[88:89]
	v_pk_add_f32 v[72:73], v[72:73], v[88:89] neg_lo:[0,1] neg_hi:[0,1]
	v_pk_fma_f32 v[80:81], v[80:81], s[66:67], v[92:93] op_sel:[0,0,1] op_sel_hi:[1,0,0] neg_lo:[1,0,0] neg_hi:[1,0,0]
	v_pk_add_f32 v[92:93], v[82:83], v[94:95]
	v_pk_add_f32 v[82:83], v[82:83], v[94:95] neg_lo:[0,1] neg_hi:[0,1]
	v_xor_b32_e32 v89, 0x80000000, v72
	v_pk_mul_f32 v[94:95], v[82:83], s[18:19]
	v_mov_b32_e32 v88, v73
	v_pk_fma_f32 v[82:83], v[82:83], s[16:17], v[94:95] op_sel:[0,0,1] op_sel_hi:[1,0,0] neg_lo:[1,0,0] neg_hi:[1,0,0]
	v_pk_add_f32 v[94:95], v[96:97], v[86:87]
	v_pk_add_f32 v[86:87], v[96:97], v[86:87] neg_lo:[0,1] neg_hi:[0,1]
	v_pk_add_f32 v[96:97], v[76:77], v[98:99]
	v_pk_add_f32 v[76:77], v[76:77], v[98:99] neg_lo:[0,1] neg_hi:[0,1]
	v_pk_add_f32 v[100:101], v[84:85], v[92:93]
	v_pk_add_f32 v[84:85], v[84:85], v[92:93] neg_lo:[0,1] neg_hi:[0,1]
	v_pk_add_f32 v[72:73], v[64:65], v[88:89]
	v_pk_add_f32 v[64:65], v[64:65], v[88:89] neg_lo:[0,1] neg_hi:[0,1]
	v_pk_add_f32 v[88:89], v[66:67], v[74:75]
	v_pk_add_f32 v[66:67], v[66:67], v[74:75] neg_lo:[0,1] neg_hi:[0,1]
	v_pk_mul_f32 v[98:99], v[76:77], s[36:37]
	v_pk_mul_f32 v[92:93], v[84:85], s[36:37]
	v_pk_mul_f32 v[74:75], v[66:67], s[36:37]
	v_pk_fma_f32 v[76:77], v[76:77], s[66:67], v[98:99] op_sel:[0,0,1] op_sel_hi:[1,0,0]
	v_pk_add_f32 v[98:99], v[78:79], v[90:91]
	v_pk_add_f32 v[78:79], v[78:79], v[90:91] neg_lo:[0,1] neg_hi:[0,1]
	v_pk_fma_f32 v[84:85], v[84:85], s[66:67], v[92:93] op_sel:[0,0,1] op_sel_hi:[1,0,0] neg_lo:[1,0,0] neg_hi:[1,0,0]
	v_pk_fma_f32 v[66:67], v[66:67], s[66:67], v[74:75] op_sel:[0,0,1] op_sel_hi:[1,0,0]
	v_pk_add_f32 v[74:75], v[68:69], v[80:81]
	v_pk_add_f32 v[92:93], v[70:71], v[82:83]
	v_pk_add_f32 v[70:71], v[70:71], v[82:83] neg_lo:[0,1] neg_hi:[0,1]
	v_xor_b32_e32 v91, 0x80000000, v78
	v_pk_add_f32 v[68:69], v[68:69], v[80:81] neg_lo:[0,1] neg_hi:[0,1]
	v_pk_mul_f32 v[82:83], v[70:71], s[36:37]
	v_mov_b32_e32 v90, v79
	v_pk_add_f32 v[102:103], v[72:73], v[74:75]
	v_pk_add_f32 v[72:73], v[72:73], v[74:75] neg_lo:[0,1] neg_hi:[0,1]
	v_pk_add_f32 v[74:75], v[88:89], v[92:93]
	v_pk_add_f32 v[88:89], v[88:89], v[92:93] neg_lo:[0,1] neg_hi:[0,1]
	v_xor_b32_e32 v20, 0x80000000, v9
	v_mov_b32_e32 v21, v9
	v_pk_mul_f32 v[24:25], v[12:13], v[10:11] op_sel:[0,1] op_sel_hi:[1,0]
	v_xor_b32_e32 v81, 0x80000000, v68
	v_pk_fma_f32 v[70:71], v[70:71], s[66:67], v[82:83] op_sel:[0,0,1] op_sel_hi:[1,0,0] neg_lo:[1,0,0] neg_hi:[1,0,0]
	v_pk_add_f32 v[78:79], v[86:87], v[90:91]
	v_pk_add_f32 v[86:87], v[86:87], v[90:91] neg_lo:[0,1] neg_hi:[0,1]
	v_pk_add_f32 v[90:91], v[76:77], v[84:85]
	v_pk_add_f32 v[76:77], v[76:77], v[84:85] neg_lo:[0,1] neg_hi:[0,1]
	v_xor_b32_e32 v93, 0x80000000, v88
	v_mov_b32_e32 v80, v69
	v_mov_b32_e32 v92, v89
	v_xor_b32_e32 v22, 0x80000000, v17
	v_mov_b32_e32 v23, v17
	v_pk_fma_f32 v[24:25], v[6:7], v[10:11], v[24:25] op_sel_hi:[0,1,1]
	v_pk_mul_f32 v[28:29], v[10:11], v[20:21] op_sel:[1,0] op_sel_hi:[0,1]
	v_xor_b32_e32 v85, 0x80000000, v76
	v_pk_add_f32 v[68:69], v[64:65], v[80:81]
	v_pk_add_f32 v[64:65], v[64:65], v[80:81] neg_lo:[0,1] neg_hi:[0,1]
	v_pk_add_f32 v[80:81], v[66:67], v[70:71]
	v_pk_add_f32 v[66:67], v[66:67], v[70:71] neg_lo:[0,1] neg_hi:[0,1]
	v_mov_b32_e32 v84, v77
	v_pk_add_f32 v[88:89], v[72:73], v[92:93]
	v_xor_b32_e32 v26, 0x80000000, v25
	v_mov_b32_e32 v27, v25
	v_pk_fma_f32 v[28:29], v[10:11], v[8:9], v[28:29] op_sel_hi:[1,0,1]
	v_xor_b32_e32 v71, 0x80000000, v66
	v_pk_add_f32 v[76:77], v[86:87], v[84:85]
	v_pk_add_f32 v[72:73], v[72:73], v[92:93] neg_lo:[0,1] neg_hi:[0,1]
	v_mov_b32_e32 v70, v67
	v_pk_mul_f32 v[92:93], v[22:23], v[88:89] op_sel:[0,1] op_sel_hi:[1,0]
	v_xor_b32_e32 v30, 0x80000000, v29
	v_mov_b32_e32 v31, v29
	v_pk_add_f32 v[82:83], v[94:95], v[98:99]
	v_pk_add_f32 v[94:95], v[94:95], v[98:99] neg_lo:[0,1] neg_hi:[0,1]
	v_pk_add_f32 v[98:99], v[96:97], v[100:101]
	v_pk_add_f32 v[66:67], v[64:65], v[70:71]
	v_pk_fma_f32 v[88:89], v[16:17], v[88:89], v[92:93] op_sel_hi:[0,1,1]
	v_pk_mul_f32 v[92:93], v[26:27], v[76:77] op_sel:[0,1] op_sel_hi:[1,0]
	v_xor_b32_e32 v34, 0x80000000, v33
	v_mov_b32_e32 v35, v33
	v_pk_mul_f32 v[40:41], v[12:13], v[32:33] op_sel:[0,1] op_sel_hi:[1,0]
	v_pk_add_f32 v[104:105], v[82:83], v[98:99]
	v_pk_add_f32 v[82:83], v[82:83], v[98:99] neg_lo:[0,1] neg_hi:[0,1]
	v_pk_fma_f32 v[76:77], v[24:25], v[76:77], v[92:93] op_sel_hi:[0,1,1]
	v_pk_mul_f32 v[92:93], v[30:31], v[66:67] op_sel:[0,1] op_sel_hi:[1,0]
	v_xor_b32_e32 v38, 0x80000000, v37
	v_mov_b32_e32 v39, v37
	v_pk_fma_f32 v[40:41], v[6:7], v[32:33], v[40:41] op_sel_hi:[0,1,1]
	v_pk_mul_f32 v[44:45], v[20:21], v[32:33] op_sel:[0,1] op_sel_hi:[1,0]
	v_pk_add_f32 v[84:85], v[86:87], v[84:85] neg_lo:[0,1] neg_hi:[0,1]
	v_pk_add_f32 v[86:87], v[102:103], v[74:75]
	v_pk_add_f32 v[74:75], v[102:103], v[74:75] neg_lo:[0,1] neg_hi:[0,1]
	v_pk_fma_f32 v[66:67], v[28:29], v[66:67], v[92:93] op_sel_hi:[0,1,1]
	v_pk_mul_f32 v[92:93], v[34:35], v[82:83] op_sel:[0,1] op_sel_hi:[1,0]
	v_xor_b32_e32 v42, 0x80000000, v41
	v_mov_b32_e32 v43, v41
	v_pk_fma_f32 v[44:45], v[8:9], v[32:33], v[44:45] op_sel_hi:[0,1,1]
	v_pk_add_f32 v[96:97], v[96:97], v[100:101] neg_lo:[0,1] neg_hi:[0,1]
	v_pk_add_f32 v[98:99], v[78:79], v[90:91]
	v_pk_add_f32 v[78:79], v[78:79], v[90:91] neg_lo:[0,1] neg_hi:[0,1]
	v_pk_fma_f32 v[82:83], v[32:33], v[82:83], v[92:93] op_sel_hi:[0,1,1]
	v_pk_mul_f32 v[92:93], v[38:39], v[74:75] op_sel:[0,1] op_sel_hi:[1,0]
	v_xor_b32_e32 v46, 0x80000000, v45
	v_mov_b32_e32 v47, v45
	v_xor_b32_e32 v101, 0x80000000, v96
	v_mov_b32_e32 v100, v97
	v_pk_add_f32 v[90:91], v[68:69], v[80:81]
	v_pk_add_f32 v[68:69], v[68:69], v[80:81] neg_lo:[0,1] neg_hi:[0,1]
	v_pk_fma_f32 v[74:75], v[36:37], v[74:75], v[92:93] op_sel_hi:[0,1,1]
	v_pk_mul_f32 v[92:93], v[42:43], v[78:79] op_sel:[0,1] op_sel_hi:[1,0]
	v_xor_b32_e32 v50, 0x80000000, v49
	v_mov_b32_e32 v51, v49
	v_pk_mul_f32 v[56:57], v[12:13], v[48:49] op_sel:[0,1] op_sel_hi:[1,0]
	v_pk_add_f32 v[96:97], v[94:95], v[100:101]
	v_pk_add_f32 v[94:95], v[94:95], v[100:101] neg_lo:[0,1] neg_hi:[0,1]
	v_pk_fma_f32 v[78:79], v[40:41], v[78:79], v[92:93] op_sel_hi:[0,1,1]
	v_pk_mul_f32 v[92:93], v[46:47], v[68:69] op_sel:[0,1] op_sel_hi:[1,0]
	v_xor_b32_e32 v54, 0x80000000, v53
	v_mov_b32_e32 v55, v53
	v_pk_fma_f32 v[56:57], v[6:7], v[48:49], v[56:57] op_sel_hi:[0,1,1]
	v_pk_mul_f32 v[60:61], v[20:21], v[48:49] op_sel:[0,1] op_sel_hi:[1,0]
	v_pk_fma_f32 v[68:69], v[44:45], v[68:69], v[92:93] op_sel_hi:[0,1,1]
	v_pk_mul_f32 v[92:93], v[50:51], v[94:95] op_sel:[0,1] op_sel_hi:[1,0]
	v_xor_b32_e32 v58, 0x80000000, v57
	v_mov_b32_e32 v59, v57
	v_pk_fma_f32 v[60:61], v[8:9], v[48:49], v[60:61] op_sel_hi:[0,1,1]
	v_pk_add_f32 v[64:65], v[64:65], v[70:71] neg_lo:[0,1] neg_hi:[0,1]
	v_pk_mul_f32 v[70:71], v[2:3], v[86:87] op_sel:[0,1] op_sel_hi:[1,0]
	v_pk_fma_f32 v[92:93], v[48:49], v[94:95], v[92:93] op_sel_hi:[0,1,1]
	v_pk_mul_f32 v[94:95], v[54:55], v[72:73] op_sel:[0,1] op_sel_hi:[1,0]
	v_xor_b32_e32 v62, 0x80000000, v61
	v_mov_b32_e32 v63, v61
	v_pk_fma_f32 v[70:71], v[4:5], v[86:87], v[70:71] op_sel_hi:[0,1,1]
	v_pk_mul_f32 v[86:87], v[20:21], v[90:91] op_sel:[0,1] op_sel_hi:[1,0]
	v_pk_fma_f32 v[72:73], v[52:53], v[72:73], v[94:95] op_sel_hi:[0,1,1]
	v_pk_mul_f32 v[94:95], v[58:59], v[84:85] op_sel:[0,1] op_sel_hi:[1,0]
	v_add_u32_e32 v5, 0x2000, v5
	v_pk_mul_f32 v[80:81], v[12:13], v[98:99] op_sel:[0,1] op_sel_hi:[1,0]
	v_pk_fma_f32 v[86:87], v[8:9], v[90:91], v[86:87] op_sel_hi:[0,1,1]
	v_pk_mul_f32 v[90:91], v[14:15], v[96:97] op_sel:[0,1] op_sel_hi:[1,0]
	v_pk_fma_f32 v[84:85], v[56:57], v[84:85], v[94:95] op_sel_hi:[0,1,1]
	v_pk_mul_f32 v[94:95], v[62:63], v[64:65] op_sel:[0,1] op_sel_hi:[1,0]
	v_ashrrev_i32_e32 v5, 2, v5
	v_pk_fma_f32 v[80:81], v[6:7], v[98:99], v[80:81] op_sel_hi:[0,1,1]
	v_pk_fma_f32 v[90:91], v[10:11], v[96:97], v[90:91] op_sel_hi:[0,1,1]
	v_pk_fma_f32 v[64:65], v[60:61], v[64:65], v[94:95] op_sel_hi:[0,1,1]
	ds_write2_b64 v106, v[104:105], v[82:83] offset1:16
	ds_write2_b64 v106, v[90:91], v[92:93] offset0:33 offset1:49
	ds_write2_b64 v106, v[80:81], v[78:79] offset0:66 offset1:82
	ds_write2_b64 v106, v[76:77], v[84:85] offset0:99 offset1:115
	ds_write2_b64 v106, v[70:71], v[74:75] offset0:132 offset1:148
	ds_write2_b64 v106, v[88:89], v[72:73] offset0:165 offset1:181
	ds_write2_b64 v106, v[86:87], v[68:69] offset0:198 offset1:214
	ds_write2_b64 v106, v[66:67], v[64:65] offset0:231 offset1:247
	v_add3_u32 v18, v18, v5, s5
	ds_read2_b64 v[64:67], v18 offset1:16
	ds_read2_b64 v[68:71], v18 offset0:33 offset1:49
	ds_read2_b64 v[72:75], v18 offset0:66 offset1:82
	ds_read2_b64 v[76:79], v18 offset0:132 offset1:148
	ds_read2_b64 v[80:83], v18 offset0:99 offset1:115
	ds_read2_b64 v[84:87], v18 offset0:165 offset1:181
	ds_read2_b64 v[88:91], v18 offset0:198 offset1:214
	ds_read2_b64 v[92:95], v18 offset0:231 offset1:247
	s_waitcnt lgkmcnt(4)
	v_pk_add_f32 v[96:97], v[64:65], v[76:77]
	v_pk_add_f32 v[64:65], v[64:65], v[76:77] neg_lo:[0,1] neg_hi:[0,1]
	v_pk_add_f32 v[76:77], v[66:67], v[78:79]
	v_pk_add_f32 v[66:67], v[66:67], v[78:79] neg_lo:[0,1] neg_hi:[0,1]
	s_waitcnt lgkmcnt(1)
	v_pk_add_f32 v[98:99], v[74:75], v[90:91]
	v_pk_mul_f32 v[78:79], v[66:67], s[18:19]
	v_pk_add_f32 v[74:75], v[74:75], v[90:91] neg_lo:[0,1] neg_hi:[0,1]
	v_pk_fma_f32 v[66:67], v[66:67], s[16:17], v[78:79] op_sel:[0,0,1] op_sel_hi:[1,0,0]
	v_pk_add_f32 v[78:79], v[68:69], v[84:85]
	v_pk_add_f32 v[68:69], v[68:69], v[84:85] neg_lo:[0,1] neg_hi:[0,1]
	v_pk_mul_f32 v[90:91], v[74:75], s[40:41]
	v_pk_mul_f32 v[84:85], v[68:69], s[36:37]
	v_pk_fma_f32 v[74:75], v[74:75], s[68:69], v[90:91] op_sel:[0,0,1] op_sel_hi:[1,0,0] neg_lo:[1,0,0] neg_hi:[1,0,0]
	s_waitcnt lgkmcnt(0)
	v_pk_add_f32 v[90:91], v[80:81], v[92:93]
	v_pk_add_f32 v[80:81], v[80:81], v[92:93] neg_lo:[0,1] neg_hi:[0,1]
	v_pk_fma_f32 v[68:69], v[68:69], s[66:67], v[84:85] op_sel:[0,0,1] op_sel_hi:[1,0,0]
	v_pk_add_f32 v[84:85], v[70:71], v[86:87]
	v_pk_add_f32 v[70:71], v[70:71], v[86:87] neg_lo:[0,1] neg_hi:[0,1]
	v_pk_mul_f32 v[92:93], v[80:81], s[36:37]
	v_pk_mul_f32 v[86:87], v[70:71], s[40:41]
	v_pk_fma_f32 v[80:81], v[80:81], s[66:67], v[92:93] op_sel:[0,0,1] op_sel_hi:[1,0,0] neg_lo:[1,0,0] neg_hi:[1,0,0]
	v_pk_add_f32 v[92:93], v[82:83], v[94:95]
	v_pk_add_f32 v[82:83], v[82:83], v[94:95] neg_lo:[0,1] neg_hi:[0,1]
	v_pk_fma_f32 v[70:71], v[70:71], s[68:69], v[86:87] op_sel:[0,0,1] op_sel_hi:[1,0,0]
	v_pk_add_f32 v[86:87], v[72:73], v[88:89]
	v_pk_mul_f32 v[94:95], v[82:83], s[18:19]
	v_pk_add_f32 v[72:73], v[72:73], v[88:89] neg_lo:[0,1] neg_hi:[0,1]
	v_pk_fma_f32 v[82:83], v[82:83], s[16:17], v[94:95] op_sel:[0,0,1] op_sel_hi:[1,0,0] neg_lo:[1,0,0] neg_hi:[1,0,0]
	v_pk_add_f32 v[94:95], v[96:97], v[86:87]
	v_pk_add_f32 v[86:87], v[96:97], v[86:87] neg_lo:[0,1] neg_hi:[0,1]
	v_pk_add_f32 v[96:97], v[76:77], v[98:99]
	v_pk_add_f32 v[76:77], v[76:77], v[98:99] neg_lo:[0,1] neg_hi:[0,1]
	v_xor_b32_e32 v89, 0x80000000, v72
	v_pk_mul_f32 v[98:99], v[76:77], s[36:37]
	v_pk_add_f32 v[100:101], v[84:85], v[92:93]
	v_pk_add_f32 v[84:85], v[84:85], v[92:93] neg_lo:[0,1] neg_hi:[0,1]
	v_mov_b32_e32 v88, v73
	v_pk_fma_f32 v[76:77], v[76:77], s[66:67], v[98:99] op_sel:[0,0,1] op_sel_hi:[1,0,0]
	v_pk_add_f32 v[98:99], v[78:79], v[90:91]
	v_pk_add_f32 v[78:79], v[78:79], v[90:91] neg_lo:[0,1] neg_hi:[0,1]
	v_pk_mul_f32 v[92:93], v[84:85], s[36:37]
	v_pk_add_f32 v[72:73], v[64:65], v[88:89]
	v_pk_add_f32 v[64:65], v[64:65], v[88:89] neg_lo:[0,1] neg_hi:[0,1]
	v_pk_add_f32 v[88:89], v[66:67], v[74:75]
	v_pk_add_f32 v[66:67], v[66:67], v[74:75] neg_lo:[0,1] neg_hi:[0,1]
	v_xor_b32_e32 v91, 0x80000000, v78
	v_pk_fma_f32 v[84:85], v[84:85], s[66:67], v[92:93] op_sel:[0,0,1] op_sel_hi:[1,0,0] neg_lo:[1,0,0] neg_hi:[1,0,0]
	v_pk_mul_f32 v[74:75], v[66:67], s[36:37]
	v_mov_b32_e32 v90, v79
	v_pk_fma_f32 v[66:67], v[66:67], s[66:67], v[74:75] op_sel:[0,0,1] op_sel_hi:[1,0,0]
	v_pk_add_f32 v[74:75], v[68:69], v[80:81]
	v_pk_add_f32 v[92:93], v[70:71], v[82:83]
	v_pk_add_f32 v[70:71], v[70:71], v[82:83] neg_lo:[0,1] neg_hi:[0,1]
	v_pk_add_f32 v[78:79], v[86:87], v[90:91]
	v_pk_add_f32 v[86:87], v[86:87], v[90:91] neg_lo:[0,1] neg_hi:[0,1]
	v_pk_add_f32 v[90:91], v[76:77], v[84:85]
	v_pk_add_f32 v[76:77], v[76:77], v[84:85] neg_lo:[0,1] neg_hi:[0,1]
	v_pk_add_f32 v[68:69], v[68:69], v[80:81] neg_lo:[0,1] neg_hi:[0,1]
	v_pk_mul_f32 v[82:83], v[70:71], s[36:37]
	v_xor_b32_e32 v85, 0x80000000, v76
	v_pk_add_f32 v[102:103], v[72:73], v[74:75]
	v_pk_add_f32 v[72:73], v[72:73], v[74:75] neg_lo:[0,1] neg_hi:[0,1]
	v_pk_add_f32 v[74:75], v[88:89], v[92:93]
	v_mov_b32_e32 v84, v77
	v_xor_b32_e32 v81, 0x80000000, v68
	v_pk_fma_f32 v[70:71], v[70:71], s[66:67], v[82:83] op_sel:[0,0,1] op_sel_hi:[1,0,0] neg_lo:[1,0,0] neg_hi:[1,0,0]
	v_pk_add_f32 v[82:83], v[94:95], v[98:99]
	v_pk_add_f32 v[94:95], v[94:95], v[98:99] neg_lo:[0,1] neg_hi:[0,1]
	v_pk_add_f32 v[98:99], v[96:97], v[100:101]
	v_mov_b32_e32 v80, v69
	v_pk_add_f32 v[76:77], v[86:87], v[84:85]
	v_pk_add_f32 v[84:85], v[86:87], v[84:85] neg_lo:[0,1] neg_hi:[0,1]
	v_pk_add_f32 v[86:87], v[102:103], v[74:75]
	v_pk_add_f32 v[96:97], v[96:97], v[100:101] neg_lo:[0,1] neg_hi:[0,1]
	v_pk_add_f32 v[68:69], v[64:65], v[80:81]
	v_pk_add_f32 v[64:65], v[64:65], v[80:81] neg_lo:[0,1] neg_hi:[0,1]
	v_pk_add_f32 v[80:81], v[66:67], v[70:71]
	v_pk_add_f32 v[104:105], v[82:83], v[98:99]
	v_pk_add_f32 v[82:83], v[82:83], v[98:99] neg_lo:[0,1] neg_hi:[0,1]
	v_pk_add_f32 v[98:99], v[78:79], v[90:91]
	v_pk_mul_f32 v[2:3], v[2:3], v[86:87] op_sel:[0,1] op_sel_hi:[1,0]
	v_xor_b32_e32 v101, 0x80000000, v96
	v_pk_add_f32 v[88:89], v[88:89], v[92:93] neg_lo:[0,1] neg_hi:[0,1]
	v_mov_b32_e32 v100, v97
	v_pk_add_f32 v[78:79], v[78:79], v[90:91] neg_lo:[0,1] neg_hi:[0,1]
	v_pk_add_f32 v[90:91], v[68:69], v[80:81]
	v_pk_fma_f32 v[2:3], v[4:5], v[86:87], v[2:3] op_sel_hi:[0,1,1]
	v_pk_mul_f32 v[4:5], v[12:13], v[98:99] op_sel:[0,1] op_sel_hi:[1,0]
	v_xor_b32_e32 v93, 0x80000000, v88
	v_pk_add_f32 v[66:67], v[66:67], v[70:71] neg_lo:[0,1] neg_hi:[0,1]
	v_pk_add_f32 v[96:97], v[94:95], v[100:101]
	v_mov_b32_e32 v92, v89
	v_pk_fma_f32 v[4:5], v[6:7], v[98:99], v[4:5] op_sel_hi:[0,1,1]
	v_pk_mul_f32 v[6:7], v[20:21], v[90:91] op_sel:[0,1] op_sel_hi:[1,0]
	v_xor_b32_e32 v71, 0x80000000, v66
	v_pk_add_f32 v[88:89], v[72:73], v[92:93]
	v_mov_b32_e32 v70, v67
	v_pk_fma_f32 v[6:7], v[8:9], v[90:91], v[6:7] op_sel_hi:[0,1,1]
	v_pk_mul_f32 v[8:9], v[14:15], v[96:97] op_sel:[0,1] op_sel_hi:[1,0]
	v_pk_add_f32 v[66:67], v[64:65], v[70:71]
	v_pk_fma_f32 v[8:9], v[10:11], v[96:97], v[8:9] op_sel_hi:[0,1,1]
	v_pk_mul_f32 v[10:11], v[22:23], v[88:89] op_sel:[0,1] op_sel_hi:[1,0]
	v_pk_add_f32 v[94:95], v[94:95], v[100:101] neg_lo:[0,1] neg_hi:[0,1]
	v_pk_add_f32 v[74:75], v[102:103], v[74:75] neg_lo:[0,1] neg_hi:[0,1]
	v_pk_add_f32 v[72:73], v[72:73], v[92:93] neg_lo:[0,1] neg_hi:[0,1]
	v_pk_add_f32 v[68:69], v[68:69], v[80:81] neg_lo:[0,1] neg_hi:[0,1]
	v_pk_add_f32 v[64:65], v[64:65], v[70:71] neg_lo:[0,1] neg_hi:[0,1]
	v_pk_fma_f32 v[10:11], v[16:17], v[88:89], v[10:11] op_sel_hi:[0,1,1]
	v_pk_mul_f32 v[12:13], v[26:27], v[76:77] op_sel:[0,1] op_sel_hi:[1,0]
	v_pk_mul_f32 v[14:15], v[30:31], v[66:67] op_sel:[0,1] op_sel_hi:[1,0]
	v_pk_mul_f32 v[16:17], v[34:35], v[82:83] op_sel:[0,1] op_sel_hi:[1,0]
	v_pk_fma_f32 v[12:13], v[24:25], v[76:77], v[12:13] op_sel_hi:[0,1,1]
	v_pk_fma_f32 v[14:15], v[28:29], v[66:67], v[14:15] op_sel_hi:[0,1,1]
	v_pk_fma_f32 v[16:17], v[32:33], v[82:83], v[16:17] op_sel_hi:[0,1,1]
	v_pk_mul_f32 v[20:21], v[38:39], v[74:75] op_sel:[0,1] op_sel_hi:[1,0]
	v_pk_mul_f32 v[22:23], v[42:43], v[78:79] op_sel:[0,1] op_sel_hi:[1,0]
	v_pk_mul_f32 v[24:25], v[46:47], v[68:69] op_sel:[0,1] op_sel_hi:[1,0]
	v_pk_mul_f32 v[26:27], v[50:51], v[94:95] op_sel:[0,1] op_sel_hi:[1,0]
	v_pk_mul_f32 v[28:29], v[54:55], v[72:73] op_sel:[0,1] op_sel_hi:[1,0]
	v_pk_mul_f32 v[30:31], v[58:59], v[84:85] op_sel:[0,1] op_sel_hi:[1,0]
	v_pk_mul_f32 v[32:33], v[62:63], v[64:65] op_sel:[0,1] op_sel_hi:[1,0]
	v_pk_fma_f32 v[20:21], v[36:37], v[74:75], v[20:21] op_sel_hi:[0,1,1]
	v_pk_fma_f32 v[22:23], v[40:41], v[78:79], v[22:23] op_sel_hi:[0,1,1]
	v_pk_fma_f32 v[24:25], v[44:45], v[68:69], v[24:25] op_sel_hi:[0,1,1]
	v_pk_fma_f32 v[26:27], v[48:49], v[94:95], v[26:27] op_sel_hi:[0,1,1]
	v_pk_fma_f32 v[28:29], v[52:53], v[72:73], v[28:29] op_sel_hi:[0,1,1]
	v_pk_fma_f32 v[30:31], v[56:57], v[84:85], v[30:31] op_sel_hi:[0,1,1]
	v_pk_fma_f32 v[32:33], v[60:61], v[64:65], v[32:33] op_sel_hi:[0,1,1]
	ds_write2_b64 v18, v[104:105], v[16:17] offset1:16
	ds_write2_b64 v18, v[8:9], v[26:27] offset0:33 offset1:49
	ds_write2_b64 v18, v[4:5], v[22:23] offset0:66 offset1:82
	ds_write2_b64 v18, v[12:13], v[30:31] offset0:99 offset1:115
	ds_write2_b64 v18, v[2:3], v[20:21] offset0:132 offset1:148
	ds_write2_b64 v18, v[10:11], v[28:29] offset0:165 offset1:181
	ds_write2_b64 v18, v[6:7], v[24:25] offset0:198 offset1:214
	ds_write2_b64 v18, v[14:15], v[32:33] offset0:231 offset1:247
	v_ashrrev_i32_e32 v2, 31, v210
	v_add_u32_sdwa v2, v210, v2 dst_sel:DWORD dst_unused:UNUSED_PAD src0_sel:DWORD src1_sel:BYTE_3
	s_lshl_b64 s[0:1], s[64:65], 15
	v_and_b32_e32 v2, 0xffffff00, v2
	s_add_u32 s0, s29, s0
	v_sub_u32_e32 v2, v210, v2
	s_addc_u32 s1, s85, s1
	v_ashrrev_i32_e32 v3, 31, v2
	v_lshl_add_u64 v[14:15], v[2:3], 3, s[0:1]
	s_movk_i32 s0, 0x1000
	v_add_co_u32_e32 v16, vcc, s0, v14
	s_movk_i32 s0, 0x3000
	s_nop 0
	v_addc_co_u32_e32 v17, vcc, 0, v15, vcc
	v_add_co_u32_e32 v2, vcc, s92, v14
	s_waitcnt lgkmcnt(0)
	s_nop 0
	v_addc_co_u32_e32 v3, vcc, 0, v15, vcc
	v_add_co_u32_e32 v22, vcc, s0, v14
	s_movk_i32 s0, 0x5000
	s_nop 0
	v_addc_co_u32_e32 v23, vcc, 0, v15, vcc
	v_add_co_u32_e32 v8, vcc, s95, v14
	s_barrier
	s_waitcnt vmcnt(0)
	s_nop 0
	v_addc_co_u32_e32 v9, vcc, 0, v15, vcc
	v_add_co_u32_e32 v26, vcc, s0, v14
	s_nop 1
	v_addc_co_u32_e32 v27, vcc, 0, v15, vcc
	v_add_co_u32_e32 v10, vcc, s96, v14
	v_mov_b64_e32 v[12:13], v[222:223]
	v_mov_b64_e32 v[6:7], v[224:225]
	v_mov_b64_e32 v[4:5], v[226:227]
	v_mov_b64_e32 v[122:123], v[230:231]
	v_addc_co_u32_e32 v11, vcc, 0, v15, vcc
	v_add_co_u32_e32 v28, vcc, s97, v14
	v_mov_b64_e32 v[46:47], v[232:233]
	v_mov_b64_e32 v[38:39], v[234:235]
	v_mov_b64_e32 v[20:21], v[238:239]
	s_nop 0
	v_mov_b64_e32 v[10:11], v[240:241]
	v_addc_co_u32_e32 v29, vcc, 0, v15, vcc
	v_mov_b64_e32 v[24:25], v[218:219]
	s_nop 0
	v_mov_b64_e32 v[26:27], v[236:237]
	s_nop 0
	v_mov_b64_e32 v[8:9], v[242:243]
	v_mov_b64_e32 v[2:3], v[246:247]
	v_mov_b64_e32 v[30:31], v[216:217]
	s_nop 0
	v_mov_b64_e32 v[28:29], v[220:221]
	s_nop 0
	v_mov_b64_e32 v[16:17], v[228:229]
	v_mov_b64_e32 v[32:33], v[214:215]
	v_mov_b32_e32 v14, v210
	s_waitcnt vmcnt(15)
	v_cvt_f32_f16_sdwa v164, v12 dst_sel:DWORD dst_unused:UNUSED_PAD src0_sel:WORD_1
	v_ashrrev_i32_e32 v15, 31, v14
	v_add_u32_sdwa v15, v14, v15 dst_sel:DWORD dst_unused:UNUSED_PAD src0_sel:DWORD src1_sel:BYTE_3
	v_ashrrev_i32_e32 v15, 8, v15
	v_mul_i32_i24_e32 v18, 0x100, v15
	v_sub_u32_e32 v18, v14, v18
	v_lshlrev_b32_e32 v14, 13, v15
	v_lshlrev_b32_e32 v15, 1, v18
	v_bfrev_b32_e32 v15, v15
	v_lshrrev_b32_e32 v15, 23, v15
	v_sub_u32_e32 v15, 0x200, v15
	v_bfrev_b32_e32 v15, v15
	v_lshrrev_b32_e32 v15, 19, v15
	v_and_b32_e32 v15, 0x1ff0, v15
	v_cmp_eq_u32_e64 s[0:1], 0, v18
	v_lshl_add_u32 v22, v18, 5, v14
	v_lshl_add_u32 v23, v22, 3, 0
	v_cndmask_b32_e64 v15, v15, 16, s[0:1]
	v_or_b32_e32 v14, v15, v14
	v_ashrrev_i32_e32 v22, 2, v22
	v_ashrrev_i32_e32 v15, 5, v14
	v_add_u32_e32 v211, v23, v22
	v_lshlrev_b32_e32 v14, 3, v14
	v_lshlrev_b32_e32 v15, 3, v15
	v_add3_u32 v212, 0, v14, v15
	ds_read2_b64 v[34:37], v211 offset1:1
	ds_read2_b64 v[40:43], v211 offset0:2 offset1:3
	ds_read2_b64 v[48:51], v212 offset1:1
	ds_read2_b64 v[52:55], v212 offset0:2 offset1:3
	ds_read2_b64 v[56:59], v211 offset0:4 offset1:5
	ds_read2_b64 v[60:63], v211 offset0:6 offset1:7
	ds_read2_b64 v[68:71], v212 offset0:4 offset1:5
	ds_read2_b64 v[72:75], v212 offset0:6 offset1:7
	ds_read2_b64 v[64:67], v211 offset0:8 offset1:9
	ds_read2_b64 v[76:79], v211 offset0:10 offset1:11
	ds_read2_b64 v[80:83], v212 offset0:8 offset1:9
	ds_read2_b64 v[98:101], v212 offset0:10 offset1:11
	ds_read2_b64 v[84:87], v211 offset0:12 offset1:13
	ds_read2_b64 v[88:91], v211 offset0:14 offset1:15
	ds_read2_b64 v[102:105], v212 offset0:12 offset1:13
	ds_read2_b64 v[106:109], v212 offset0:14 offset1:15
	s_waitcnt lgkmcnt(7)
	v_pk_add_f32 v[14:15], v[34:35], v[64:65]
	v_pk_add_f32 v[22:23], v[34:35], v[64:65] neg_lo:[0,1] neg_hi:[0,1]
	v_pk_add_f32 v[34:35], v[36:37], v[66:67]
	v_pk_add_f32 v[36:37], v[36:37], v[66:67] neg_lo:[0,1] neg_hi:[0,1]
	v_cmp_ne_u32_e32 vcc, 0, v18
	v_pk_mul_f32 v[44:45], v[36:37], s[18:19]
	v_bfrev_b32_e32 v18, v18
	v_pk_fma_f32 v[36:37], v[36:37], s[16:17], v[44:45] op_sel:[0,0,1] op_sel_hi:[1,0,0]
	s_waitcnt lgkmcnt(6)
	v_pk_add_f32 v[44:45], v[40:41], v[76:77]
	v_pk_add_f32 v[40:41], v[40:41], v[76:77] neg_lo:[0,1] neg_hi:[0,1]
	v_cvt_f32_ubyte3_e32 v18, v18
	v_pk_mul_f32 v[64:65], v[40:41], s[36:37]
	v_mul_f32_e32 v18, 0x38800000, v18
	v_pk_fma_f32 v[40:41], v[40:41], s[66:67], v[64:65] op_sel:[0,0,1] op_sel_hi:[1,0,0]
	v_pk_add_f32 v[64:65], v[42:43], v[78:79]
	v_pk_add_f32 v[42:43], v[42:43], v[78:79] neg_lo:[0,1] neg_hi:[0,1]
	s_waitcnt lgkmcnt(3)
	v_pk_add_f32 v[78:79], v[58:59], v[86:87]
	v_pk_mul_f32 v[66:67], v[42:43], s[40:41]
	v_pk_add_f32 v[58:59], v[58:59], v[86:87] neg_lo:[0,1] neg_hi:[0,1]
	v_pk_fma_f32 v[42:43], v[42:43], s[68:69], v[66:67] op_sel:[0,0,1] op_sel_hi:[1,0,0]
	v_pk_add_f32 v[66:67], v[56:57], v[84:85]
	v_pk_add_f32 v[56:57], v[56:57], v[84:85] neg_lo:[0,1] neg_hi:[0,1]
	v_pk_mul_f32 v[84:85], v[58:59], s[40:41]
	v_xor_b32_e32 v77, 0x80000000, v56
	v_pk_fma_f32 v[58:59], v[58:59], s[68:69], v[84:85] op_sel:[0,0,1] op_sel_hi:[1,0,0] neg_lo:[1,0,0] neg_hi:[1,0,0]
	s_waitcnt lgkmcnt(2)
	v_pk_add_f32 v[84:85], v[60:61], v[88:89]
	v_pk_add_f32 v[60:61], v[60:61], v[88:89] neg_lo:[0,1] neg_hi:[0,1]
	v_mov_b32_e32 v76, v57
	v_pk_mul_f32 v[86:87], v[60:61], s[36:37]
	v_pk_add_f32 v[56:57], v[22:23], v[76:77]
	v_pk_fma_f32 v[60:61], v[60:61], s[66:67], v[86:87] op_sel:[0,0,1] op_sel_hi:[1,0,0] neg_lo:[1,0,0] neg_hi:[1,0,0]
	v_pk_add_f32 v[86:87], v[62:63], v[90:91]
	v_pk_add_f32 v[62:63], v[62:63], v[90:91] neg_lo:[0,1] neg_hi:[0,1]
	v_pk_add_f32 v[90:91], v[64:65], v[86:87]
	v_pk_mul_f32 v[88:89], v[62:63], s[18:19]
	v_pk_add_f32 v[64:65], v[64:65], v[86:87] neg_lo:[0,1] neg_hi:[0,1]
	v_pk_fma_f32 v[62:63], v[62:63], s[16:17], v[88:89] op_sel:[0,0,1] op_sel_hi:[1,0,0] neg_lo:[1,0,0] neg_hi:[1,0,0]
	v_pk_add_f32 v[88:89], v[14:15], v[66:67]
	v_pk_add_f32 v[14:15], v[14:15], v[66:67] neg_lo:[0,1] neg_hi:[0,1]
	v_pk_add_f32 v[66:67], v[34:35], v[78:79]
	v_pk_add_f32 v[34:35], v[34:35], v[78:79] neg_lo:[0,1] neg_hi:[0,1]
	v_pk_add_f32 v[22:23], v[22:23], v[76:77] neg_lo:[0,1] neg_hi:[0,1]
	v_pk_mul_f32 v[78:79], v[34:35], s[36:37]
	v_pk_add_f32 v[76:77], v[36:37], v[58:59]
	v_pk_add_f32 v[36:37], v[36:37], v[58:59] neg_lo:[0,1] neg_hi:[0,1]
	v_pk_fma_f32 v[34:35], v[34:35], s[66:67], v[78:79] op_sel:[0,0,1] op_sel_hi:[1,0,0]
	v_pk_add_f32 v[78:79], v[44:45], v[84:85]
	v_pk_add_f32 v[44:45], v[44:45], v[84:85] neg_lo:[0,1] neg_hi:[0,1]
	v_pk_mul_f32 v[86:87], v[64:65], s[36:37]
	v_pk_mul_f32 v[58:59], v[36:37], s[36:37]
	v_xor_b32_e32 v85, 0x80000000, v44
	v_pk_fma_f32 v[64:65], v[64:65], s[66:67], v[86:87] op_sel:[0,0,1] op_sel_hi:[1,0,0] neg_lo:[1,0,0] neg_hi:[1,0,0]
	v_pk_fma_f32 v[36:37], v[36:37], s[66:67], v[58:59] op_sel:[0,0,1] op_sel_hi:[1,0,0]
	v_pk_add_f32 v[58:59], v[40:41], v[60:61]
	v_pk_add_f32 v[86:87], v[42:43], v[62:63]
	v_pk_add_f32 v[42:43], v[42:43], v[62:63] neg_lo:[0,1] neg_hi:[0,1]
	v_mov_b32_e32 v84, v45
	v_pk_mul_f32 v[62:63], v[42:43], s[36:37]
	v_pk_add_f32 v[44:45], v[14:15], v[84:85]
	v_pk_add_f32 v[14:15], v[14:15], v[84:85] neg_lo:[0,1] neg_hi:[0,1]
	v_pk_add_f32 v[84:85], v[34:35], v[64:65]
	v_pk_add_f32 v[34:35], v[34:35], v[64:65] neg_lo:[0,1] neg_hi:[0,1]
	v_pk_add_f32 v[94:95], v[56:57], v[58:59]
	v_pk_add_f32 v[56:57], v[56:57], v[58:59] neg_lo:[0,1] neg_hi:[0,1]
	v_pk_add_f32 v[58:59], v[76:77], v[86:87]
	v_pk_fma_f32 v[42:43], v[42:43], s[66:67], v[62:63] op_sel:[0,0,1] op_sel_hi:[1,0,0] neg_lo:[1,0,0] neg_hi:[1,0,0]
	v_pk_add_f32 v[62:63], v[88:89], v[78:79]
	v_pk_add_f32 v[78:79], v[88:89], v[78:79] neg_lo:[0,1] neg_hi:[0,1]
	v_pk_add_f32 v[88:89], v[66:67], v[90:91]
	v_xor_b32_e32 v65, 0x80000000, v34
	v_pk_add_f32 v[76:77], v[76:77], v[86:87] neg_lo:[0,1] neg_hi:[0,1]
	v_mov_b32_e32 v64, v35
	v_pk_add_f32 v[86:87], v[94:95], v[58:59]
	v_pk_add_f32 v[34:35], v[94:95], v[58:59] neg_lo:[0,1] neg_hi:[0,1]
	v_pk_add_f32 v[58:59], v[50:51], v[82:83]
	v_pk_add_f32 v[50:51], v[50:51], v[82:83] neg_lo:[0,1] neg_hi:[0,1]
	v_pk_add_f32 v[40:41], v[40:41], v[60:61] neg_lo:[0,1] neg_hi:[0,1]
	v_pk_add_f32 v[148:149], v[62:63], v[88:89]
	v_pk_add_f32 v[138:139], v[62:63], v[88:89] neg_lo:[0,1] neg_hi:[0,1]
	v_pk_mul_f32 v[62:63], v[50:51], s[18:19]
	v_xor_b32_e32 v61, 0x80000000, v40
	v_pk_add_f32 v[66:67], v[66:67], v[90:91] neg_lo:[0,1] neg_hi:[0,1]
	v_mov_b32_e32 v60, v41
	v_pk_fma_f32 v[50:51], v[50:51], s[16:17], v[62:63] op_sel:[0,0,1] op_sel_hi:[1,0,0]
	v_pk_add_f32 v[62:63], v[52:53], v[98:99]
	v_pk_add_f32 v[52:53], v[52:53], v[98:99] neg_lo:[0,1] neg_hi:[0,1]
	v_xor_b32_e32 v91, 0x80000000, v66
	v_pk_add_f32 v[112:113], v[22:23], v[60:61]
	v_pk_add_f32 v[114:115], v[22:23], v[60:61] neg_lo:[0,1] neg_hi:[0,1]
	v_mov_b32_e32 v90, v67
	v_pk_add_f32 v[96:97], v[44:45], v[84:85]
	v_pk_add_f32 v[66:67], v[44:45], v[84:85] neg_lo:[0,1] neg_hi:[0,1]
	v_pk_add_f32 v[60:61], v[14:15], v[64:65]
	v_pk_add_f32 v[84:85], v[14:15], v[64:65] neg_lo:[0,1] neg_hi:[0,1]
	v_pk_mul_f32 v[64:65], v[52:53], s[36:37]
	v_xor_b32_e32 v111, 0x80000000, v76
	v_pk_fma_f32 v[52:53], v[52:53], s[66:67], v[64:65] op_sel:[0,0,1] op_sel_hi:[1,0,0]
	v_pk_add_f32 v[64:65], v[54:55], v[100:101]
	v_pk_add_f32 v[54:55], v[54:55], v[100:101] neg_lo:[0,1] neg_hi:[0,1]
	v_mov_b32_e32 v110, v77
	v_pk_mul_f32 v[76:77], v[54:55], s[40:41]
	v_pk_add_f32 v[92:93], v[78:79], v[90:91]
	v_pk_fma_f32 v[54:55], v[54:55], s[68:69], v[76:77] op_sel:[0,0,1] op_sel_hi:[1,0,0]
	s_waitcnt lgkmcnt(1)
	v_pk_add_f32 v[76:77], v[68:69], v[102:103]
	v_pk_add_f32 v[68:69], v[68:69], v[102:103] neg_lo:[0,1] neg_hi:[0,1]
	v_pk_add_f32 v[88:89], v[78:79], v[90:91] neg_lo:[0,1] neg_hi:[0,1]
	v_xor_b32_e32 v79, 0x80000000, v68
	v_mov_b32_e32 v78, v69
	v_pk_add_f32 v[68:69], v[70:71], v[104:105]
	v_pk_add_f32 v[70:71], v[70:71], v[104:105] neg_lo:[0,1] neg_hi:[0,1]
	v_pk_add_f32 v[40:41], v[56:57], v[110:111]
	v_pk_add_f32 v[44:45], v[56:57], v[110:111] neg_lo:[0,1] neg_hi:[0,1]
	v_pk_add_f32 v[56:57], v[48:49], v[80:81]
	v_pk_add_f32 v[48:49], v[48:49], v[80:81] neg_lo:[0,1] neg_hi:[0,1]
	v_pk_mul_f32 v[80:81], v[70:71], s[40:41]
	v_cndmask_b32_e64 v18, v18, v208, s[0:1]
	v_pk_fma_f32 v[70:71], v[70:71], s[68:69], v[80:81] op_sel:[0,0,1] op_sel_hi:[1,0,0] neg_lo:[1,0,0] neg_hi:[1,0,0]
	s_waitcnt lgkmcnt(0)
	v_pk_add_f32 v[80:81], v[72:73], v[106:107]
	v_pk_add_f32 v[72:73], v[72:73], v[106:107] neg_lo:[0,1] neg_hi:[0,1]
	v_pk_add_f32 v[22:23], v[36:37], v[42:43]
	v_pk_mul_f32 v[82:83], v[72:73], s[36:37]
	v_pk_add_f32 v[36:37], v[36:37], v[42:43] neg_lo:[0,1] neg_hi:[0,1]
	v_pk_fma_f32 v[72:73], v[72:73], s[66:67], v[82:83] op_sel:[0,0,1] op_sel_hi:[1,0,0] neg_lo:[1,0,0] neg_hi:[1,0,0]
	v_pk_add_f32 v[82:83], v[74:75], v[108:109]
	v_pk_add_f32 v[74:75], v[74:75], v[108:109] neg_lo:[0,1] neg_hi:[0,1]
	v_xor_b32_e32 v117, 0x80000000, v36
	v_pk_mul_f32 v[90:91], v[74:75], s[18:19]
	v_mov_b32_e32 v116, v37
	v_pk_fma_f32 v[74:75], v[74:75], s[16:17], v[90:91] op_sel:[0,0,1] op_sel_hi:[1,0,0] neg_lo:[1,0,0] neg_hi:[1,0,0]
	v_pk_add_f32 v[90:91], v[56:57], v[76:77]
	v_pk_add_f32 v[56:57], v[56:57], v[76:77] neg_lo:[0,1] neg_hi:[0,1]
	v_pk_add_f32 v[76:77], v[58:59], v[68:69]
	v_pk_add_f32 v[58:59], v[58:59], v[68:69] neg_lo:[0,1] neg_hi:[0,1]
	v_pk_add_f32 v[14:15], v[114:115], v[116:117]
	v_pk_mul_f32 v[68:69], v[58:59], s[36:37]
	v_pk_add_f32 v[36:37], v[114:115], v[116:117] neg_lo:[0,1] neg_hi:[0,1]
	v_pk_fma_f32 v[58:59], v[58:59], s[66:67], v[68:69] op_sel:[0,0,1] op_sel_hi:[1,0,0]
	v_pk_add_f32 v[68:69], v[62:63], v[80:81]
	v_pk_add_f32 v[62:63], v[62:63], v[80:81] neg_lo:[0,1] neg_hi:[0,1]
	s_waitcnt vmcnt(0)
	v_cvt_f32_f16_e32 v193, v33
	v_xor_b32_e32 v81, 0x80000000, v62
	v_mov_b32_e32 v80, v63
	v_pk_add_f32 v[62:63], v[64:65], v[82:83]
	v_pk_add_f32 v[64:65], v[64:65], v[82:83] neg_lo:[0,1] neg_hi:[0,1]
	v_cvt_f32_f16_sdwa v192, v32 dst_sel:DWORD dst_unused:UNUSED_PAD src0_sel:WORD_1
	v_pk_mul_f32 v[82:83], v[64:65], s[36:37]
	v_cvt_f32_f16_e32 v194, v32
	v_pk_fma_f32 v[64:65], v[64:65], s[66:67], v[82:83] op_sel:[0,0,1] op_sel_hi:[1,0,0] neg_lo:[1,0,0] neg_hi:[1,0,0]
	v_pk_add_f32 v[82:83], v[48:49], v[78:79]
	v_pk_add_f32 v[48:49], v[48:49], v[78:79] neg_lo:[0,1] neg_hi:[0,1]
	v_pk_add_f32 v[78:79], v[50:51], v[70:71]
	v_pk_add_f32 v[50:51], v[50:51], v[70:71] neg_lo:[0,1] neg_hi:[0,1]
	v_cvt_f32_f16_sdwa v195, v33 dst_sel:DWORD dst_unused:UNUSED_PAD src0_sel:WORD_1
	v_pk_mul_f32 v[70:71], v[50:51], s[36:37]
	v_cvt_f32_f16_sdwa v170, v30 dst_sel:DWORD dst_unused:UNUSED_PAD src0_sel:WORD_1
	v_pk_fma_f32 v[50:51], v[50:51], s[66:67], v[70:71] op_sel:[0,0,1] op_sel_hi:[1,0,0]
	v_pk_add_f32 v[70:71], v[52:53], v[72:73]
	v_pk_add_f32 v[52:53], v[52:53], v[72:73] neg_lo:[0,1] neg_hi:[0,1]
	v_cvt_f32_f16_e32 v171, v31
	v_xor_b32_e32 v73, 0x80000000, v52
	v_mov_b32_e32 v72, v53
	v_pk_add_f32 v[52:53], v[54:55], v[74:75]
	v_pk_add_f32 v[54:55], v[54:55], v[74:75] neg_lo:[0,1] neg_hi:[0,1]
	v_cvt_f32_f16_sdwa v185, v31 dst_sel:DWORD dst_unused:UNUSED_PAD src0_sel:WORD_1
	v_pk_mul_f32 v[74:75], v[54:55], s[36:37]
	v_cvt_f32_f16_e32 v184, v30
	v_pk_fma_f32 v[54:55], v[54:55], s[66:67], v[74:75] op_sel:[0,0,1] op_sel_hi:[1,0,0] neg_lo:[1,0,0] neg_hi:[1,0,0]
	v_pk_add_f32 v[74:75], v[90:91], v[68:69]
	v_pk_add_f32 v[68:69], v[90:91], v[68:69] neg_lo:[0,1] neg_hi:[0,1]
	v_pk_add_f32 v[90:91], v[76:77], v[62:63]
	v_pk_add_f32 v[62:63], v[76:77], v[62:63] neg_lo:[0,1] neg_hi:[0,1]
	v_cvt_f32_f16_sdwa v172, v24 dst_sel:DWORD dst_unused:UNUSED_PAD src0_sel:WORD_1
	v_xor_b32_e32 v77, 0x80000000, v62
	v_mov_b32_e32 v76, v63
	v_pk_add_f32 v[62:63], v[56:57], v[80:81]
	v_pk_add_f32 v[56:57], v[56:57], v[80:81] neg_lo:[0,1] neg_hi:[0,1]
	v_pk_add_f32 v[80:81], v[58:59], v[64:65]
	v_pk_add_f32 v[58:59], v[58:59], v[64:65] neg_lo:[0,1] neg_hi:[0,1]
	v_cvt_f32_f16_e32 v173, v25
	v_xor_b32_e32 v65, 0x80000000, v58
	v_mov_b32_e32 v64, v59
	v_pk_add_f32 v[58:59], v[82:83], v[70:71]
	v_pk_add_f32 v[70:71], v[82:83], v[70:71] neg_lo:[0,1] neg_hi:[0,1]
	v_pk_add_f32 v[82:83], v[78:79], v[52:53]
	v_pk_add_f32 v[52:53], v[78:79], v[52:53] neg_lo:[0,1] neg_hi:[0,1]
	v_pk_add_f32 v[118:119], v[58:59], v[82:83]
	v_pk_add_f32 v[134:135], v[58:59], v[82:83] neg_lo:[0,1] neg_hi:[0,1]
	v_cos_f32_e32 v83, v18
	v_sin_f32_e32 v82, v18
	v_cvt_f32_f16_sdwa v181, v25 dst_sel:DWORD dst_unused:UNUSED_PAD src0_sel:WORD_1
	v_cvt_f32_f16_e32 v180, v24
	v_cvt_f32_f16_sdwa v174, v28 dst_sel:DWORD dst_unused:UNUSED_PAD src0_sel:WORD_1
	v_cvt_f32_f16_e32 v175, v29
	v_cvt_f32_f16_sdwa v179, v29 dst_sel:DWORD dst_unused:UNUSED_PAD src0_sel:WORD_1
	v_cvt_f32_f16_e32 v178, v28
	v_cvt_f32_f16_e32 v165, v13
	v_cvt_f32_f16_sdwa v167, v13 dst_sel:DWORD dst_unused:UNUSED_PAD src0_sel:WORD_1
	v_cvt_f32_f16_e32 v166, v12
	v_cvt_f32_f16_e32 v154, v6
	v_cvt_f32_f16_e32 v155, v7
	v_cvt_f32_f16_sdwa v157, v7 dst_sel:DWORD dst_unused:UNUSED_PAD src0_sel:WORD_1
	v_cvt_f32_f16_sdwa v156, v6 dst_sel:DWORD dst_unused:UNUSED_PAD src0_sel:WORD_1
	v_cvt_f32_f16_sdwa v140, v4 dst_sel:DWORD dst_unused:UNUSED_PAD src0_sel:WORD_1
	v_cvt_f32_f16_e32 v141, v5
	v_cvt_f32_f16_sdwa v143, v5 dst_sel:DWORD dst_unused:UNUSED_PAD src0_sel:WORD_1
	v_cvt_f32_f16_e32 v142, v4
	v_cvt_f32_f16_e32 v124, v16
	v_cvt_f32_f16_e32 v125, v17
	v_cvt_f32_f16_sdwa v127, v17 dst_sel:DWORD dst_unused:UNUSED_PAD src0_sel:WORD_1
	v_cvt_f32_f16_sdwa v126, v16 dst_sel:DWORD dst_unused:UNUSED_PAD src0_sel:WORD_1
	v_cvt_f32_f16_sdwa v114, v122 dst_sel:DWORD dst_unused:UNUSED_PAD src0_sel:WORD_1
	v_cvt_f32_f16_e32 v115, v123
	v_cvt_f32_f16_sdwa v117, v123 dst_sel:DWORD dst_unused:UNUSED_PAD src0_sel:WORD_1
	v_cvt_f32_f16_e32 v116, v122
	v_xor_b32_e32 v79, 0x80000000, v52
	v_mov_b32_e32 v78, v53
	v_pk_add_f32 v[52:53], v[48:49], v[72:73]
	v_pk_add_f32 v[48:49], v[48:49], v[72:73] neg_lo:[0,1] neg_hi:[0,1]
	v_pk_add_f32 v[72:73], v[50:51], v[54:55]
	v_pk_add_f32 v[50:51], v[50:51], v[54:55] neg_lo:[0,1] neg_hi:[0,1]
	v_pk_fma_f32 v[160:161], v[82:83], 0, v[82:83] op_sel:[0,0,1] op_sel_hi:[1,0,0] neg_lo:[1,0,0] neg_hi:[1,0,0]
	v_xor_b32_e32 v55, 0x80000000, v50
	v_mov_b32_e32 v54, v51
	v_pk_fma_f32 v[198:199], v[82:83], 0, v[82:83] op_sel:[0,0,1] op_sel_hi:[1,0,0]
	v_pk_add_f32 v[42:43], v[112:113], v[22:23]
	v_pk_add_f32 v[22:23], v[112:113], v[22:23] neg_lo:[0,1] neg_hi:[0,1]
	v_pk_add_f32 v[98:99], v[74:75], v[90:91]
	v_pk_add_f32 v[100:101], v[74:75], v[90:91] neg_lo:[0,1] neg_hi:[0,1]
	v_pk_add_f32 v[102:103], v[68:69], v[76:77]
	v_pk_add_f32 v[106:107], v[68:69], v[76:77] neg_lo:[0,1] neg_hi:[0,1]
	v_pk_add_f32 v[104:105], v[62:63], v[80:81]
	v_pk_add_f32 v[108:109], v[62:63], v[80:81] neg_lo:[0,1] neg_hi:[0,1]
	v_pk_add_f32 v[110:111], v[56:57], v[64:65]
	v_pk_add_f32 v[112:113], v[56:57], v[64:65] neg_lo:[0,1] neg_hi:[0,1]
	v_pk_add_f32 v[152:153], v[70:71], v[78:79]
	v_pk_add_f32 v[162:163], v[70:71], v[78:79] neg_lo:[0,1] neg_hi:[0,1]
	v_pk_add_f32 v[176:177], v[52:53], v[72:73]
	v_pk_add_f32 v[182:183], v[52:53], v[72:73] neg_lo:[0,1] neg_hi:[0,1]
	v_pk_add_f32 v[188:189], v[48:49], v[54:55]
	v_pk_add_f32 v[196:197], v[48:49], v[54:55] neg_lo:[0,1] neg_hi:[0,1]
	v_pk_mul_f32 v[186:187], v[82:83], 0 op_sel_hi:[1,0]
	v_mov_b32_e32 v190, v160
	v_mov_b32_e32 v191, v199
	v_mul_f32_e32 v18, 0x3f3504f3, v83
	v_mul_f32_e32 v158, 0xbec3ef15, v83
	v_mul_f32_e32 v132, 0xbf6c835e, v83
	s_and_saveexec_b64 s[0:1], vcc
	s_xor_b64 s[0:1], exec, s[0:1]
	s_cbranch_execz .LBB0_536
	v_pk_add_f32 v[4:5], v[148:149], v[196:197]
	v_pk_add_f32 v[6:7], v[148:149], v[196:197] neg_lo:[0,1] neg_hi:[0,1]
	v_mul_f32_e32 v4, 0.5, v4
	v_mul_f32_e32 v12, 0.5, v7
	v_mov_b32_e32 v7, v5
	v_pk_mul_f32 v[6:7], v[6:7], s[44:45]
	v_pk_mov_b32 v[16:17], v[198:199], v[160:161] op_sel:[1,0]
	v_pk_mul_f32 v[24:25], v[190:191], v[6:7] op_sel:[0,1] op_sel_hi:[1,0]
	v_pk_mul_f32 v[6:7], v[190:191], v[6:7]
	v_pk_add_f32 v[24:25], v[24:25], v[24:25] op_sel:[0,1] op_sel_hi:[0,1]
	v_pk_add_f32 v[28:29], v[4:5], v[24:25]
	v_pk_add_f32 v[4:5], v[4:5], v[24:25] op_sel_hi:[0,1] neg_lo:[0,1] neg_hi:[0,1]
	v_mov_b32_e32 v29, v5
	v_pk_add_f32 v[4:5], v[6:7], v[6:7] op_sel:[0,1] op_sel_hi:[0,1] neg_lo:[0,1] neg_hi:[0,1]
	v_pk_add_f32 v[6:7], v[12:13], v[4:5]
	v_pk_add_f32 v[4:5], v[12:13], v[4:5] op_sel_hi:[0,1] neg_lo:[0,1] neg_hi:[0,1]
	v_mov_b32_e32 v7, v5
	v_pk_mul_f32 v[4:5], v[6:7], v[194:195]
	v_pk_mul_f32 v[6:7], v[6:7], v[192:193]
	v_pk_fma_f32 v[4:5], v[28:29], v[192:193], v[4:5]
	v_pk_fma_f32 v[6:7], v[28:29], v[194:195], v[6:7] neg_lo:[0,0,1] neg_hi:[0,0,1]
	s_mov_b32 s66, s19
	v_pk_add_f32 v[12:13], v[6:7], v[4:5] op_sel:[0,1] op_sel_hi:[1,0] neg_lo:[0,1] neg_hi:[0,1]
	v_pk_add_f32 v[28:29], v[6:7], v[4:5] op_sel:[0,1] op_sel_hi:[1,0]
	v_pk_add_f32 v[4:5], v[4:5], v[6:7] op_sel:[1,0] op_sel_hi:[0,1] neg_lo:[0,1] neg_hi:[0,1]
	v_mov_b32_e32 v13, v29
	v_pk_mul_f32 v[12:13], v[12:13], 0.5 op_sel_hi:[1,0]
	v_mov_b32_e32 v29, v5
	v_mul_f32_e32 v24, v190, v12
	v_pk_fma_f32 v[30:31], v[190:191], v[12:13], v[24:25] op_sel_hi:[1,1,0] neg_lo:[1,0,0] neg_hi:[1,0,0]
	v_mul_f32_e32 v24, v160, v13
	v_pk_fma_f32 v[12:13], v[16:17], v[12:13], v[24:25] op_sel_hi:[1,1,0]
	v_mov_b32_e32 v16, v83
	v_mov_b32_e32 v30, v12
	v_pk_fma_f32 v[4:5], v[28:29], 0.5, v[12:13] op_sel_hi:[1,0,1] neg_lo:[0,0,1] neg_hi:[0,0,1]
	v_pk_fma_f32 v[122:123], v[28:29], 0.5, v[30:31] op_sel_hi:[1,0,1]
	v_pk_fma_f32 v[6:7], v[28:29], 0.5, v[30:31] op_sel_hi:[1,0,1] neg_lo:[1,0,0] neg_hi:[1,0,0]
	v_mov_b32_e32 v5, v123
	v_pk_mul_f32 v[24:25], v[4:5], s[46:47] op_sel_hi:[1,0]
	v_pk_add_f32 v[4:5], v[138:139], v[188:189]
	v_pk_add_f32 v[12:13], v[138:139], v[188:189] neg_lo:[0,1] neg_hi:[0,1]
	v_mov_b32_e32 v17, v82
	v_mul_f32_e32 v6, 0.5, v13
	v_pk_add_f32 v[28:29], v[186:187], v[16:17] neg_lo:[0,1] neg_hi:[0,1]
	v_pk_add_f32 v[30:31], v[186:187], v[16:17]
	v_mov_b32_e32 v13, v5
	v_pk_mov_b32 v[32:33], v[28:29], v[30:31] op_sel:[1,0]
	v_pk_mul_f32 v[12:13], v[12:13], s[44:45]
	v_mul_f32_e32 v4, 0.5, v4
	v_pk_mul_f32 v[48:49], v[32:33], v[12:13] op_sel:[0,1] op_sel_hi:[1,0]
	v_pk_mul_f32 v[12:13], v[32:33], v[12:13]
	v_pk_add_f32 v[48:49], v[48:49], v[48:49] op_sel:[0,1] op_sel_hi:[0,1]
	v_pk_add_f32 v[50:51], v[4:5], v[48:49]
	v_pk_add_f32 v[4:5], v[4:5], v[48:49] op_sel_hi:[0,1] neg_lo:[0,1] neg_hi:[0,1]
	v_mov_b32_e32 v51, v5
	v_pk_add_f32 v[4:5], v[12:13], v[12:13] op_sel:[0,1] op_sel_hi:[0,1] neg_lo:[0,1] neg_hi:[0,1]
	v_pk_add_f32 v[12:13], v[6:7], v[4:5]
	v_pk_add_f32 v[4:5], v[6:7], v[4:5] op_sel_hi:[0,1] neg_lo:[0,1] neg_hi:[0,1]
	v_mov_b32_e32 v13, v5
	v_pk_mul_f32 v[4:5], v[12:13], v[184:185]
	v_pk_mul_f32 v[12:13], v[12:13], v[170:171]
	v_pk_fma_f32 v[4:5], v[50:51], v[170:171], v[4:5]
	v_pk_fma_f32 v[12:13], v[50:51], v[184:185], v[12:13] neg_lo:[0,0,1] neg_hi:[0,0,1]
	v_mov_b32_e32 v31, v29
	v_pk_add_f32 v[48:49], v[12:13], v[4:5] op_sel:[0,1] op_sel_hi:[1,0] neg_lo:[0,1] neg_hi:[0,1]
	v_pk_add_f32 v[50:51], v[12:13], v[4:5] op_sel:[0,1] op_sel_hi:[1,0]
	v_pk_add_f32 v[4:5], v[4:5], v[12:13] op_sel:[1,0] op_sel_hi:[0,1] neg_lo:[0,1] neg_hi:[0,1]
	v_mov_b32_e32 v49, v51
	v_pk_mul_f32 v[48:49], v[48:49], 0.5 op_sel_hi:[1,0]
	v_mov_b32_e32 v51, v5
	v_mul_f32_e32 v6, v29, v48
	v_pk_fma_f32 v[32:33], v[32:33], v[48:49], v[6:7] op_sel_hi:[1,1,0] neg_lo:[1,0,0] neg_hi:[1,0,0]
	v_mul_f32_e32 v6, v29, v49
	v_pk_fma_f32 v[28:29], v[30:31], v[48:49], v[6:7] op_sel_hi:[1,1,0]
	v_pk_mul_f32 v[12:13], v[16:17], s[36:37]
	v_mov_b32_e32 v32, v28
	v_pk_fma_f32 v[4:5], v[50:51], 0.5, v[28:29] op_sel_hi:[1,0,1] neg_lo:[0,0,1] neg_hi:[0,0,1]
	v_pk_fma_f32 v[138:139], v[50:51], 0.5, v[32:33] op_sel_hi:[1,0,1]
	v_pk_add_f32 v[16:17], v[92:93], v[182:183]
	v_mov_b32_e32 v5, v139
	v_pk_add_f32 v[28:29], v[92:93], v[182:183] neg_lo:[0,1] neg_hi:[0,1]
	v_pk_mul_f32 v[30:31], v[4:5], s[46:47] op_sel_hi:[1,0]
	v_pk_fma_f32 v[4:5], v[50:51], 0.5, v[32:33] op_sel_hi:[1,0,1] neg_lo:[1,0,0] neg_hi:[1,0,0]
	v_mul_f32_e32 v6, 0.5, v29
	v_pk_add_f32 v[32:33], v[18:19], v[12:13] op_sel:[0,1] op_sel_hi:[0,1] neg_lo:[0,1] neg_hi:[0,1]
	v_pk_add_f32 v[48:49], v[18:19], v[12:13] op_sel:[0,1] op_sel_hi:[0,1]
	v_mov_b32_e32 v29, v17
	v_mul_f32_e32 v4, 0.5, v16
	v_mov_b32_e32 v50, v32
	v_mov_b32_e32 v51, v49
	v_pk_mul_f32 v[16:17], v[28:29], s[44:45]
	v_pk_mov_b32 v[48:49], v[48:49], v[32:33] op_sel:[1,0]
	v_pk_mul_f32 v[28:29], v[50:51], v[16:17] op_sel:[0,1] op_sel_hi:[1,0]
	v_pk_mul_f32 v[16:17], v[50:51], v[16:17]
	v_pk_add_f32 v[28:29], v[28:29], v[28:29] op_sel:[0,1] op_sel_hi:[0,1]
	v_pk_add_f32 v[52:53], v[4:5], v[28:29]
	v_pk_add_f32 v[28:29], v[4:5], v[28:29] op_sel_hi:[0,1] neg_lo:[0,1] neg_hi:[0,1]
	v_pk_add_f32 v[16:17], v[16:17], v[16:17] op_sel:[0,1] op_sel_hi:[0,1] neg_lo:[0,1] neg_hi:[0,1]
	v_mov_b32_e32 v53, v29
	v_pk_add_f32 v[28:29], v[6:7], v[16:17]
	v_pk_add_f32 v[16:17], v[6:7], v[16:17] op_sel_hi:[0,1] neg_lo:[0,1] neg_hi:[0,1]
	v_mov_b32_e32 v29, v17
	v_pk_mul_f32 v[16:17], v[28:29], v[180:181]
	v_pk_mul_f32 v[28:29], v[28:29], v[172:173]
	v_pk_fma_f32 v[16:17], v[52:53], v[172:173], v[16:17]
	v_pk_fma_f32 v[28:29], v[52:53], v[180:181], v[28:29] neg_lo:[0,0,1] neg_hi:[0,0,1]
	v_sub_f32_e32 v6, v89, v177
	v_pk_add_f32 v[52:53], v[28:29], v[16:17] op_sel:[0,1] op_sel_hi:[1,0] neg_lo:[0,1] neg_hi:[0,1]
	v_pk_add_f32 v[54:55], v[28:29], v[16:17] op_sel:[0,1] op_sel_hi:[1,0]
	v_pk_add_f32 v[16:17], v[16:17], v[28:29] op_sel:[1,0] op_sel_hi:[0,1] neg_lo:[0,1] neg_hi:[0,1]
	v_mov_b32_e32 v53, v55
	v_pk_mul_f32 v[52:53], v[52:53], 0.5 op_sel_hi:[1,0]
	v_mov_b32_e32 v55, v17
	v_mul_f32_e32 v4, v32, v52
	v_pk_fma_f32 v[56:57], v[50:51], v[52:53], v[4:5] op_sel_hi:[1,1,0] neg_lo:[1,0,0] neg_hi:[1,0,0]
	v_mul_f32_e32 v4, v32, v53
	v_pk_fma_f32 v[48:49], v[48:49], v[52:53], v[4:5] op_sel_hi:[1,1,0]
	v_pk_add_f32 v[28:29], v[88:89], v[176:177]
	v_mov_b32_e32 v56, v48
	v_pk_fma_f32 v[16:17], v[54:55], 0.5, v[48:49] op_sel_hi:[1,0,1] neg_lo:[0,0,1] neg_hi:[0,0,1]
	v_mov_b32_e32 v48, v12
	v_mov_b32_e32 v49, v88
	v_pk_mov_b32 v[12:13], v[12:13], v[176:177] op_sel:[1,0]
	v_mul_f32_e32 v18, 0.5, v29
	v_pk_add_f32 v[12:13], v[48:49], v[12:13] neg_lo:[0,1] neg_hi:[0,1]
	v_mul_f32_e32 v4, 0.5, v28
	v_pk_mul_f32 v[48:49], v[12:13], v[18:19]
	v_mov_b32_e32 v13, v32
	v_pk_fma_f32 v[50:51], v[50:51], v[48:49], v[48:49] op_sel:[0,1,0] op_sel_hi:[1,0,1]
	v_mov_b32_e32 v48, v49
	v_mov_b32_e32 v49, v18
	v_pk_mul_f32 v[48:49], v[12:13], v[48:49]
	v_pk_add_f32 v[52:53], v[4:5], v[50:51]
	v_mul_f32_e32 v6, 0.5, v6
	v_fma_f32 v53, v28, 0.5, -v50
	v_pk_add_f32 v[28:29], v[48:49], v[48:49] op_sel:[0,1] op_sel_hi:[0,1] neg_lo:[0,1] neg_hi:[0,1]
	v_pk_add_f32 v[48:49], v[6:7], v[28:29]
	v_pk_add_f32 v[28:29], v[6:7], v[28:29] op_sel_hi:[0,1] neg_lo:[0,1] neg_hi:[0,1]
	v_mov_b32_e32 v49, v29
	v_pk_mul_f32 v[28:29], v[48:49], v[178:179]
	v_pk_mul_f32 v[48:49], v[48:49], v[174:175]
	v_pk_fma_f32 v[28:29], v[52:53], v[174:175], v[28:29]
	v_pk_fma_f32 v[48:49], v[52:53], v[178:179], v[48:49] neg_lo:[0,0,1] neg_hi:[0,0,1]
	v_pk_fma_f32 v[92:93], v[54:55], 0.5, v[56:57] op_sel_hi:[1,0,1]
	v_pk_add_f32 v[50:51], v[48:49], v[28:29] op_sel:[0,1] op_sel_hi:[1,0] neg_lo:[0,1] neg_hi:[0,1]
	v_pk_add_f32 v[52:53], v[48:49], v[28:29] op_sel:[0,1] op_sel_hi:[1,0]
	v_mov_b32_e32 v17, v93
	v_mov_b32_e32 v51, v53
	v_pk_mul_f32 v[50:51], v[50:51], 0.5 op_sel_hi:[1,0]
	v_pk_mul_f32 v[64:65], v[16:17], s[46:47] op_sel_hi:[1,0]
	v_mul_f32_e32 v4, v12, v50
	v_pk_fma_f32 v[16:17], v[54:55], 0.5, v[56:57] op_sel_hi:[1,0,1] neg_lo:[1,0,0] neg_hi:[1,0,0]
	v_pk_fma_f32 v[54:55], v[12:13], v[50:51], v[4:5] op_sel_hi:[1,1,0] neg_lo:[1,0,0] neg_hi:[1,0,0]
	v_mov_b32_e32 v33, v12
	v_mul_f32_e32 v4, v12, v51
	v_pk_fma_f32 v[12:13], v[32:33], v[50:51], v[4:5] op_sel_hi:[1,1,0]
	v_pk_add_f32 v[28:29], v[28:29], v[48:49] op_sel:[1,0] op_sel_hi:[0,1] neg_lo:[0,1] neg_hi:[0,1]
	v_mov_b32_e32 v53, v29
	v_mov_b32_e32 v54, v12
	v_pk_fma_f32 v[12:13], v[52:53], 0.5, v[12:13] op_sel_hi:[1,0,1] neg_lo:[0,0,1] neg_hi:[0,0,1]
	v_pk_fma_f32 v[88:89], v[52:53], 0.5, v[54:55] op_sel_hi:[1,0,1]
	s_mov_b32 s67, s16
	v_mov_b32_e32 v13, v89
	v_pk_mul_f32 v[68:69], v[12:13], s[46:47] op_sel_hi:[1,0]
	v_pk_fma_f32 v[12:13], v[52:53], 0.5, v[54:55] op_sel_hi:[1,0,1] neg_lo:[1,0,0] neg_hi:[1,0,0]
	v_mov_b32_e32 v4, v83
	s_mov_b32 s17, s19
	v_pk_mul_f32 v[48:49], v[82:83], s[66:67] op_sel_hi:[0,1]
	v_pk_add_f32 v[28:29], v[96:97], v[162:163]
	v_pk_add_f32 v[32:33], v[96:97], v[162:163] neg_lo:[0,1] neg_hi:[0,1]
	v_pk_fma_f32 v[52:53], v[4:5], s[16:17], v[48:49] op_sel_hi:[0,1,1] neg_lo:[0,0,1] neg_hi:[0,0,1]
	v_mul_f32_e32 v12, 0.5, v33
	v_pk_fma_f32 v[50:51], v[4:5], s[16:17], v[48:49] op_sel_hi:[0,1,1]
	v_mov_b32_e32 v33, v29
	v_mul_f32_e32 v6, 0.5, v28
	v_mov_b32_e32 v54, v52
	v_mov_b32_e32 v55, v51
	v_pk_mul_f32 v[28:29], v[32:33], s[44:45]
	v_pk_mov_b32 v[56:57], v[50:51], v[52:53] op_sel:[1,0]
	v_pk_mul_f32 v[32:33], v[54:55], v[28:29] op_sel:[0,1] op_sel_hi:[1,0]
	v_pk_mul_f32 v[28:29], v[54:55], v[28:29]
	v_pk_add_f32 v[32:33], v[32:33], v[32:33] op_sel:[0,1] op_sel_hi:[0,1]
	v_pk_add_f32 v[58:59], v[6:7], v[32:33]
	v_pk_add_f32 v[32:33], v[6:7], v[32:33] op_sel_hi:[0,1] neg_lo:[0,1] neg_hi:[0,1]
	v_pk_add_f32 v[28:29], v[28:29], v[28:29] op_sel:[0,1] op_sel_hi:[0,1] neg_lo:[0,1] neg_hi:[0,1]
	v_mov_b32_e32 v59, v33
	v_pk_add_f32 v[32:33], v[12:13], v[28:29]
	v_pk_add_f32 v[28:29], v[12:13], v[28:29] op_sel_hi:[0,1] neg_lo:[0,1] neg_hi:[0,1]
	v_mov_b32_e32 v33, v29
	v_pk_mul_f32 v[28:29], v[32:33], v[166:167]
	v_pk_mul_f32 v[32:33], v[32:33], v[164:165]
	v_pk_fma_f32 v[28:29], v[58:59], v[164:165], v[28:29]
	v_pk_fma_f32 v[32:33], v[58:59], v[166:167], v[32:33] neg_lo:[0,0,1] neg_hi:[0,0,1]
	v_mov_b32_e32 v159, v66
	v_pk_add_f32 v[58:59], v[32:33], v[28:29] op_sel:[0,1] op_sel_hi:[1,0] neg_lo:[0,1] neg_hi:[0,1]
	v_pk_add_f32 v[70:71], v[32:33], v[28:29] op_sel:[0,1] op_sel_hi:[1,0]
	v_pk_add_f32 v[28:29], v[28:29], v[32:33] op_sel:[1,0] op_sel_hi:[0,1] neg_lo:[0,1] neg_hi:[0,1]
	v_mov_b32_e32 v59, v71
	v_pk_mul_f32 v[58:59], v[58:59], 0.5 op_sel_hi:[1,0]
	v_mov_b32_e32 v71, v29
	v_mul_f32_e32 v6, v52, v58
	v_pk_fma_f32 v[72:73], v[54:55], v[58:59], v[6:7] op_sel_hi:[1,1,0] neg_lo:[1,0,0] neg_hi:[1,0,0]
	v_mul_f32_e32 v6, v52, v59
	v_pk_fma_f32 v[56:57], v[56:57], v[58:59], v[6:7] op_sel_hi:[1,1,0]
	v_sub_f32_e32 v12, v67, v153
	v_mov_b32_e32 v72, v56
	v_pk_fma_f32 v[28:29], v[70:71], 0.5, v[56:57] op_sel_hi:[1,0,1] neg_lo:[0,0,1] neg_hi:[0,0,1]
	v_pk_fma_f32 v[96:97], v[70:71], 0.5, v[72:73] op_sel_hi:[1,0,1]
	v_pk_mov_b32 v[56:57], v[48:49], v[152:153] op_sel:[1,0]
	v_mov_b32_e32 v29, v97
	v_pk_mul_f32 v[62:63], v[28:29], s[46:47] op_sel_hi:[1,0]
	v_pk_add_f32 v[28:29], v[66:67], v[152:153]
	v_pk_add_f32 v[56:57], v[158:159], v[56:57] neg_lo:[0,1] neg_hi:[0,1]
	v_mul_f32_e32 v18, 0.5, v29
	v_pk_mul_f32 v[58:59], v[56:57], v[18:19]
	v_mul_f32_e32 v6, 0.5, v28
	v_pk_fma_f32 v[54:55], v[54:55], v[58:59], v[58:59] op_sel:[0,1,0] op_sel_hi:[1,0,1]
	v_mov_b32_e32 v66, v56
	v_mov_b32_e32 v67, v52
	v_mov_b32_e32 v58, v59
	v_mov_b32_e32 v59, v18
	v_pk_mul_f32 v[58:59], v[66:67], v[58:59]
	v_pk_add_f32 v[66:67], v[6:7], v[54:55]
	v_mul_f32_e32 v12, 0.5, v12
	v_fma_f32 v67, v28, 0.5, -v54
	v_pk_add_f32 v[28:29], v[58:59], v[58:59] op_sel:[0,1] op_sel_hi:[0,1] neg_lo:[0,1] neg_hi:[0,1]
	v_pk_add_f32 v[54:55], v[12:13], v[28:29]
	v_pk_add_f32 v[28:29], v[12:13], v[28:29] op_sel_hi:[0,1] neg_lo:[0,1] neg_hi:[0,1]
	v_mov_b32_e32 v55, v29
	v_pk_mul_f32 v[28:29], v[54:55], v[156:157]
	v_pk_mul_f32 v[54:55], v[54:55], v[154:155]
	v_pk_fma_f32 v[32:33], v[70:71], 0.5, v[72:73] op_sel_hi:[1,0,1] neg_lo:[1,0,0] neg_hi:[1,0,0]
	v_pk_fma_f32 v[58:59], v[66:67], v[154:155], v[28:29] neg_lo:[0,0,1] neg_hi:[0,0,1]
	v_pk_fma_f32 v[28:29], v[66:67], v[154:155], v[28:29]
	v_pk_fma_f32 v[70:71], v[66:67], v[156:157], v[54:55]
	v_pk_fma_f32 v[54:55], v[66:67], v[156:157], v[54:55] neg_lo:[0,0,1] neg_hi:[0,0,1]
	v_pk_add_f32 v[72:73], v[58:59], v[28:29] op_sel:[0,1] op_sel_hi:[1,0]
	v_pk_add_f32 v[66:67], v[70:71], v[54:55] op_sel_hi:[0,1] neg_lo:[0,1] neg_hi:[0,1]
	v_pk_add_f32 v[28:29], v[58:59], v[28:29] op_sel_hi:[0,1] neg_lo:[0,1] neg_hi:[0,1]
	v_pk_add_f32 v[54:55], v[70:71], v[54:55] op_sel:[0,1] op_sel_hi:[1,0]
	v_mov_b32_e32 v73, v67
	v_mov_b32_e32 v55, v29
	v_pk_mul_f32 v[28:29], v[54:55], 0.5 op_sel_hi:[1,0]
	v_mov_b32_e32 v133, v84
	v_pk_mul_f32 v[54:55], v[52:53], v[28:29] op_sel:[0,1] op_sel_hi:[0,0]
	v_pk_fma_f32 v[58:59], v[56:57], v[28:29], v[54:55] op_sel_hi:[0,1,1]
	v_pk_fma_f32 v[28:29], v[56:57], v[28:29], v[54:55] op_sel_hi:[0,1,1] neg_lo:[0,0,1] neg_hi:[0,0,1]
	v_mov_b32_e32 v28, v58
	v_pk_fma_f32 v[54:55], v[72:73], 0.5, v[58:59] op_sel_hi:[1,0,1] neg_lo:[0,0,1] neg_hi:[0,0,1]
	v_pk_fma_f32 v[66:67], v[72:73], 0.5, v[28:29] op_sel_hi:[1,0,1]
	v_pk_add_f32 v[56:57], v[60:61], v[134:135] neg_lo:[0,1] neg_hi:[0,1]
	v_mov_b32_e32 v55, v67
	v_pk_mul_f32 v[90:91], v[54:55], s[46:47] op_sel_hi:[1,0]
	v_pk_add_f32 v[54:55], v[134:135], v[60:61]
	v_mul_f32_e32 v12, 0.5, v57
	v_mov_b32_e32 v57, v55
	v_mul_f32_e32 v6, 0.5, v54
	v_pk_mov_b32 v[58:59], v[52:53], v[50:51] op_sel:[1,0]
	v_pk_mul_f32 v[54:55], v[56:57], s[44:45]
	v_pk_fma_f32 v[28:29], v[72:73], 0.5, v[28:29] op_sel_hi:[1,0,1] neg_lo:[1,0,0] neg_hi:[1,0,0]
	v_pk_mul_f32 v[56:57], v[58:59], v[54:55] op_sel:[0,1] op_sel_hi:[1,0]
	v_pk_mul_f32 v[54:55], v[58:59], v[54:55]
	v_pk_add_f32 v[56:57], v[56:57], v[56:57] op_sel:[0,1] op_sel_hi:[0,1]
	v_pk_add_f32 v[60:61], v[6:7], v[56:57]
	v_pk_add_f32 v[56:57], v[6:7], v[56:57] op_sel_hi:[0,1] neg_lo:[0,1] neg_hi:[0,1]
	v_pk_add_f32 v[54:55], v[54:55], v[54:55] op_sel:[0,1] op_sel_hi:[0,1] neg_lo:[0,1] neg_hi:[0,1]
	v_mov_b32_e32 v61, v57
	v_pk_add_f32 v[56:57], v[12:13], v[54:55]
	v_pk_add_f32 v[54:55], v[12:13], v[54:55] op_sel_hi:[0,1] neg_lo:[0,1] neg_hi:[0,1]
	v_mov_b32_e32 v57, v55
	v_pk_mul_f32 v[54:55], v[56:57], v[142:143]
	v_pk_mul_f32 v[56:57], v[56:57], v[140:141]
	v_pk_fma_f32 v[54:55], v[60:61], v[140:141], v[54:55]
	v_pk_fma_f32 v[56:57], v[60:61], v[142:143], v[56:57] neg_lo:[0,0,1] neg_hi:[0,0,1]
	v_mov_b32_e32 v51, v53
	v_pk_add_f32 v[60:61], v[56:57], v[54:55] op_sel:[0,1] op_sel_hi:[1,0] neg_lo:[0,1] neg_hi:[0,1]
	v_pk_add_f32 v[70:71], v[56:57], v[54:55] op_sel:[0,1] op_sel_hi:[1,0]
	v_pk_add_f32 v[54:55], v[54:55], v[56:57] op_sel:[1,0] op_sel_hi:[0,1] neg_lo:[0,1] neg_hi:[0,1]
	v_mov_b32_e32 v61, v71
	v_pk_mul_f32 v[60:61], v[60:61], 0.5 op_sel_hi:[1,0]
	v_mov_b32_e32 v71, v55
	v_mul_f32_e32 v6, v53, v60
	v_pk_fma_f32 v[72:73], v[58:59], v[60:61], v[6:7] op_sel_hi:[1,1,0] neg_lo:[1,0,0] neg_hi:[1,0,0]
	v_mul_f32_e32 v6, v53, v61
	v_pk_fma_f32 v[50:51], v[50:51], v[60:61], v[6:7] op_sel_hi:[1,1,0]
	v_pk_add_f32 v[54:55], v[118:119], v[84:85]
	v_mov_b32_e32 v72, v50
	v_mov_b32_e32 v49, v118
	v_pk_fma_f32 v[50:51], v[70:71], 0.5, v[50:51] op_sel_hi:[1,0,1] neg_lo:[0,0,1] neg_hi:[0,0,1]
	v_pk_fma_f32 v[60:61], v[70:71], 0.5, v[72:73] op_sel_hi:[1,0,1]
	v_mul_f32_e32 v18, 0.5, v55
	v_pk_add_f32 v[48:49], v[132:133], v[48:49] neg_lo:[0,1] neg_hi:[0,1]
	v_mov_b32_e32 v51, v61
	v_pk_mul_f32 v[56:57], v[48:49], v[18:19]
	v_pk_mul_f32 v[94:95], v[50:51], s[46:47] op_sel_hi:[1,0]
	v_pk_fma_f32 v[50:51], v[70:71], 0.5, v[72:73] op_sel_hi:[1,0,1] neg_lo:[1,0,0] neg_hi:[1,0,0]
	v_mul_f32_e32 v6, 0.5, v54
	v_pk_fma_f32 v[58:59], v[58:59], v[56:57], v[56:57] op_sel:[0,1,0] op_sel_hi:[1,0,1]
	v_mov_b32_e32 v70, v48
	v_mov_b32_e32 v71, v53
	v_mov_b32_e32 v56, v57
	v_mov_b32_e32 v57, v18
	v_sub_f32_e32 v12, v85, v119
	v_pk_mul_f32 v[56:57], v[70:71], v[56:57]
	v_pk_add_f32 v[70:71], v[6:7], v[58:59]
	v_mul_f32_e32 v12, 0.5, v12
	v_fma_f32 v71, v54, 0.5, -v58
	v_pk_add_f32 v[54:55], v[56:57], v[56:57] op_sel:[0,1] op_sel_hi:[0,1] neg_lo:[0,1] neg_hi:[0,1]
	v_pk_add_f32 v[56:57], v[12:13], v[54:55]
	v_pk_add_f32 v[54:55], v[12:13], v[54:55] op_sel_hi:[0,1] neg_lo:[0,1] neg_hi:[0,1]
	v_mov_b32_e32 v57, v55
	v_pk_mul_f32 v[54:55], v[56:57], v[126:127]
	v_pk_mul_f32 v[56:57], v[56:57], v[124:125]
	v_pk_fma_f32 v[58:59], v[70:71], v[124:125], v[54:55] neg_lo:[0,0,1] neg_hi:[0,0,1]
	v_pk_fma_f32 v[54:55], v[70:71], v[124:125], v[54:55]
	v_pk_fma_f32 v[72:73], v[70:71], v[126:127], v[56:57]
	v_pk_fma_f32 v[56:57], v[70:71], v[126:127], v[56:57] neg_lo:[0,0,1] neg_hi:[0,0,1]
	v_pk_add_f32 v[70:71], v[58:59], v[54:55] op_sel:[0,1] op_sel_hi:[1,0]
	v_pk_add_f32 v[74:75], v[72:73], v[56:57] op_sel_hi:[0,1] neg_lo:[0,1] neg_hi:[0,1]
	v_pk_add_f32 v[54:55], v[58:59], v[54:55] op_sel_hi:[0,1] neg_lo:[0,1] neg_hi:[0,1]
	v_pk_add_f32 v[56:57], v[72:73], v[56:57] op_sel:[0,1] op_sel_hi:[1,0]
	v_mov_b32_e32 v71, v75
	v_mov_b32_e32 v57, v55
	v_pk_mul_f32 v[54:55], v[56:57], 0.5 op_sel_hi:[1,0]
	s_mov_b32 s66, s11
	v_pk_mul_f32 v[52:53], v[52:53], v[54:55] op_sel:[1,1] op_sel_hi:[1,0]
	s_mov_b32 s67, s8
	v_pk_fma_f32 v[56:57], v[48:49], v[54:55], v[52:53] op_sel_hi:[0,1,1]
	v_pk_fma_f32 v[48:49], v[48:49], v[54:55], v[52:53] op_sel_hi:[0,1,1] neg_lo:[0,0,1] neg_hi:[0,0,1]
	v_mov_b32_e32 v48, v56
	v_pk_fma_f32 v[52:53], v[70:71], 0.5, v[56:57] op_sel_hi:[1,0,1] neg_lo:[0,0,1] neg_hi:[0,0,1]
	v_pk_fma_f32 v[84:85], v[70:71], 0.5, v[48:49] op_sel_hi:[1,0,1]
	s_mov_b32 s9, s11
	v_mov_b32_e32 v53, v85
	v_pk_mul_f32 v[80:81], v[52:53], s[46:47] op_sel_hi:[1,0]
	v_pk_mul_f32 v[118:119], v[82:83], s[66:67] op_sel_hi:[0,1]
	v_pk_add_f32 v[52:53], v[86:87], v[112:113]
	v_pk_add_f32 v[54:55], v[86:87], v[112:113] neg_lo:[0,1] neg_hi:[0,1]
	v_pk_fma_f32 v[58:59], v[4:5], s[8:9], v[118:119] op_sel_hi:[0,1,1] neg_lo:[0,0,1] neg_hi:[0,0,1]
	v_mul_f32_e32 v12, 0.5, v55
	v_pk_fma_f32 v[72:73], v[4:5], s[8:9], v[118:119] op_sel_hi:[0,1,1]
	v_mov_b32_e32 v55, v53
	v_mul_f32_e32 v6, 0.5, v52
	v_mov_b32_e32 v56, v58
	v_mov_b32_e32 v57, v73
	v_pk_mul_f32 v[52:53], v[54:55], s[44:45]
	v_pk_fma_f32 v[48:49], v[70:71], 0.5, v[48:49] op_sel_hi:[1,0,1] neg_lo:[1,0,0] neg_hi:[1,0,0]
	v_pk_mul_f32 v[54:55], v[56:57], v[52:53] op_sel:[0,1] op_sel_hi:[1,0]
	v_pk_mul_f32 v[52:53], v[56:57], v[52:53]
	v_pk_add_f32 v[54:55], v[54:55], v[54:55] op_sel:[0,1] op_sel_hi:[0,1]
	v_pk_add_f32 v[74:75], v[6:7], v[54:55]
	v_pk_add_f32 v[54:55], v[6:7], v[54:55] op_sel_hi:[0,1] neg_lo:[0,1] neg_hi:[0,1]
	v_pk_add_f32 v[52:53], v[52:53], v[52:53] op_sel:[0,1] op_sel_hi:[0,1] neg_lo:[0,1] neg_hi:[0,1]
	v_mov_b32_e32 v75, v55
	v_pk_add_f32 v[54:55], v[12:13], v[52:53]
	v_pk_add_f32 v[52:53], v[12:13], v[52:53] op_sel_hi:[0,1] neg_lo:[0,1] neg_hi:[0,1]
	v_mov_b32_e32 v55, v53
	v_pk_mul_f32 v[52:53], v[54:55], v[116:117]
	v_pk_mul_f32 v[54:55], v[54:55], v[114:115]
	v_pk_fma_f32 v[52:53], v[74:75], v[114:115], v[52:53]
	v_pk_fma_f32 v[54:55], v[74:75], v[116:117], v[54:55] neg_lo:[0,0,1] neg_hi:[0,0,1]
	v_pk_mov_b32 v[70:71], v[72:73], v[58:59] op_sel:[1,0]
	v_pk_add_f32 v[74:75], v[54:55], v[52:53] op_sel:[0,1] op_sel_hi:[1,0] neg_lo:[0,1] neg_hi:[0,1]
	v_pk_add_f32 v[76:77], v[54:55], v[52:53] op_sel:[0,1] op_sel_hi:[1,0]
	v_pk_add_f32 v[52:53], v[52:53], v[54:55] op_sel:[1,0] op_sel_hi:[0,1] neg_lo:[0,1] neg_hi:[0,1]
	v_mov_b32_e32 v75, v77
	v_pk_mul_f32 v[74:75], v[74:75], 0.5 op_sel_hi:[1,0]
	v_mov_b32_e32 v77, v53
	v_mul_f32_e32 v6, v58, v74
	v_pk_fma_f32 v[112:113], v[56:57], v[74:75], v[6:7] op_sel_hi:[1,1,0] neg_lo:[1,0,0] neg_hi:[1,0,0]
	v_mul_f32_e32 v6, v58, v75
	v_pk_fma_f32 v[70:71], v[70:71], v[74:75], v[6:7] op_sel_hi:[1,1,0]
	v_pk_add_f32 v[54:55], v[34:35], v[110:111]
	v_mov_b32_e32 v112, v70
	v_pk_fma_f32 v[52:53], v[76:77], 0.5, v[70:71] op_sel_hi:[1,0,1] neg_lo:[0,0,1] neg_hi:[0,0,1]
	v_pk_fma_f32 v[86:87], v[76:77], 0.5, v[112:113] op_sel_hi:[1,0,1]
	v_sub_f32_e32 v12, v35, v111
	v_mov_b32_e32 v53, v87
	v_pk_mul_f32 v[78:79], v[52:53], s[46:47] op_sel_hi:[1,0]
	v_mul_f32_e32 v52, 0xbe47c5c2, v83
	v_mov_b32_e32 v53, v34
	v_pk_mov_b32 v[34:35], v[118:119], v[110:111] op_sel:[1,0]
	v_mul_f32_e32 v18, 0.5, v55
	v_pk_add_f32 v[34:35], v[52:53], v[34:35] neg_lo:[0,1] neg_hi:[0,1]
	v_mov_b32_e32 v71, v58
	v_pk_mul_f32 v[52:53], v[34:35], v[18:19]
	v_mov_b32_e32 v70, v34
	v_pk_fma_f32 v[56:57], v[56:57], v[52:53], v[52:53] op_sel:[0,1,0] op_sel_hi:[1,0,1]
	v_mov_b32_e32 v52, v53
	v_mov_b32_e32 v53, v18
	v_mul_f32_e32 v6, 0.5, v54
	v_pk_mul_f32 v[52:53], v[70:71], v[52:53]
	v_cvt_f32_f16_e32 v70, v46
	v_cvt_f32_f16_e32 v71, v47
	v_cvt_f32_f16_sdwa v47, v47 dst_sel:DWORD dst_unused:UNUSED_PAD src0_sel:WORD_1
	v_cvt_f32_f16_sdwa v46, v46 dst_sel:DWORD dst_unused:UNUSED_PAD src0_sel:WORD_1
	v_pk_fma_f32 v[74:75], v[76:77], 0.5, v[112:113] op_sel_hi:[1,0,1] neg_lo:[1,0,0] neg_hi:[1,0,0]
	v_mul_f32_e32 v12, 0.5, v12
	v_pk_add_f32 v[76:77], v[6:7], v[56:57]
	v_pk_add_f32 v[52:53], v[52:53], v[52:53] op_sel:[0,1] op_sel_hi:[0,1] neg_lo:[0,1] neg_hi:[0,1]
	v_fma_f32 v77, v54, 0.5, -v56
	v_pk_add_f32 v[54:55], v[12:13], v[52:53]
	v_pk_add_f32 v[52:53], v[12:13], v[52:53] op_sel_hi:[0,1] neg_lo:[0,1] neg_hi:[0,1]
	v_mov_b32_e32 v55, v53
	v_pk_mul_f32 v[52:53], v[54:55], v[46:47]
	v_pk_mul_f32 v[54:55], v[54:55], v[70:71]
	v_pk_fma_f32 v[56:57], v[76:77], v[70:71], v[52:53] neg_lo:[0,0,1] neg_hi:[0,0,1]
	v_pk_fma_f32 v[52:53], v[76:77], v[70:71], v[52:53]
	v_pk_fma_f32 v[70:71], v[76:77], v[46:47], v[54:55]
	v_pk_fma_f32 v[46:47], v[76:77], v[46:47], v[54:55] neg_lo:[0,0,1] neg_hi:[0,0,1]
	v_pk_add_f32 v[54:55], v[56:57], v[52:53] op_sel:[0,1] op_sel_hi:[1,0]
	v_pk_add_f32 v[76:77], v[70:71], v[46:47] op_sel_hi:[0,1] neg_lo:[0,1] neg_hi:[0,1]
	v_pk_add_f32 v[52:53], v[56:57], v[52:53] op_sel_hi:[0,1] neg_lo:[0,1] neg_hi:[0,1]
	v_pk_add_f32 v[46:47], v[70:71], v[46:47] op_sel:[0,1] op_sel_hi:[1,0]
	v_mov_b32_e32 v55, v77
	v_mov_b32_e32 v47, v53
	v_pk_mul_f32 v[46:47], v[46:47], 0.5 op_sel_hi:[1,0]
	s_mov_b32 s25, s27
	v_pk_mul_f32 v[52:53], v[58:59], v[46:47] op_sel:[0,1] op_sel_hi:[0,0]
	v_pk_fma_f32 v[56:57], v[34:35], v[46:47], v[52:53] op_sel_hi:[0,1,1]
	v_pk_fma_f32 v[46:47], v[34:35], v[46:47], v[52:53] op_sel_hi:[0,1,1] neg_lo:[0,0,1] neg_hi:[0,0,1]
	v_mov_b32_e32 v46, v56
	v_pk_fma_f32 v[52:53], v[54:55], 0.5, v[56:57] op_sel_hi:[1,0,1] neg_lo:[0,0,1] neg_hi:[0,0,1]
	v_pk_fma_f32 v[34:35], v[54:55], 0.5, v[46:47] op_sel_hi:[1,0,1]
	s_mov_b32 s66, s27
	v_mov_b32_e32 v53, v35
	v_pk_mul_f32 v[136:137], v[52:53], s[46:47] op_sel_hi:[1,0]
	v_pk_fma_f32 v[52:53], v[54:55], 0.5, v[46:47] op_sel_hi:[1,0,1] neg_lo:[1,0,0] neg_hi:[1,0,0]
	s_mov_b32 s67, s24
	v_pk_mul_f32 v[46:47], v[82:83], s[24:25] op_sel_hi:[0,1]
	v_pk_add_f32 v[54:55], v[108:109], v[40:41]
	v_pk_add_f32 v[40:41], v[40:41], v[108:109] neg_lo:[0,1] neg_hi:[0,1]
	v_pk_fma_f32 v[108:109], v[4:5], s[66:67], v[46:47] op_sel_hi:[0,1,1] neg_lo:[0,0,1] neg_hi:[0,0,1]
	v_mul_f32_e32 v12, 0.5, v41
	v_pk_fma_f32 v[70:71], v[4:5], s[66:67], v[46:47] op_sel_hi:[0,1,1]
	v_mov_b32_e32 v41, v55
	v_mov_b32_e32 v56, v108
	v_mov_b32_e32 v57, v71
	v_pk_mul_f32 v[40:41], v[40:41], s[44:45]
	v_mul_f32_e32 v6, 0.5, v54
	v_pk_mul_f32 v[54:55], v[56:57], v[40:41] op_sel:[0,1] op_sel_hi:[1,0]
	v_cvt_f32_f16_sdwa v76, v38 dst_sel:DWORD dst_unused:UNUSED_PAD src0_sel:WORD_1
	v_cvt_f32_f16_e32 v77, v39
	v_cvt_f32_f16_sdwa v39, v39 dst_sel:DWORD dst_unused:UNUSED_PAD src0_sel:WORD_1
	v_cvt_f32_f16_e32 v38, v38
	v_pk_mul_f32 v[40:41], v[56:57], v[40:41]
	v_pk_add_f32 v[54:55], v[54:55], v[54:55] op_sel:[0,1] op_sel_hi:[0,1]
	v_pk_add_f32 v[112:113], v[6:7], v[54:55]
	v_pk_add_f32 v[54:55], v[6:7], v[54:55] op_sel_hi:[0,1] neg_lo:[0,1] neg_hi:[0,1]
	v_pk_add_f32 v[40:41], v[40:41], v[40:41] op_sel:[0,1] op_sel_hi:[0,1] neg_lo:[0,1] neg_hi:[0,1]
	v_mov_b32_e32 v113, v55
	v_pk_add_f32 v[54:55], v[12:13], v[40:41]
	v_pk_add_f32 v[40:41], v[12:13], v[40:41] op_sel_hi:[0,1] neg_lo:[0,1] neg_hi:[0,1]
	v_mov_b32_e32 v55, v41
	v_pk_mul_f32 v[40:41], v[54:55], v[38:39]
	v_pk_mul_f32 v[54:55], v[54:55], v[76:77]
	v_pk_fma_f32 v[40:41], v[112:113], v[76:77], v[40:41]
	v_pk_fma_f32 v[38:39], v[112:113], v[38:39], v[54:55] neg_lo:[0,0,1] neg_hi:[0,0,1]
	v_pk_mov_b32 v[110:111], v[70:71], v[108:109] op_sel:[1,0]
	v_pk_add_f32 v[54:55], v[38:39], v[40:41] op_sel:[0,1] op_sel_hi:[1,0] neg_lo:[0,1] neg_hi:[0,1]
	v_pk_add_f32 v[76:77], v[38:39], v[40:41] op_sel:[0,1] op_sel_hi:[1,0]
	v_pk_add_f32 v[38:39], v[40:41], v[38:39] op_sel:[1,0] op_sel_hi:[0,1] neg_lo:[0,1] neg_hi:[0,1]
	v_mov_b32_e32 v55, v77
	v_pk_mul_f32 v[54:55], v[54:55], 0.5 op_sel_hi:[1,0]
	v_mov_b32_e32 v77, v39
	v_mul_f32_e32 v4, v108, v54
	v_pk_fma_f32 v[112:113], v[56:57], v[54:55], v[4:5] op_sel_hi:[1,1,0] neg_lo:[1,0,0] neg_hi:[1,0,0]
	v_mul_f32_e32 v4, v108, v55
	v_pk_fma_f32 v[54:55], v[110:111], v[54:55], v[4:5] op_sel_hi:[1,1,0]
	v_sub_f32_e32 v6, v45, v105
	v_mov_b32_e32 v112, v54
	v_pk_fma_f32 v[40:41], v[76:77], 0.5, v[54:55] op_sel_hi:[1,0,1] neg_lo:[0,0,1] neg_hi:[0,0,1]
	v_pk_fma_f32 v[38:39], v[76:77], 0.5, v[112:113] op_sel_hi:[1,0,1]
	v_pk_add_f32 v[54:55], v[104:105], v[44:45]
	v_mov_b32_e32 v41, v39
	v_pk_mul_f32 v[130:131], v[40:41], s[46:47] op_sel_hi:[1,0]
	v_mul_f32_e32 v40, 0xbf54db31, v83
	v_mov_b32_e32 v41, v44
	v_pk_mov_b32 v[44:45], v[46:47], v[104:105] op_sel:[1,0]
	v_mul_f32_e32 v18, 0.5, v55
	v_pk_add_f32 v[40:41], v[40:41], v[44:45] neg_lo:[0,1] neg_hi:[0,1]
	v_mov_b32_e32 v105, v108
	v_pk_mul_f32 v[44:45], v[40:41], v[18:19]
	v_mov_b32_e32 v104, v40
	v_pk_fma_f32 v[56:57], v[56:57], v[44:45], v[44:45] op_sel:[0,1,0] op_sel_hi:[1,0,1]
	v_mov_b32_e32 v44, v45
	v_mov_b32_e32 v45, v18
	v_mul_f32_e32 v4, 0.5, v54
	v_pk_mul_f32 v[44:45], v[104:105], v[44:45]
	v_cvt_f32_f16_e32 v104, v26
	v_cvt_f32_f16_e32 v105, v27
	v_cvt_f32_f16_sdwa v27, v27 dst_sel:DWORD dst_unused:UNUSED_PAD src0_sel:WORD_1
	v_cvt_f32_f16_sdwa v26, v26 dst_sel:DWORD dst_unused:UNUSED_PAD src0_sel:WORD_1
	v_mul_f32_e32 v6, 0.5, v6
	v_pk_add_f32 v[110:111], v[4:5], v[56:57]
	v_pk_add_f32 v[44:45], v[44:45], v[44:45] op_sel:[0,1] op_sel_hi:[0,1] neg_lo:[0,1] neg_hi:[0,1]
	v_fma_f32 v111, v54, 0.5, -v56
	v_pk_add_f32 v[54:55], v[6:7], v[44:45]
	v_pk_add_f32 v[44:45], v[6:7], v[44:45] op_sel_hi:[0,1] neg_lo:[0,1] neg_hi:[0,1]
	v_mov_b32_e32 v55, v45
	v_pk_mul_f32 v[44:45], v[54:55], v[26:27]
	v_pk_mul_f32 v[54:55], v[54:55], v[104:105]
	v_pk_fma_f32 v[56:57], v[110:111], v[104:105], v[44:45] neg_lo:[0,0,1] neg_hi:[0,0,1]
	v_pk_fma_f32 v[44:45], v[110:111], v[104:105], v[44:45]
	v_pk_fma_f32 v[104:105], v[110:111], v[26:27], v[54:55]
	v_pk_fma_f32 v[26:27], v[110:111], v[26:27], v[54:55] neg_lo:[0,0,1] neg_hi:[0,0,1]
	v_pk_add_f32 v[54:55], v[56:57], v[44:45] op_sel:[0,1] op_sel_hi:[1,0]
	v_pk_add_f32 v[110:111], v[104:105], v[26:27] op_sel_hi:[0,1] neg_lo:[0,1] neg_hi:[0,1]
	v_pk_add_f32 v[44:45], v[56:57], v[44:45] op_sel_hi:[0,1] neg_lo:[0,1] neg_hi:[0,1]
	v_pk_add_f32 v[26:27], v[104:105], v[26:27] op_sel:[0,1] op_sel_hi:[1,0]
	v_mov_b32_e32 v55, v111
	v_mov_b32_e32 v27, v45
	v_pk_mul_f32 v[26:27], v[26:27], 0.5 op_sel_hi:[1,0]
	v_mov_b32_e32 v47, v102
	v_pk_mul_f32 v[44:45], v[108:109], v[26:27] op_sel:[0,1] op_sel_hi:[0,0]
	v_pk_fma_f32 v[56:57], v[40:41], v[26:27], v[44:45] op_sel_hi:[0,1,1]
	v_pk_fma_f32 v[40:41], v[40:41], v[26:27], v[44:45] op_sel_hi:[0,1,1] neg_lo:[0,0,1] neg_hi:[0,0,1]
	v_mov_b32_e32 v40, v56
	v_pk_fma_f32 v[44:45], v[54:55], 0.5, v[56:57] op_sel_hi:[1,0,1] neg_lo:[0,0,1] neg_hi:[0,0,1]
	v_pk_fma_f32 v[26:27], v[54:55], 0.5, v[40:41] op_sel_hi:[1,0,1]
	v_pk_fma_f32 v[56:57], v[54:55], 0.5, v[40:41] op_sel_hi:[1,0,1] neg_lo:[1,0,0] neg_hi:[1,0,0]
	v_pk_add_f32 v[40:41], v[106:107], v[42:43]
	v_pk_add_f32 v[42:43], v[42:43], v[106:107] neg_lo:[0,1] neg_hi:[0,1]
	v_mov_b32_e32 v45, v27
	v_mul_f32_e32 v6, 0.5, v43
	v_mov_b32_e32 v43, v41
	v_pk_mul_f32 v[120:121], v[44:45], s[46:47] op_sel_hi:[1,0]
	v_mul_f32_e32 v4, 0.5, v40
	v_pk_mov_b32 v[44:45], v[108:109], v[70:71] op_sel:[1,0]
	v_pk_mul_f32 v[40:41], v[42:43], s[44:45]
	v_cvt_f32_f16_sdwa v54, v20 dst_sel:DWORD dst_unused:UNUSED_PAD src0_sel:WORD_1
	v_pk_mul_f32 v[42:43], v[44:45], v[40:41] op_sel:[0,1] op_sel_hi:[1,0]
	v_cvt_f32_f16_e32 v55, v21
	v_cvt_f32_f16_sdwa v21, v21 dst_sel:DWORD dst_unused:UNUSED_PAD src0_sel:WORD_1
	v_cvt_f32_f16_e32 v20, v20
	v_pk_mul_f32 v[40:41], v[44:45], v[40:41]
	v_pk_add_f32 v[42:43], v[42:43], v[42:43] op_sel:[0,1] op_sel_hi:[0,1]
	v_pk_add_f32 v[104:105], v[4:5], v[42:43]
	v_pk_add_f32 v[42:43], v[4:5], v[42:43] op_sel_hi:[0,1] neg_lo:[0,1] neg_hi:[0,1]
	v_pk_add_f32 v[40:41], v[40:41], v[40:41] op_sel:[0,1] op_sel_hi:[0,1] neg_lo:[0,1] neg_hi:[0,1]
	v_mov_b32_e32 v105, v43
	v_pk_add_f32 v[42:43], v[6:7], v[40:41]
	v_pk_add_f32 v[40:41], v[6:7], v[40:41] op_sel_hi:[0,1] neg_lo:[0,1] neg_hi:[0,1]
	v_mov_b32_e32 v43, v41
	v_pk_mul_f32 v[40:41], v[42:43], v[20:21]
	v_pk_mul_f32 v[42:43], v[42:43], v[54:55]
	v_pk_fma_f32 v[40:41], v[104:105], v[54:55], v[40:41]
	v_pk_fma_f32 v[20:21], v[104:105], v[20:21], v[42:43] neg_lo:[0,0,1] neg_hi:[0,0,1]
	v_mov_b32_e32 v71, v109
	v_pk_add_f32 v[42:43], v[20:21], v[40:41] op_sel:[0,1] op_sel_hi:[1,0] neg_lo:[0,1] neg_hi:[0,1]
	v_pk_add_f32 v[54:55], v[20:21], v[40:41] op_sel:[0,1] op_sel_hi:[1,0]
	v_pk_add_f32 v[20:21], v[40:41], v[20:21] op_sel:[1,0] op_sel_hi:[0,1] neg_lo:[0,1] neg_hi:[0,1]
	v_mov_b32_e32 v43, v55
	v_pk_mul_f32 v[42:43], v[42:43], 0.5 op_sel_hi:[1,0]
	v_mov_b32_e32 v55, v21
	v_mul_f32_e32 v4, v109, v42
	v_pk_fma_f32 v[104:105], v[44:45], v[42:43], v[4:5] op_sel_hi:[1,1,0] neg_lo:[1,0,0] neg_hi:[1,0,0]
	v_mul_f32_e32 v4, v109, v43
	v_pk_fma_f32 v[42:43], v[70:71], v[42:43], v[4:5] op_sel_hi:[1,1,0]
	v_sub_f32_e32 v6, v23, v103
	v_mov_b32_e32 v104, v42
	v_pk_fma_f32 v[40:41], v[54:55], 0.5, v[42:43] op_sel_hi:[1,0,1] neg_lo:[0,0,1] neg_hi:[0,0,1]
	v_pk_fma_f32 v[20:21], v[54:55], 0.5, v[104:105] op_sel_hi:[1,0,1]
	v_pk_add_f32 v[42:43], v[102:103], v[22:23]
	v_mov_b32_e32 v41, v21
	v_pk_mul_f32 v[128:129], v[40:41], s[46:47] op_sel_hi:[1,0]
	v_mul_f32_e32 v40, 0xbf0e39da, v83
	v_mov_b32_e32 v41, v22
	v_mul_f32_e32 v18, 0.5, v43
	v_pk_add_f32 v[22:23], v[40:41], v[46:47] neg_lo:[0,1] neg_hi:[0,1]
	v_mov_b32_e32 v47, v109
	v_pk_mul_f32 v[40:41], v[22:23], v[18:19]
	v_mov_b32_e32 v46, v22
	v_pk_fma_f32 v[44:45], v[44:45], v[40:41], v[40:41] op_sel:[0,1,0] op_sel_hi:[1,0,1]
	v_mov_b32_e32 v40, v41
	v_mov_b32_e32 v41, v18
	v_mul_f32_e32 v4, 0.5, v42
	v_pk_mul_f32 v[40:41], v[46:47], v[40:41]
	v_cvt_f32_f16_e32 v46, v10
	v_cvt_f32_f16_e32 v47, v11
	v_cvt_f32_f16_sdwa v11, v11 dst_sel:DWORD dst_unused:UNUSED_PAD src0_sel:WORD_1
	v_cvt_f32_f16_sdwa v10, v10 dst_sel:DWORD dst_unused:UNUSED_PAD src0_sel:WORD_1
	v_pk_fma_f32 v[70:71], v[54:55], 0.5, v[104:105] op_sel_hi:[1,0,1] neg_lo:[1,0,0] neg_hi:[1,0,0]
	v_mul_f32_e32 v6, 0.5, v6
	v_pk_add_f32 v[54:55], v[4:5], v[44:45]
	v_pk_add_f32 v[40:41], v[40:41], v[40:41] op_sel:[0,1] op_sel_hi:[0,1] neg_lo:[0,1] neg_hi:[0,1]
	v_fma_f32 v55, v42, 0.5, -v44
	v_pk_add_f32 v[42:43], v[6:7], v[40:41]
	v_pk_add_f32 v[40:41], v[6:7], v[40:41] op_sel_hi:[0,1] neg_lo:[0,1] neg_hi:[0,1]
	v_mov_b32_e32 v43, v41
	v_pk_mul_f32 v[40:41], v[42:43], v[10:11]
	v_pk_mul_f32 v[42:43], v[42:43], v[46:47]
	v_pk_fma_f32 v[44:45], v[54:55], v[46:47], v[40:41] neg_lo:[0,0,1] neg_hi:[0,0,1]
	v_pk_fma_f32 v[40:41], v[54:55], v[46:47], v[40:41]
	v_pk_fma_f32 v[46:47], v[54:55], v[10:11], v[42:43]
	v_pk_fma_f32 v[10:11], v[54:55], v[10:11], v[42:43] neg_lo:[0,0,1] neg_hi:[0,0,1]
	v_pk_add_f32 v[42:43], v[44:45], v[40:41] op_sel:[0,1] op_sel_hi:[1,0]
	v_pk_add_f32 v[54:55], v[46:47], v[10:11] op_sel_hi:[0,1] neg_lo:[0,1] neg_hi:[0,1]
	v_pk_add_f32 v[40:41], v[44:45], v[40:41] op_sel_hi:[0,1] neg_lo:[0,1] neg_hi:[0,1]
	v_pk_add_f32 v[10:11], v[46:47], v[10:11] op_sel:[0,1] op_sel_hi:[1,0]
	v_mov_b32_e32 v43, v55
	v_mov_b32_e32 v11, v41
	v_pk_mul_f32 v[10:11], v[10:11], 0.5 op_sel_hi:[1,0]
	v_mov_b32_e32 v119, v98
	v_pk_mul_f32 v[40:41], v[108:109], v[10:11] op_sel:[1,1] op_sel_hi:[1,0]
	v_pk_fma_f32 v[76:77], v[76:77], 0.5, v[112:113] op_sel_hi:[1,0,1] neg_lo:[1,0,0] neg_hi:[1,0,0]
	v_pk_fma_f32 v[44:45], v[22:23], v[10:11], v[40:41] op_sel_hi:[0,1,1]
	v_pk_fma_f32 v[10:11], v[22:23], v[10:11], v[40:41] op_sel_hi:[0,1,1] neg_lo:[0,0,1] neg_hi:[0,0,1]
	v_mov_b32_e32 v10, v44
	v_pk_fma_f32 v[22:23], v[42:43], 0.5, v[44:45] op_sel_hi:[1,0,1] neg_lo:[0,0,1] neg_hi:[0,0,1]
	v_pk_fma_f32 v[40:41], v[42:43], 0.5, v[10:11] op_sel_hi:[1,0,1]
	v_pk_fma_f32 v[54:55], v[42:43], 0.5, v[10:11] op_sel_hi:[1,0,1] neg_lo:[1,0,0] neg_hi:[1,0,0]
	v_pk_add_f32 v[10:11], v[100:101], v[14:15]
	v_pk_add_f32 v[14:15], v[14:15], v[100:101] neg_lo:[0,1] neg_hi:[0,1]
	v_mov_b32_e32 v23, v41
	v_mul_f32_e32 v6, 0.5, v15
	v_mov_b32_e32 v15, v11
	v_pk_mul_f32 v[150:151], v[22:23], s[46:47] op_sel_hi:[1,0]
	v_mul_f32_e32 v4, 0.5, v10
	v_pk_mov_b32 v[22:23], v[58:59], v[72:73] op_sel:[1,0]
	v_pk_mul_f32 v[10:11], v[14:15], s[44:45]
	v_cvt_f32_f16_sdwa v42, v8 dst_sel:DWORD dst_unused:UNUSED_PAD src0_sel:WORD_1
	v_pk_mul_f32 v[14:15], v[22:23], v[10:11] op_sel:[0,1] op_sel_hi:[1,0]
	v_cvt_f32_f16_e32 v43, v9
	v_cvt_f32_f16_sdwa v9, v9 dst_sel:DWORD dst_unused:UNUSED_PAD src0_sel:WORD_1
	v_cvt_f32_f16_e32 v8, v8
	v_pk_mul_f32 v[10:11], v[22:23], v[10:11]
	v_pk_add_f32 v[14:15], v[14:15], v[14:15] op_sel:[0,1] op_sel_hi:[0,1]
	v_pk_add_f32 v[44:45], v[4:5], v[14:15]
	v_pk_add_f32 v[14:15], v[4:5], v[14:15] op_sel_hi:[0,1] neg_lo:[0,1] neg_hi:[0,1]
	v_pk_add_f32 v[10:11], v[10:11], v[10:11] op_sel:[0,1] op_sel_hi:[0,1] neg_lo:[0,1] neg_hi:[0,1]
	v_mov_b32_e32 v45, v15
	v_pk_add_f32 v[14:15], v[6:7], v[10:11]
	v_pk_add_f32 v[10:11], v[6:7], v[10:11] op_sel_hi:[0,1] neg_lo:[0,1] neg_hi:[0,1]
	v_mov_b32_e32 v15, v11
	v_pk_mul_f32 v[10:11], v[14:15], v[8:9]
	v_pk_mul_f32 v[14:15], v[14:15], v[42:43]
	v_pk_fma_f32 v[10:11], v[44:45], v[42:43], v[10:11]
	v_pk_fma_f32 v[8:9], v[44:45], v[8:9], v[14:15] neg_lo:[0,0,1] neg_hi:[0,0,1]
	v_mov_b32_e32 v73, v59
	v_pk_add_f32 v[14:15], v[8:9], v[10:11] op_sel:[0,1] op_sel_hi:[1,0] neg_lo:[0,1] neg_hi:[0,1]
	v_pk_add_f32 v[42:43], v[8:9], v[10:11] op_sel:[0,1] op_sel_hi:[1,0]
	v_pk_add_f32 v[8:9], v[10:11], v[8:9] op_sel:[1,0] op_sel_hi:[0,1] neg_lo:[0,1] neg_hi:[0,1]
	v_mov_b32_e32 v15, v43
	v_pk_mul_f32 v[14:15], v[14:15], 0.5 op_sel_hi:[1,0]
	v_mov_b32_e32 v43, v9
	v_mul_f32_e32 v4, v59, v14
	v_pk_fma_f32 v[44:45], v[22:23], v[14:15], v[4:5] op_sel_hi:[1,1,0] neg_lo:[1,0,0] neg_hi:[1,0,0]
	v_mul_f32_e32 v4, v59, v15
	v_pk_fma_f32 v[14:15], v[72:73], v[14:15], v[4:5] op_sel_hi:[1,1,0]
	v_sub_f32_e32 v6, v37, v99
	v_mov_b32_e32 v44, v14
	v_pk_fma_f32 v[8:9], v[42:43], 0.5, v[14:15] op_sel_hi:[1,0,1] neg_lo:[0,0,1] neg_hi:[0,0,1]
	v_pk_fma_f32 v[10:11], v[42:43], 0.5, v[44:45] op_sel_hi:[1,0,1]
	v_pk_add_f32 v[14:15], v[98:99], v[36:37]
	v_mov_b32_e32 v9, v11
	v_pk_mul_f32 v[168:169], v[8:9], s[46:47] op_sel_hi:[1,0]
	v_mul_f32_e32 v8, 0xbf7b14be, v83
	v_mov_b32_e32 v9, v36
	v_mul_f32_e32 v18, 0.5, v15
	v_pk_add_f32 v[8:9], v[8:9], v[118:119] neg_lo:[0,1] neg_hi:[0,1]
	v_pk_fma_f32 v[72:73], v[42:43], 0.5, v[44:45] op_sel_hi:[1,0,1] neg_lo:[1,0,0] neg_hi:[1,0,0]
	v_pk_mul_f32 v[36:37], v[8:9], v[18:19]
	v_mov_b32_e32 v42, v8
	v_pk_fma_f32 v[22:23], v[22:23], v[36:37], v[36:37] op_sel:[0,1,0] op_sel_hi:[1,0,1]
	v_mov_b32_e32 v43, v59
	v_mov_b32_e32 v36, v37
	v_mov_b32_e32 v37, v18
	v_mul_f32_e32 v4, 0.5, v14
	v_pk_mul_f32 v[36:37], v[42:43], v[36:37]
	v_cvt_f32_f16_e32 v44, v2
	v_cvt_f32_f16_e32 v45, v3
	v_cvt_f32_f16_sdwa v3, v3 dst_sel:DWORD dst_unused:UNUSED_PAD src0_sel:WORD_1
	v_cvt_f32_f16_sdwa v2, v2 dst_sel:DWORD dst_unused:UNUSED_PAD src0_sel:WORD_1
	v_mul_f32_e32 v6, 0.5, v6
	v_pk_add_f32 v[46:47], v[4:5], v[22:23]
	v_fma_f32 v4, v14, 0.5, -v22
	v_pk_add_f32 v[22:23], v[36:37], v[36:37] op_sel:[0,1] op_sel_hi:[0,1] neg_lo:[0,1] neg_hi:[0,1]
	v_pk_add_f32 v[36:37], v[6:7], v[22:23]
	v_pk_add_f32 v[22:23], v[6:7], v[22:23] op_sel_hi:[0,1] neg_lo:[0,1] neg_hi:[0,1]
	v_mov_b32_e32 v37, v23
	v_mov_b32_e32 v14, v46
	v_mov_b32_e32 v15, v4
	v_pk_mul_f32 v[22:23], v[4:5], v[44:45] op_sel_hi:[0,1]
	v_pk_mul_f32 v[82:83], v[36:37], v[2:3]
	v_pk_mul_f32 v[46:47], v[46:47], v[2:3]
	v_pk_mul_f32 v[36:37], v[36:37], v[44:45]
	v_pk_fma_f32 v[98:99], v[14:15], v[44:45], v[82:83] neg_lo:[0,0,1] neg_hi:[0,0,1]
	v_pk_fma_f32 v[2:3], v[14:15], v[2:3], v[36:37] neg_lo:[0,0,1] neg_hi:[0,0,1]
	v_add_f32_e32 v4, v23, v83
	v_add_f32_e32 v6, v46, v36
	v_pk_add_f32 v[22:23], v[6:7], v[2:3] op_sel_hi:[0,1] neg_lo:[0,1] neg_hi:[0,1]
	v_pk_add_f32 v[36:37], v[98:99], v[4:5] op_sel_hi:[1,0] neg_lo:[0,1] neg_hi:[0,1]
	v_pk_add_f32 v[2:3], v[6:7], v[2:3] op_sel_hi:[0,1]
	v_mov_b32_e32 v37, v3
	v_pk_mul_f32 v[2:3], v[36:37], 0.5 op_sel_hi:[1,0]
	v_pk_add_f32 v[14:15], v[98:99], v[4:5] op_sel_hi:[1,0]
	v_mul_f32_e32 v4, v59, v3
	v_pk_fma_f32 v[36:37], v[42:43], v[2:3], v[4:5] op_sel_hi:[1,1,0] neg_lo:[0,0,1] neg_hi:[0,0,1]
	v_pk_mov_b32 v[42:43], v[58:59], v[8:9] op_sel:[1,0]
	v_mul_f32_e32 v4, v8, v3
	v_pk_fma_f32 v[2:3], v[42:43], v[2:3], v[4:5] op_sel_hi:[1,1,0]
	v_mov_b32_e32 v15, v23
	v_pk_fma_f32 v[8:9], v[14:15], 0.5, v[2:3] op_sel_hi:[1,0,1] neg_lo:[0,0,1] neg_hi:[0,0,1]
	v_pk_fma_f32 v[42:43], v[14:15], 0.5, v[36:37] op_sel_hi:[1,0,0]
	v_pk_fma_f32 v[2:3], v[14:15], 0.5, v[2:3] op_sel_hi:[1,0,1]
	v_mov_b32_e32 v9, v43
	v_pk_fma_f32 v[58:59], v[22:23], 0.5, v[36:37] op_sel_hi:[1,0,0] neg_lo:[1,0,0] neg_hi:[1,0,0]
	v_pk_mul_f32 v[144:145], v[8:9], s[46:47] op_sel_hi:[1,0]
	v_mov_b32_e32 v58, v2
	v_mov_b32_e32 v72, v10
	v_mov_b32_e32 v54, v40
	v_mov_b32_e32 v70, v20
	v_mov_b32_e32 v56, v26
	v_mov_b32_e32 v76, v38
	v_mov_b32_e32 v52, v34
	v_mov_b32_e32 v74, v86
	v_mov_b32_e32 v48, v84
	v_mov_b32_e32 v50, v60
	v_mov_b32_e32 v28, v66
	v_mov_b32_e32 v32, v96
	v_mov_b32_e32 v12, v88
	v_mov_b32_e32 v16, v92
	v_mov_b32_e32 v4, v138
	v_mov_b32_e32 v6, v122

	.amdhsa_kernel _Z4mega6Params
		.amdhsa_group_segment_fixed_size 0
		.amdhsa_private_segment_fixed_size 0
		.amdhsa_kernarg_size 448
		.amdhsa_user_sgpr_count 2
		.amdhsa_user_sgpr_dispatch_ptr 0
		.amdhsa_user_sgpr_queue_ptr 0
		.amdhsa_user_sgpr_kernarg_segment_ptr 1
		.amdhsa_user_sgpr_dispatch_id 0
		.amdhsa_user_sgpr_kernarg_preload_length 0
		.amdhsa_user_sgpr_kernarg_preload_offset 0
		.amdhsa_user_sgpr_private_segment_size 0
		.amdhsa_uses_dynamic_stack 0
		.amdhsa_enable_private_segment 0
		.amdhsa_system_sgpr_workgroup_id_x 1
		.amdhsa_system_sgpr_workgroup_id_y 0
		.amdhsa_system_sgpr_workgroup_id_z 0
		.amdhsa_system_sgpr_workgroup_info 0
		.amdhsa_system_vgpr_workitem_id 2
		.amdhsa_next_free_vgpr 248
		.amdhsa_next_free_sgpr 102
		.amdhsa_accum_offset 248
		.amdhsa_reserve_vcc 1
		.amdhsa_float_round_mode_32 0
		.amdhsa_float_round_mode_16_64 0
		.amdhsa_float_denorm_mode_32 3
		.amdhsa_float_denorm_mode_16_64 3
		.amdhsa_dx10_clamp 1
		.amdhsa_ieee_mode 1
		.amdhsa_fp16_overflow 0
		.amdhsa_tg_split 0
		.amdhsa_exception_fp_ieee_invalid_op 0
		.amdhsa_exception_fp_denorm_src 0
		.amdhsa_exception_fp_ieee_div_zero 0
		.amdhsa_exception_fp_ieee_overflow 0
		.amdhsa_exception_fp_ieee_underflow 0
		.amdhsa_exception_fp_ieee_inexact 0
		.amdhsa_exception_int_div_zero 0
	.end_amdhsa_kernel

amdhsa.kernels:
  - .agpr_count:     0
    .args:
      - .offset:         0
        .size:           192
        .value_kind:     by_value
      - .offset:         192
        .size:           4
        .value_kind:     hidden_block_count_x
      - .offset:         196
        .size:           4
        .value_kind:     hidden_block_count_y
      - .offset:         200
        .size:           4
        .value_kind:     hidden_block_count_z
      - .offset:         204
        .size:           2
        .value_kind:     hidden_group_size_x
      - .offset:         206
        .size:           2
        .value_kind:     hidden_group_size_y
      - .offset:         208
        .size:           2
        .value_kind:     hidden_group_size_z
      - .offset:         210
        .size:           2
        .value_kind:     hidden_remainder_x
      - .offset:         212
        .size:           2
        .value_kind:     hidden_remainder_y
      - .offset:         214
        .size:           2
        .value_kind:     hidden_remainder_z
      - .offset:         232
        .size:           8
        .value_kind:     hidden_global_offset_x
      - .offset:         240
        .size:           8
        .value_kind:     hidden_global_offset_y
      - .offset:         248
        .size:           8
        .value_kind:     hidden_global_offset_z
      - .offset:         256
        .size:           2
        .value_kind:     hidden_grid_dims
      - .offset:         280
        .size:           8
        .value_kind:     hidden_multigrid_sync_arg
      - .offset:         312
        .size:           4
        .value_kind:     hidden_dynamic_lds_size
    .group_segment_fixed_size: 0
    .kernarg_segment_align: 8
    .kernarg_segment_size: 448
    .language:       OpenCL C
    .language_version:
      - 2
      - 0
    .max_flat_workgroup_size: 512
    .name:           _Z4mega6Params
    .private_segment_fixed_size: 0
    .sgpr_count:     108
    .sgpr_spill_count: 18
    .symbol:         _Z4mega6Params.kd
    .uniform_work_group_size: 1
    .uses_dynamic_stack: false
    .vgpr_count:     248
    .vgpr_spill_count: 0
    .wavefront_size: 64
